# mLSTM scan phase rewritten: csc preloaded + readlane broadcast, kv/ksum loads 16 chunks ahead in a register ring, no waits on stores, unrolled (same arithmetic order)
# speedup vs baseline: 1.0087x; 1.0087x over previous
; DI int otid() { int t = __builtin_amdgcn_workitem_id_x(); asm volatile("" : "+v"(t)); return t; }
; DI unsigned pack2(float a, float b) { const f32x2 v = {a, b}; return __builtin_bit_cast(unsigned, __builtin_convertvector(v, bf16v2)); }
; DI float bflo(unsigned w) { return __uint_as_float(w << 16); }
; DI float bfhi(unsigned w) { return __uint_as_float(w & 0xffff0000u); }
; DI void phase_mlstm_scan(const Params& p) {
;   char* ws = p.ws;
;   const int tid = otid();
;   for (int unit = blockIdx.x; unit < 256; unit += gridDim.x) {
;     const int bh = unit >> 3, part = unit & 7;
;     u16* kv = (u16*)(ws + OFF_KVS) + (size_t)bh * 128 * 16384 + part * 2048 + tid * 4;
;     float* ks = (float*)(ws + OFF_KSUM) + (size_t)bh * 128 * 128 + tid;
;     float* csc = (float*)(ws + OFF_CSC) + (size_t)bh * 128 * 4;
;     const bool don = (part == 0) && (tid < 128);
;     float m = 0.f, c0 = 0.f, c1 = 0.f, c2 = 0.f, c3 = 0.f, n = 0.f;
; #pragma unroll 1
;     for (int cb = 0; cb < 128; cb += 8) {
;       uint2 raw[8]; float kr[8];
; #pragma unroll
;       for (int j = 0; j < 8; ++j) { raw[j] = *(const uint2*)(kv + (size_t)(cb + j) * 16384); kr[j] = don ? ks[(cb + j) * 128] : 0.f; }
; #pragma unroll
;       for (int j = 0; j < 8; ++j) {
;         const float B = csc[(cb + j) * 4], A = csc[(cb + j) * 4 + 1];
;         const float mnew = fmaxf(B + m, A);
;         const float wp = __expf(B + m - mnew), wl = __expf(A - mnew);
;         m = mnew;
;         c0 = wp * c0 + wl * bflo(raw[j].x); c1 = wp * c1 + wl * bfhi(raw[j].x); c2 = wp * c2 + wl * bflo(raw[j].y); c3 = wp * c3 + wl * bfhi(raw[j].y);
;         uint2 o; o.x = pack2(c0, c1); o.y = pack2(c2, c3);
;         *(uint2*)(kv + (size_t)(cb + j) * 16384) = o;
;         if (don) { n = wp * n + wl * kr[j]; ks[(cb + j) * 128] = n; }
;         if (part == 0 && tid == 0) csc[(cb + j) * 4 + 2] = mnew;
.LBB0_462:
	s_or_b64 exec, exec, s[0:1]
	v_readlane_b32 s0, v250, 21
	v_readlane_b32 s1, v250, 22
	s_waitcnt lgkmcnt(0)
	v_mov_b32_e32 v0, v222
	s_and_b64 vcc, exec, s[0:1]
	s_barrier
	s_cbranch_vccnz .LBB0_515
	s_mov_b64 s[20:21], exec
	v_mov_b32_e32 v0, 0
	v_lshlrev_b32_e32 v1, 3, v222
	v_lshlrev_b32_e32 v2, 2, v222
	v_and_b32_e32 v3, 63, v222
	v_lshlrev_b32_e32 v3, 4, v3
	s_mov_b32 s2, s94
.Lsc_unit:
	s_cmpk_gt_i32 s2, 0xff
	s_cbranch_scc1 .Lsc_done
	s_lshr_b32 s4, s2, 3
	s_and_b32 s5, s2, 7
	s_lshl_b32 s22, s4, 22
	s_lshl_b32 s23, s5, 12
	s_add_u32 s22, s22, s23
	s_add_u32 s22, s22, 0x32800000
	s_add_u32 s6, s68, s22
	s_addc_u32 s7, s69, 0
	s_mov_b64 s[8:9], s[6:7]
	s_lshl_b32 s22, s4, 16
	s_add_u32 s22, s22, 0x3a800000
	s_add_u32 s10, s68, s22
	s_addc_u32 s11, s69, 0
	s_mov_b64 s[12:13], s[10:11]
	s_lshl_b32 s22, s4, 11
	s_add_u32 s22, s22, 0x3aa00000
	s_add_u32 s14, s68, s22
	s_addc_u32 s15, s69, 0
	v_lshrrev_b32_e32 v11, 6, v222
	v_cmp_gt_u32_e64 s[16:17], 2, v11
	v_cmp_eq_u32_e64 s[18:19], 0, v222
	s_cmp_eq_u32 s5, 0
	s_cselect_b64 s[22:23], -1, 0
	s_nop 3
	s_and_b64 s[16:17], s[16:17], s[22:23]
	s_and_b64 s[18:19], s[18:19], s[22:23]
	global_load_dwordx2 v[4:5], v3, s[14:15]
	global_load_dwordx2 v[6:7], v3, s[14:15] offset:1024
	global_load_dwordx2 v[100:101], v1, s[6:7]
	global_load_dword v132, v2, s[10:11]
	s_add_u32 s6, s6, 0x8000
	s_addc_u32 s7, s7, 0
	s_add_u32 s10, s10, 0x200
	s_addc_u32 s11, s11, 0
	global_load_dwordx2 v[102:103], v1, s[6:7]
	global_load_dword v133, v2, s[10:11]
	s_add_u32 s6, s6, 0x8000
	s_addc_u32 s7, s7, 0
	s_add_u32 s10, s10, 0x200
	s_addc_u32 s11, s11, 0
	global_load_dwordx2 v[104:105], v1, s[6:7]
	global_load_dword v134, v2, s[10:11]
	s_add_u32 s6, s6, 0x8000
	s_addc_u32 s7, s7, 0
	s_add_u32 s10, s10, 0x200
	s_addc_u32 s11, s11, 0
	global_load_dwordx2 v[106:107], v1, s[6:7]
	global_load_dword v135, v2, s[10:11]
	s_add_u32 s6, s6, 0x8000
	s_addc_u32 s7, s7, 0
	s_add_u32 s10, s10, 0x200
	s_addc_u32 s11, s11, 0
	global_load_dwordx2 v[108:109], v1, s[6:7]
	global_load_dword v136, v2, s[10:11]
	s_add_u32 s6, s6, 0x8000
	s_addc_u32 s7, s7, 0
	s_add_u32 s10, s10, 0x200
	s_addc_u32 s11, s11, 0
	global_load_dwordx2 v[110:111], v1, s[6:7]
	global_load_dword v137, v2, s[10:11]
	s_add_u32 s6, s6, 0x8000
	s_addc_u32 s7, s7, 0
	s_add_u32 s10, s10, 0x200
	s_addc_u32 s11, s11, 0
	global_load_dwordx2 v[112:113], v1, s[6:7]
	global_load_dword v138, v2, s[10:11]
	s_add_u32 s6, s6, 0x8000
	s_addc_u32 s7, s7, 0
	s_add_u32 s10, s10, 0x200
	s_addc_u32 s11, s11, 0
	global_load_dwordx2 v[114:115], v1, s[6:7]
	global_load_dword v139, v2, s[10:11]
	s_add_u32 s6, s6, 0x8000
	s_addc_u32 s7, s7, 0
	s_add_u32 s10, s10, 0x200
	s_addc_u32 s11, s11, 0
	global_load_dwordx2 v[116:117], v1, s[6:7]
	global_load_dword v140, v2, s[10:11]
	s_add_u32 s6, s6, 0x8000
	s_addc_u32 s7, s7, 0
	s_add_u32 s10, s10, 0x200
	s_addc_u32 s11, s11, 0
	global_load_dwordx2 v[118:119], v1, s[6:7]
	global_load_dword v141, v2, s[10:11]
	s_add_u32 s6, s6, 0x8000
	s_addc_u32 s7, s7, 0
	s_add_u32 s10, s10, 0x200
	s_addc_u32 s11, s11, 0
	global_load_dwordx2 v[120:121], v1, s[6:7]
	global_load_dword v142, v2, s[10:11]
	s_add_u32 s6, s6, 0x8000
	s_addc_u32 s7, s7, 0
	s_add_u32 s10, s10, 0x200
	s_addc_u32 s11, s11, 0
	global_load_dwordx2 v[122:123], v1, s[6:7]
	global_load_dword v143, v2, s[10:11]
	s_add_u32 s6, s6, 0x8000
	s_addc_u32 s7, s7, 0
	s_add_u32 s10, s10, 0x200
	s_addc_u32 s11, s11, 0
	global_load_dwordx2 v[124:125], v1, s[6:7]
	global_load_dword v144, v2, s[10:11]
	s_add_u32 s6, s6, 0x8000
	s_addc_u32 s7, s7, 0
	s_add_u32 s10, s10, 0x200
	s_addc_u32 s11, s11, 0
	global_load_dwordx2 v[126:127], v1, s[6:7]
	global_load_dword v145, v2, s[10:11]
	s_add_u32 s6, s6, 0x8000
	s_addc_u32 s7, s7, 0
	s_add_u32 s10, s10, 0x200
	s_addc_u32 s11, s11, 0
	global_load_dwordx2 v[128:129], v1, s[6:7]
	global_load_dword v146, v2, s[10:11]
	s_add_u32 s6, s6, 0x8000
	s_addc_u32 s7, s7, 0
	s_add_u32 s10, s10, 0x200
	s_addc_u32 s11, s11, 0
	global_load_dwordx2 v[130:131], v1, s[6:7]
	global_load_dword v147, v2, s[10:11]
	s_add_u32 s6, s6, 0x8000
	s_addc_u32 s7, s7, 0
	s_add_u32 s10, s10, 0x200
	s_addc_u32 s11, s11, 0
	v_mov_b32_e32 v46, 0
	v_mov_b32_e32 v32, 0
	v_mov_b32_e32 v33, 0
	v_mov_b32_e32 v40, 0
	v_mov_b32_e32 v41, 0
	v_mov_b32_e32 v10, 0
	s_waitcnt vmcnt(32)
	v_readlane_b32 s0, v4, 0
	v_readlane_b32 s1, v5, 0
	s_waitcnt vmcnt(30)
	v_lshlrev_b32_e32 v50, 16, v100
	v_and_b32_e32 v51, 0xffff0000, v100
	v_lshlrev_b32_e32 v42, 16, v101
	v_and_b32_e32 v43, 0xffff0000, v101
	v_mov_b32_e32 v11, v132
	v_add_f32_e32 v36, s0, v46
	v_max_f32_e64 v37, s1, s1
	v_max_f32_e32 v47, v36, v37
	v_sub_f32_e32 v37, s1, v47
	v_sub_f32_e32 v36, v36, v47
	v_mul_f32_e32 v37, 0x3fb8aa3b, v37
	v_mul_f32_e32 v36, 0x3fb8aa3b, v36
	v_exp_f32_e32 v38, v37
	v_exp_f32_e32 v36, v36
	v_mov_b32_e32 v46, v47
	v_pk_mul_f32 v[50:51], v[38:39], v[50:51] op_sel_hi:[0,1]
	v_pk_mul_f32 v[42:43], v[38:39], v[42:43] op_sel_hi:[0,1]
	v_pk_fma_f32 v[32:33], v[32:33], v[36:37], v[50:51] op_sel_hi:[1,0,1]
	v_pk_fma_f32 v[40:41], v[40:41], v[36:37], v[42:43] op_sel_hi:[1,0,1]
	v_cvt_pk_bf16_f32 v30, v32, v33
	v_cvt_pk_bf16_f32 v31, v40, v41
	global_store_dwordx2 v1, v[30:31], s[8:9]
	v_mov_b32_e32 v37, v38
	v_pk_mul_f32 v[10:11], v[10:11], v[36:37]
	s_add_u32 s8, s8, 0x8000
	s_addc_u32 s9, s9, 0
	v_add_f32_e32 v10, v10, v11
	s_mov_b64 exec, s[16:17]
	global_store_dword v2, v10, s[12:13]
	s_mov_b64 exec, s[18:19]
	global_store_dword v0, v47, s[14:15] offset:8
	s_mov_b64 exec, s[20:21]
	s_add_u32 s12, s12, 0x200
	s_addc_u32 s13, s13, 0
	global_load_dwordx2 v[100:101], v1, s[6:7]
	global_load_dword v132, v2, s[10:11]
	s_add_u32 s6, s6, 0x8000
	s_addc_u32 s7, s7, 0
	s_add_u32 s10, s10, 0x200
	s_addc_u32 s11, s11, 0
	v_readlane_b32 s0, v4, 1
	v_readlane_b32 s1, v5, 1
	s_waitcnt vmcnt(31)
; DI unsigned pack2(float a, float b) { const f32x2 v = {a, b}; return __builtin_bit_cast(unsigned, __builtin_convertvector(v, bf16v2)); }
; DI float bflo(unsigned w) { return __uint_as_float(w << 16); }
; DI float bfhi(unsigned w) { return __uint_as_float(w & 0xffff0000u); }
; DI void phase_mlstm_scan(const Params& p) {
;     ...
;       for (int j = 0; j < 8; ++j) { raw[j] = *(const uint2*)(kv + (size_t)(cb + j) * 16384); kr[j] = don ? ks[(cb + j) * 128] : 0.f; }
; #pragma unroll
;       for (int j = 0; j < 8; ++j) {
;         const float B = csc[(cb + j) * 4], A = csc[(cb + j) * 4 + 1];
;         const float mnew = fmaxf(B + m, A);
;         const float wp = __expf(B + m - mnew), wl = __expf(A - mnew);
;         m = mnew;
;         c0 = wp * c0 + wl * bflo(raw[j].x); c1 = wp * c1 + wl * bfhi(raw[j].x); c2 = wp * c2 + wl * bflo(raw[j].y); c3 = wp * c3 + wl * bfhi(raw[j].y);
;         uint2 o; o.x = pack2(c0, c1); o.y = pack2(c2, c3);
;         *(uint2*)(kv + (size_t)(cb + j) * 16384) = o;
;         if (don) { n = wp * n + wl * kr[j]; ks[(cb + j) * 128] = n; }
;         if (part == 0 && tid == 0) csc[(cb + j) * 4 + 2] = mnew;
	v_lshlrev_b32_e32 v50, 16, v102
	v_and_b32_e32 v51, 0xffff0000, v102
	v_lshlrev_b32_e32 v42, 16, v103
	v_and_b32_e32 v43, 0xffff0000, v103
	v_mov_b32_e32 v11, v133
	v_add_f32_e32 v36, s0, v46
	v_max_f32_e64 v37, s1, s1
	v_max_f32_e32 v47, v36, v37
	v_sub_f32_e32 v37, s1, v47
	v_sub_f32_e32 v36, v36, v47
	v_mul_f32_e32 v37, 0x3fb8aa3b, v37
	v_mul_f32_e32 v36, 0x3fb8aa3b, v36
	v_exp_f32_e32 v38, v37
	v_exp_f32_e32 v36, v36
	v_mov_b32_e32 v46, v47
	v_pk_mul_f32 v[50:51], v[38:39], v[50:51] op_sel_hi:[0,1]
	v_pk_mul_f32 v[42:43], v[38:39], v[42:43] op_sel_hi:[0,1]
	v_pk_fma_f32 v[32:33], v[32:33], v[36:37], v[50:51] op_sel_hi:[1,0,1]
	v_pk_fma_f32 v[40:41], v[40:41], v[36:37], v[42:43] op_sel_hi:[1,0,1]
	v_cvt_pk_bf16_f32 v30, v32, v33
	v_cvt_pk_bf16_f32 v31, v40, v41
	global_store_dwordx2 v1, v[30:31], s[8:9]
	v_mov_b32_e32 v37, v38
	v_pk_mul_f32 v[10:11], v[10:11], v[36:37]
	s_add_u32 s8, s8, 0x8000
	s_addc_u32 s9, s9, 0
	v_add_f32_e32 v10, v10, v11
	s_mov_b64 exec, s[16:17]
	global_store_dword v2, v10, s[12:13]
	s_mov_b64 exec, s[18:19]
	global_store_dword v0, v47, s[14:15] offset:24
	s_mov_b64 exec, s[20:21]
	s_add_u32 s12, s12, 0x200
	s_addc_u32 s13, s13, 0
	global_load_dwordx2 v[102:103], v1, s[6:7]
	global_load_dword v133, v2, s[10:11]
	s_add_u32 s6, s6, 0x8000
	s_addc_u32 s7, s7, 0
	s_add_u32 s10, s10, 0x200
	s_addc_u32 s11, s11, 0
	v_readlane_b32 s0, v4, 2
	v_readlane_b32 s1, v5, 2
	s_waitcnt vmcnt(32)
	v_lshlrev_b32_e32 v50, 16, v104
	v_and_b32_e32 v51, 0xffff0000, v104
	v_lshlrev_b32_e32 v42, 16, v105
	v_and_b32_e32 v43, 0xffff0000, v105
	v_mov_b32_e32 v11, v134
	v_add_f32_e32 v36, s0, v46
	v_max_f32_e64 v37, s1, s1
	v_max_f32_e32 v47, v36, v37
	v_sub_f32_e32 v37, s1, v47
	v_sub_f32_e32 v36, v36, v47
	v_mul_f32_e32 v37, 0x3fb8aa3b, v37
	v_mul_f32_e32 v36, 0x3fb8aa3b, v36
	v_exp_f32_e32 v38, v37
	v_exp_f32_e32 v36, v36
	v_mov_b32_e32 v46, v47
	v_pk_mul_f32 v[50:51], v[38:39], v[50:51] op_sel_hi:[0,1]
	v_pk_mul_f32 v[42:43], v[38:39], v[42:43] op_sel_hi:[0,1]
	v_pk_fma_f32 v[32:33], v[32:33], v[36:37], v[50:51] op_sel_hi:[1,0,1]
	v_pk_fma_f32 v[40:41], v[40:41], v[36:37], v[42:43] op_sel_hi:[1,0,1]
	v_cvt_pk_bf16_f32 v30, v32, v33
	v_cvt_pk_bf16_f32 v31, v40, v41
	global_store_dwordx2 v1, v[30:31], s[8:9]
	v_mov_b32_e32 v37, v38
	v_pk_mul_f32 v[10:11], v[10:11], v[36:37]
	s_add_u32 s8, s8, 0x8000
	s_addc_u32 s9, s9, 0
	v_add_f32_e32 v10, v10, v11
	s_mov_b64 exec, s[16:17]
	global_store_dword v2, v10, s[12:13]
	s_mov_b64 exec, s[18:19]
	global_store_dword v0, v47, s[14:15] offset:40
	s_mov_b64 exec, s[20:21]
	s_add_u32 s12, s12, 0x200
	s_addc_u32 s13, s13, 0
	global_load_dwordx2 v[104:105], v1, s[6:7]
	global_load_dword v134, v2, s[10:11]
	s_add_u32 s6, s6, 0x8000
	s_addc_u32 s7, s7, 0
	s_add_u32 s10, s10, 0x200
	s_addc_u32 s11, s11, 0
	v_readlane_b32 s0, v4, 3
	v_readlane_b32 s1, v5, 3
	s_waitcnt vmcnt(33)
	v_lshlrev_b32_e32 v50, 16, v106
	v_and_b32_e32 v51, 0xffff0000, v106
	v_lshlrev_b32_e32 v42, 16, v107
	v_and_b32_e32 v43, 0xffff0000, v107
	v_mov_b32_e32 v11, v135
	v_add_f32_e32 v36, s0, v46
	v_max_f32_e64 v37, s1, s1
	v_max_f32_e32 v47, v36, v37
	v_sub_f32_e32 v37, s1, v47
	v_sub_f32_e32 v36, v36, v47
	v_mul_f32_e32 v37, 0x3fb8aa3b, v37
	v_mul_f32_e32 v36, 0x3fb8aa3b, v36
	v_exp_f32_e32 v38, v37
	v_exp_f32_e32 v36, v36
	v_mov_b32_e32 v46, v47
	v_pk_mul_f32 v[50:51], v[38:39], v[50:51] op_sel_hi:[0,1]
	v_pk_mul_f32 v[42:43], v[38:39], v[42:43] op_sel_hi:[0,1]
	v_pk_fma_f32 v[32:33], v[32:33], v[36:37], v[50:51] op_sel_hi:[1,0,1]
	v_pk_fma_f32 v[40:41], v[40:41], v[36:37], v[42:43] op_sel_hi:[1,0,1]
	v_cvt_pk_bf16_f32 v30, v32, v33
	v_cvt_pk_bf16_f32 v31, v40, v41
	global_store_dwordx2 v1, v[30:31], s[8:9]
	v_mov_b32_e32 v37, v38
	v_pk_mul_f32 v[10:11], v[10:11], v[36:37]
	s_add_u32 s8, s8, 0x8000
	s_addc_u32 s9, s9, 0
	v_add_f32_e32 v10, v10, v11
	s_mov_b64 exec, s[16:17]
	global_store_dword v2, v10, s[12:13]
	s_mov_b64 exec, s[18:19]
	global_store_dword v0, v47, s[14:15] offset:56
	s_mov_b64 exec, s[20:21]
	s_add_u32 s12, s12, 0x200
	s_addc_u32 s13, s13, 0
	global_load_dwordx2 v[106:107], v1, s[6:7]
	global_load_dword v135, v2, s[10:11]
	s_add_u32 s6, s6, 0x8000
	s_addc_u32 s7, s7, 0
	s_add_u32 s10, s10, 0x200
	s_addc_u32 s11, s11, 0
	v_readlane_b32 s0, v4, 4
	v_readlane_b32 s1, v5, 4
	s_waitcnt vmcnt(34)
	v_lshlrev_b32_e32 v50, 16, v108
	v_and_b32_e32 v51, 0xffff0000, v108
	v_lshlrev_b32_e32 v42, 16, v109
	v_and_b32_e32 v43, 0xffff0000, v109
	v_mov_b32_e32 v11, v136
	v_add_f32_e32 v36, s0, v46
	v_max_f32_e64 v37, s1, s1
	v_max_f32_e32 v47, v36, v37
	v_sub_f32_e32 v37, s1, v47
	v_sub_f32_e32 v36, v36, v47
	v_mul_f32_e32 v37, 0x3fb8aa3b, v37
	v_mul_f32_e32 v36, 0x3fb8aa3b, v36
	v_exp_f32_e32 v38, v37
	v_exp_f32_e32 v36, v36
	v_mov_b32_e32 v46, v47
	v_pk_mul_f32 v[50:51], v[38:39], v[50:51] op_sel_hi:[0,1]
	v_pk_mul_f32 v[42:43], v[38:39], v[42:43] op_sel_hi:[0,1]
	v_pk_fma_f32 v[32:33], v[32:33], v[36:37], v[50:51] op_sel_hi:[1,0,1]
	v_pk_fma_f32 v[40:41], v[40:41], v[36:37], v[42:43] op_sel_hi:[1,0,1]
	v_cvt_pk_bf16_f32 v30, v32, v33
	v_cvt_pk_bf16_f32 v31, v40, v41
	global_store_dwordx2 v1, v[30:31], s[8:9]
	v_mov_b32_e32 v37, v38
	v_pk_mul_f32 v[10:11], v[10:11], v[36:37]
	s_add_u32 s8, s8, 0x8000
	s_addc_u32 s9, s9, 0
	v_add_f32_e32 v10, v10, v11
	s_mov_b64 exec, s[16:17]
	global_store_dword v2, v10, s[12:13]
	s_mov_b64 exec, s[18:19]
	global_store_dword v0, v47, s[14:15] offset:72
	s_mov_b64 exec, s[20:21]
	s_add_u32 s12, s12, 0x200
	s_addc_u32 s13, s13, 0
	global_load_dwordx2 v[108:109], v1, s[6:7]
	global_load_dword v136, v2, s[10:11]
	s_add_u32 s6, s6, 0x8000
	s_addc_u32 s7, s7, 0
	s_add_u32 s10, s10, 0x200
	s_addc_u32 s11, s11, 0
	v_readlane_b32 s0, v4, 5
	v_readlane_b32 s1, v5, 5
	s_waitcnt vmcnt(35)
; DI unsigned pack2(float a, float b) { const f32x2 v = {a, b}; return __builtin_bit_cast(unsigned, __builtin_convertvector(v, bf16v2)); }
; DI float bflo(unsigned w) { return __uint_as_float(w << 16); }
; DI float bfhi(unsigned w) { return __uint_as_float(w & 0xffff0000u); }
; DI void phase_mlstm_scan(const Params& p) {
;     ...
;       for (int j = 0; j < 8; ++j) { raw[j] = *(const uint2*)(kv + (size_t)(cb + j) * 16384); kr[j] = don ? ks[(cb + j) * 128] : 0.f; }
; #pragma unroll
;       for (int j = 0; j < 8; ++j) {
;         const float B = csc[(cb + j) * 4], A = csc[(cb + j) * 4 + 1];
;         const float mnew = fmaxf(B + m, A);
;         const float wp = __expf(B + m - mnew), wl = __expf(A - mnew);
;         m = mnew;
;         c0 = wp * c0 + wl * bflo(raw[j].x); c1 = wp * c1 + wl * bfhi(raw[j].x); c2 = wp * c2 + wl * bflo(raw[j].y); c3 = wp * c3 + wl * bfhi(raw[j].y);
;         uint2 o; o.x = pack2(c0, c1); o.y = pack2(c2, c3);
;         *(uint2*)(kv + (size_t)(cb + j) * 16384) = o;
;         if (don) { n = wp * n + wl * kr[j]; ks[(cb + j) * 128] = n; }
;         if (part == 0 && tid == 0) csc[(cb + j) * 4 + 2] = mnew;
	v_lshlrev_b32_e32 v50, 16, v110
	v_and_b32_e32 v51, 0xffff0000, v110
	v_lshlrev_b32_e32 v42, 16, v111
	v_and_b32_e32 v43, 0xffff0000, v111
	v_mov_b32_e32 v11, v137
	v_add_f32_e32 v36, s0, v46
	v_max_f32_e64 v37, s1, s1
	v_max_f32_e32 v47, v36, v37
	v_sub_f32_e32 v37, s1, v47
	v_sub_f32_e32 v36, v36, v47
	v_mul_f32_e32 v37, 0x3fb8aa3b, v37
	v_mul_f32_e32 v36, 0x3fb8aa3b, v36
	v_exp_f32_e32 v38, v37
	v_exp_f32_e32 v36, v36
	v_mov_b32_e32 v46, v47
	v_pk_mul_f32 v[50:51], v[38:39], v[50:51] op_sel_hi:[0,1]
	v_pk_mul_f32 v[42:43], v[38:39], v[42:43] op_sel_hi:[0,1]
	v_pk_fma_f32 v[32:33], v[32:33], v[36:37], v[50:51] op_sel_hi:[1,0,1]
	v_pk_fma_f32 v[40:41], v[40:41], v[36:37], v[42:43] op_sel_hi:[1,0,1]
	v_cvt_pk_bf16_f32 v30, v32, v33
	v_cvt_pk_bf16_f32 v31, v40, v41
	global_store_dwordx2 v1, v[30:31], s[8:9]
	v_mov_b32_e32 v37, v38
	v_pk_mul_f32 v[10:11], v[10:11], v[36:37]
	s_add_u32 s8, s8, 0x8000
	s_addc_u32 s9, s9, 0
	v_add_f32_e32 v10, v10, v11
	s_mov_b64 exec, s[16:17]
	global_store_dword v2, v10, s[12:13]
	s_mov_b64 exec, s[18:19]
	global_store_dword v0, v47, s[14:15] offset:88
	s_mov_b64 exec, s[20:21]
	s_add_u32 s12, s12, 0x200
	s_addc_u32 s13, s13, 0
	global_load_dwordx2 v[110:111], v1, s[6:7]
	global_load_dword v137, v2, s[10:11]
	s_add_u32 s6, s6, 0x8000
	s_addc_u32 s7, s7, 0
	s_add_u32 s10, s10, 0x200
	s_addc_u32 s11, s11, 0
	v_readlane_b32 s0, v4, 6
	v_readlane_b32 s1, v5, 6
	s_waitcnt vmcnt(36)
	v_lshlrev_b32_e32 v50, 16, v112
	v_and_b32_e32 v51, 0xffff0000, v112
	v_lshlrev_b32_e32 v42, 16, v113
	v_and_b32_e32 v43, 0xffff0000, v113
	v_mov_b32_e32 v11, v138
	v_add_f32_e32 v36, s0, v46
	v_max_f32_e64 v37, s1, s1
	v_max_f32_e32 v47, v36, v37
	v_sub_f32_e32 v37, s1, v47
	v_sub_f32_e32 v36, v36, v47
	v_mul_f32_e32 v37, 0x3fb8aa3b, v37
	v_mul_f32_e32 v36, 0x3fb8aa3b, v36
	v_exp_f32_e32 v38, v37
	v_exp_f32_e32 v36, v36
	v_mov_b32_e32 v46, v47
	v_pk_mul_f32 v[50:51], v[38:39], v[50:51] op_sel_hi:[0,1]
	v_pk_mul_f32 v[42:43], v[38:39], v[42:43] op_sel_hi:[0,1]
	v_pk_fma_f32 v[32:33], v[32:33], v[36:37], v[50:51] op_sel_hi:[1,0,1]
	v_pk_fma_f32 v[40:41], v[40:41], v[36:37], v[42:43] op_sel_hi:[1,0,1]
	v_cvt_pk_bf16_f32 v30, v32, v33
	v_cvt_pk_bf16_f32 v31, v40, v41
	global_store_dwordx2 v1, v[30:31], s[8:9]
	v_mov_b32_e32 v37, v38
	v_pk_mul_f32 v[10:11], v[10:11], v[36:37]
	s_add_u32 s8, s8, 0x8000
	s_addc_u32 s9, s9, 0
	v_add_f32_e32 v10, v10, v11
	s_mov_b64 exec, s[16:17]
	global_store_dword v2, v10, s[12:13]
	s_mov_b64 exec, s[18:19]
	global_store_dword v0, v47, s[14:15] offset:104
	s_mov_b64 exec, s[20:21]
	s_add_u32 s12, s12, 0x200
	s_addc_u32 s13, s13, 0
	global_load_dwordx2 v[112:113], v1, s[6:7]
	global_load_dword v138, v2, s[10:11]
	s_add_u32 s6, s6, 0x8000
	s_addc_u32 s7, s7, 0
	s_add_u32 s10, s10, 0x200
	s_addc_u32 s11, s11, 0
	v_readlane_b32 s0, v4, 7
	v_readlane_b32 s1, v5, 7
	s_waitcnt vmcnt(37)
	v_lshlrev_b32_e32 v50, 16, v114
	v_and_b32_e32 v51, 0xffff0000, v114
	v_lshlrev_b32_e32 v42, 16, v115
	v_and_b32_e32 v43, 0xffff0000, v115
	v_mov_b32_e32 v11, v139
	v_add_f32_e32 v36, s0, v46
	v_max_f32_e64 v37, s1, s1
	v_max_f32_e32 v47, v36, v37
	v_sub_f32_e32 v37, s1, v47
	v_sub_f32_e32 v36, v36, v47
	v_mul_f32_e32 v37, 0x3fb8aa3b, v37
	v_mul_f32_e32 v36, 0x3fb8aa3b, v36
	v_exp_f32_e32 v38, v37
	v_exp_f32_e32 v36, v36
	v_mov_b32_e32 v46, v47
	v_pk_mul_f32 v[50:51], v[38:39], v[50:51] op_sel_hi:[0,1]
	v_pk_mul_f32 v[42:43], v[38:39], v[42:43] op_sel_hi:[0,1]
	v_pk_fma_f32 v[32:33], v[32:33], v[36:37], v[50:51] op_sel_hi:[1,0,1]
	v_pk_fma_f32 v[40:41], v[40:41], v[36:37], v[42:43] op_sel_hi:[1,0,1]
	v_cvt_pk_bf16_f32 v30, v32, v33
	v_cvt_pk_bf16_f32 v31, v40, v41
	global_store_dwordx2 v1, v[30:31], s[8:9]
	v_mov_b32_e32 v37, v38
	v_pk_mul_f32 v[10:11], v[10:11], v[36:37]
	s_add_u32 s8, s8, 0x8000
	s_addc_u32 s9, s9, 0
	v_add_f32_e32 v10, v10, v11
	s_mov_b64 exec, s[16:17]
	global_store_dword v2, v10, s[12:13]
	s_mov_b64 exec, s[18:19]
	global_store_dword v0, v47, s[14:15] offset:120
	s_mov_b64 exec, s[20:21]
	s_add_u32 s12, s12, 0x200
	s_addc_u32 s13, s13, 0
	global_load_dwordx2 v[114:115], v1, s[6:7]
	global_load_dword v139, v2, s[10:11]
	s_add_u32 s6, s6, 0x8000
	s_addc_u32 s7, s7, 0
	s_add_u32 s10, s10, 0x200
	s_addc_u32 s11, s11, 0
	v_readlane_b32 s0, v4, 8
	v_readlane_b32 s1, v5, 8
	s_waitcnt vmcnt(38)
	v_lshlrev_b32_e32 v50, 16, v116
	v_and_b32_e32 v51, 0xffff0000, v116
	v_lshlrev_b32_e32 v42, 16, v117
	v_and_b32_e32 v43, 0xffff0000, v117
	v_mov_b32_e32 v11, v140
	v_add_f32_e32 v36, s0, v46
	v_max_f32_e64 v37, s1, s1
	v_max_f32_e32 v47, v36, v37
	v_sub_f32_e32 v37, s1, v47
	v_sub_f32_e32 v36, v36, v47
	v_mul_f32_e32 v37, 0x3fb8aa3b, v37
	v_mul_f32_e32 v36, 0x3fb8aa3b, v36
	v_exp_f32_e32 v38, v37
	v_exp_f32_e32 v36, v36
	v_mov_b32_e32 v46, v47
	v_pk_mul_f32 v[50:51], v[38:39], v[50:51] op_sel_hi:[0,1]
	v_pk_mul_f32 v[42:43], v[38:39], v[42:43] op_sel_hi:[0,1]
	v_pk_fma_f32 v[32:33], v[32:33], v[36:37], v[50:51] op_sel_hi:[1,0,1]
	v_pk_fma_f32 v[40:41], v[40:41], v[36:37], v[42:43] op_sel_hi:[1,0,1]
	v_cvt_pk_bf16_f32 v30, v32, v33
	v_cvt_pk_bf16_f32 v31, v40, v41
	global_store_dwordx2 v1, v[30:31], s[8:9]
	v_mov_b32_e32 v37, v38
	v_pk_mul_f32 v[10:11], v[10:11], v[36:37]
	s_add_u32 s8, s8, 0x8000
	s_addc_u32 s9, s9, 0
	v_add_f32_e32 v10, v10, v11
	s_mov_b64 exec, s[16:17]
	global_store_dword v2, v10, s[12:13]
	s_mov_b64 exec, s[18:19]
	global_store_dword v0, v47, s[14:15] offset:136
	s_mov_b64 exec, s[20:21]
	s_add_u32 s12, s12, 0x200
	s_addc_u32 s13, s13, 0
	global_load_dwordx2 v[116:117], v1, s[6:7]
	global_load_dword v140, v2, s[10:11]
	s_add_u32 s6, s6, 0x8000
	s_addc_u32 s7, s7, 0
	s_add_u32 s10, s10, 0x200
	s_addc_u32 s11, s11, 0
	v_readlane_b32 s0, v4, 9
	v_readlane_b32 s1, v5, 9
	s_waitcnt vmcnt(39)
; DI unsigned pack2(float a, float b) { const f32x2 v = {a, b}; return __builtin_bit_cast(unsigned, __builtin_convertvector(v, bf16v2)); }
; DI float bflo(unsigned w) { return __uint_as_float(w << 16); }
; DI float bfhi(unsigned w) { return __uint_as_float(w & 0xffff0000u); }
; DI void phase_mlstm_scan(const Params& p) {
;     ...
;       for (int j = 0; j < 8; ++j) { raw[j] = *(const uint2*)(kv + (size_t)(cb + j) * 16384); kr[j] = don ? ks[(cb + j) * 128] : 0.f; }
; #pragma unroll
;       for (int j = 0; j < 8; ++j) {
;         const float B = csc[(cb + j) * 4], A = csc[(cb + j) * 4 + 1];
;         const float mnew = fmaxf(B + m, A);
;         const float wp = __expf(B + m - mnew), wl = __expf(A - mnew);
;         m = mnew;
;         c0 = wp * c0 + wl * bflo(raw[j].x); c1 = wp * c1 + wl * bfhi(raw[j].x); c2 = wp * c2 + wl * bflo(raw[j].y); c3 = wp * c3 + wl * bfhi(raw[j].y);
;         uint2 o; o.x = pack2(c0, c1); o.y = pack2(c2, c3);
;         *(uint2*)(kv + (size_t)(cb + j) * 16384) = o;
;         if (don) { n = wp * n + wl * kr[j]; ks[(cb + j) * 128] = n; }
;         if (part == 0 && tid == 0) csc[(cb + j) * 4 + 2] = mnew;
	v_lshlrev_b32_e32 v50, 16, v118
	v_and_b32_e32 v51, 0xffff0000, v118
	v_lshlrev_b32_e32 v42, 16, v119
	v_and_b32_e32 v43, 0xffff0000, v119
	v_mov_b32_e32 v11, v141
	v_add_f32_e32 v36, s0, v46
	v_max_f32_e64 v37, s1, s1
	v_max_f32_e32 v47, v36, v37
	v_sub_f32_e32 v37, s1, v47
	v_sub_f32_e32 v36, v36, v47
	v_mul_f32_e32 v37, 0x3fb8aa3b, v37
	v_mul_f32_e32 v36, 0x3fb8aa3b, v36
	v_exp_f32_e32 v38, v37
	v_exp_f32_e32 v36, v36
	v_mov_b32_e32 v46, v47
	v_pk_mul_f32 v[50:51], v[38:39], v[50:51] op_sel_hi:[0,1]
	v_pk_mul_f32 v[42:43], v[38:39], v[42:43] op_sel_hi:[0,1]
	v_pk_fma_f32 v[32:33], v[32:33], v[36:37], v[50:51] op_sel_hi:[1,0,1]
	v_pk_fma_f32 v[40:41], v[40:41], v[36:37], v[42:43] op_sel_hi:[1,0,1]
	v_cvt_pk_bf16_f32 v30, v32, v33
	v_cvt_pk_bf16_f32 v31, v40, v41
	global_store_dwordx2 v1, v[30:31], s[8:9]
	v_mov_b32_e32 v37, v38
	v_pk_mul_f32 v[10:11], v[10:11], v[36:37]
	s_add_u32 s8, s8, 0x8000
	s_addc_u32 s9, s9, 0
	v_add_f32_e32 v10, v10, v11
	s_mov_b64 exec, s[16:17]
	global_store_dword v2, v10, s[12:13]
	s_mov_b64 exec, s[18:19]
	global_store_dword v0, v47, s[14:15] offset:152
	s_mov_b64 exec, s[20:21]
	s_add_u32 s12, s12, 0x200
	s_addc_u32 s13, s13, 0
	global_load_dwordx2 v[118:119], v1, s[6:7]
	global_load_dword v141, v2, s[10:11]
	s_add_u32 s6, s6, 0x8000
	s_addc_u32 s7, s7, 0
	s_add_u32 s10, s10, 0x200
	s_addc_u32 s11, s11, 0
	v_readlane_b32 s0, v4, 10
	v_readlane_b32 s1, v5, 10
	s_waitcnt vmcnt(40)
	v_lshlrev_b32_e32 v50, 16, v120
	v_and_b32_e32 v51, 0xffff0000, v120
	v_lshlrev_b32_e32 v42, 16, v121
	v_and_b32_e32 v43, 0xffff0000, v121
	v_mov_b32_e32 v11, v142
	v_add_f32_e32 v36, s0, v46
	v_max_f32_e64 v37, s1, s1
	v_max_f32_e32 v47, v36, v37
	v_sub_f32_e32 v37, s1, v47
	v_sub_f32_e32 v36, v36, v47
	v_mul_f32_e32 v37, 0x3fb8aa3b, v37
	v_mul_f32_e32 v36, 0x3fb8aa3b, v36
	v_exp_f32_e32 v38, v37
	v_exp_f32_e32 v36, v36
	v_mov_b32_e32 v46, v47
	v_pk_mul_f32 v[50:51], v[38:39], v[50:51] op_sel_hi:[0,1]
	v_pk_mul_f32 v[42:43], v[38:39], v[42:43] op_sel_hi:[0,1]
	v_pk_fma_f32 v[32:33], v[32:33], v[36:37], v[50:51] op_sel_hi:[1,0,1]
	v_pk_fma_f32 v[40:41], v[40:41], v[36:37], v[42:43] op_sel_hi:[1,0,1]
	v_cvt_pk_bf16_f32 v30, v32, v33
	v_cvt_pk_bf16_f32 v31, v40, v41
	global_store_dwordx2 v1, v[30:31], s[8:9]
	v_mov_b32_e32 v37, v38
	v_pk_mul_f32 v[10:11], v[10:11], v[36:37]
	s_add_u32 s8, s8, 0x8000
	s_addc_u32 s9, s9, 0
	v_add_f32_e32 v10, v10, v11
	s_mov_b64 exec, s[16:17]
	global_store_dword v2, v10, s[12:13]
	s_mov_b64 exec, s[18:19]
	global_store_dword v0, v47, s[14:15] offset:168
	s_mov_b64 exec, s[20:21]
	s_add_u32 s12, s12, 0x200
	s_addc_u32 s13, s13, 0
	global_load_dwordx2 v[120:121], v1, s[6:7]
	global_load_dword v142, v2, s[10:11]
	s_add_u32 s6, s6, 0x8000
	s_addc_u32 s7, s7, 0
	s_add_u32 s10, s10, 0x200
	s_addc_u32 s11, s11, 0
	v_readlane_b32 s0, v4, 11
	v_readlane_b32 s1, v5, 11
	s_waitcnt vmcnt(41)
	v_lshlrev_b32_e32 v50, 16, v122
	v_and_b32_e32 v51, 0xffff0000, v122
	v_lshlrev_b32_e32 v42, 16, v123
	v_and_b32_e32 v43, 0xffff0000, v123
	v_mov_b32_e32 v11, v143
	v_add_f32_e32 v36, s0, v46
	v_max_f32_e64 v37, s1, s1
	v_max_f32_e32 v47, v36, v37
	v_sub_f32_e32 v37, s1, v47
	v_sub_f32_e32 v36, v36, v47
	v_mul_f32_e32 v37, 0x3fb8aa3b, v37
	v_mul_f32_e32 v36, 0x3fb8aa3b, v36
	v_exp_f32_e32 v38, v37
	v_exp_f32_e32 v36, v36
	v_mov_b32_e32 v46, v47
	v_pk_mul_f32 v[50:51], v[38:39], v[50:51] op_sel_hi:[0,1]
	v_pk_mul_f32 v[42:43], v[38:39], v[42:43] op_sel_hi:[0,1]
	v_pk_fma_f32 v[32:33], v[32:33], v[36:37], v[50:51] op_sel_hi:[1,0,1]
	v_pk_fma_f32 v[40:41], v[40:41], v[36:37], v[42:43] op_sel_hi:[1,0,1]
	v_cvt_pk_bf16_f32 v30, v32, v33
	v_cvt_pk_bf16_f32 v31, v40, v41
	global_store_dwordx2 v1, v[30:31], s[8:9]
	v_mov_b32_e32 v37, v38
	v_pk_mul_f32 v[10:11], v[10:11], v[36:37]
	s_add_u32 s8, s8, 0x8000
	s_addc_u32 s9, s9, 0
	v_add_f32_e32 v10, v10, v11
	s_mov_b64 exec, s[16:17]
	global_store_dword v2, v10, s[12:13]
	s_mov_b64 exec, s[18:19]
	global_store_dword v0, v47, s[14:15] offset:184
	s_mov_b64 exec, s[20:21]
	s_add_u32 s12, s12, 0x200
	s_addc_u32 s13, s13, 0
	global_load_dwordx2 v[122:123], v1, s[6:7]
	global_load_dword v143, v2, s[10:11]
	s_add_u32 s6, s6, 0x8000
	s_addc_u32 s7, s7, 0
	s_add_u32 s10, s10, 0x200
	s_addc_u32 s11, s11, 0
	v_readlane_b32 s0, v4, 12
	v_readlane_b32 s1, v5, 12
	s_waitcnt vmcnt(42)
	v_lshlrev_b32_e32 v50, 16, v124
	v_and_b32_e32 v51, 0xffff0000, v124
	v_lshlrev_b32_e32 v42, 16, v125
	v_and_b32_e32 v43, 0xffff0000, v125
	v_mov_b32_e32 v11, v144
	v_add_f32_e32 v36, s0, v46
	v_max_f32_e64 v37, s1, s1
	v_max_f32_e32 v47, v36, v37
	v_sub_f32_e32 v37, s1, v47
	v_sub_f32_e32 v36, v36, v47
	v_mul_f32_e32 v37, 0x3fb8aa3b, v37
	v_mul_f32_e32 v36, 0x3fb8aa3b, v36
	v_exp_f32_e32 v38, v37
	v_exp_f32_e32 v36, v36
	v_mov_b32_e32 v46, v47
	v_pk_mul_f32 v[50:51], v[38:39], v[50:51] op_sel_hi:[0,1]
	v_pk_mul_f32 v[42:43], v[38:39], v[42:43] op_sel_hi:[0,1]
	v_pk_fma_f32 v[32:33], v[32:33], v[36:37], v[50:51] op_sel_hi:[1,0,1]
	v_pk_fma_f32 v[40:41], v[40:41], v[36:37], v[42:43] op_sel_hi:[1,0,1]
	v_cvt_pk_bf16_f32 v30, v32, v33
	v_cvt_pk_bf16_f32 v31, v40, v41
	global_store_dwordx2 v1, v[30:31], s[8:9]
	v_mov_b32_e32 v37, v38
	v_pk_mul_f32 v[10:11], v[10:11], v[36:37]
	s_add_u32 s8, s8, 0x8000
	s_addc_u32 s9, s9, 0
	v_add_f32_e32 v10, v10, v11
	s_mov_b64 exec, s[16:17]
	global_store_dword v2, v10, s[12:13]
	s_mov_b64 exec, s[18:19]
	global_store_dword v0, v47, s[14:15] offset:200
	s_mov_b64 exec, s[20:21]
	s_add_u32 s12, s12, 0x200
	s_addc_u32 s13, s13, 0
	global_load_dwordx2 v[124:125], v1, s[6:7]
	global_load_dword v144, v2, s[10:11]
	s_add_u32 s6, s6, 0x8000
	s_addc_u32 s7, s7, 0
	s_add_u32 s10, s10, 0x200
	s_addc_u32 s11, s11, 0
	v_readlane_b32 s0, v4, 13
	v_readlane_b32 s1, v5, 13
	s_waitcnt vmcnt(43)
; DI unsigned pack2(float a, float b) { const f32x2 v = {a, b}; return __builtin_bit_cast(unsigned, __builtin_convertvector(v, bf16v2)); }
; DI float bflo(unsigned w) { return __uint_as_float(w << 16); }
; DI float bfhi(unsigned w) { return __uint_as_float(w & 0xffff0000u); }
; DI void phase_mlstm_scan(const Params& p) {
;     ...
;       for (int j = 0; j < 8; ++j) { raw[j] = *(const uint2*)(kv + (size_t)(cb + j) * 16384); kr[j] = don ? ks[(cb + j) * 128] : 0.f; }
; #pragma unroll
;       for (int j = 0; j < 8; ++j) {
;         const float B = csc[(cb + j) * 4], A = csc[(cb + j) * 4 + 1];
;         const float mnew = fmaxf(B + m, A);
;         const float wp = __expf(B + m - mnew), wl = __expf(A - mnew);
;         m = mnew;
;         c0 = wp * c0 + wl * bflo(raw[j].x); c1 = wp * c1 + wl * bfhi(raw[j].x); c2 = wp * c2 + wl * bflo(raw[j].y); c3 = wp * c3 + wl * bfhi(raw[j].y);
;         uint2 o; o.x = pack2(c0, c1); o.y = pack2(c2, c3);
;         *(uint2*)(kv + (size_t)(cb + j) * 16384) = o;
;         if (don) { n = wp * n + wl * kr[j]; ks[(cb + j) * 128] = n; }
;         if (part == 0 && tid == 0) csc[(cb + j) * 4 + 2] = mnew;
	v_lshlrev_b32_e32 v50, 16, v126
	v_and_b32_e32 v51, 0xffff0000, v126
	v_lshlrev_b32_e32 v42, 16, v127
	v_and_b32_e32 v43, 0xffff0000, v127
	v_mov_b32_e32 v11, v145
	v_add_f32_e32 v36, s0, v46
	v_max_f32_e64 v37, s1, s1
	v_max_f32_e32 v47, v36, v37
	v_sub_f32_e32 v37, s1, v47
	v_sub_f32_e32 v36, v36, v47
	v_mul_f32_e32 v37, 0x3fb8aa3b, v37
	v_mul_f32_e32 v36, 0x3fb8aa3b, v36
	v_exp_f32_e32 v38, v37
	v_exp_f32_e32 v36, v36
	v_mov_b32_e32 v46, v47
	v_pk_mul_f32 v[50:51], v[38:39], v[50:51] op_sel_hi:[0,1]
	v_pk_mul_f32 v[42:43], v[38:39], v[42:43] op_sel_hi:[0,1]
	v_pk_fma_f32 v[32:33], v[32:33], v[36:37], v[50:51] op_sel_hi:[1,0,1]
	v_pk_fma_f32 v[40:41], v[40:41], v[36:37], v[42:43] op_sel_hi:[1,0,1]
	v_cvt_pk_bf16_f32 v30, v32, v33
	v_cvt_pk_bf16_f32 v31, v40, v41
	global_store_dwordx2 v1, v[30:31], s[8:9]
	v_mov_b32_e32 v37, v38
	v_pk_mul_f32 v[10:11], v[10:11], v[36:37]
	s_add_u32 s8, s8, 0x8000
	s_addc_u32 s9, s9, 0
	v_add_f32_e32 v10, v10, v11
	s_mov_b64 exec, s[16:17]
	global_store_dword v2, v10, s[12:13]
	s_mov_b64 exec, s[18:19]
	global_store_dword v0, v47, s[14:15] offset:216
	s_mov_b64 exec, s[20:21]
	s_add_u32 s12, s12, 0x200
	s_addc_u32 s13, s13, 0
	global_load_dwordx2 v[126:127], v1, s[6:7]
	global_load_dword v145, v2, s[10:11]
	s_add_u32 s6, s6, 0x8000
	s_addc_u32 s7, s7, 0
	s_add_u32 s10, s10, 0x200
	s_addc_u32 s11, s11, 0
	v_readlane_b32 s0, v4, 14
	v_readlane_b32 s1, v5, 14
	s_waitcnt vmcnt(44)
	v_lshlrev_b32_e32 v50, 16, v128
	v_and_b32_e32 v51, 0xffff0000, v128
	v_lshlrev_b32_e32 v42, 16, v129
	v_and_b32_e32 v43, 0xffff0000, v129
	v_mov_b32_e32 v11, v146
	v_add_f32_e32 v36, s0, v46
	v_max_f32_e64 v37, s1, s1
	v_max_f32_e32 v47, v36, v37
	v_sub_f32_e32 v37, s1, v47
	v_sub_f32_e32 v36, v36, v47
	v_mul_f32_e32 v37, 0x3fb8aa3b, v37
	v_mul_f32_e32 v36, 0x3fb8aa3b, v36
	v_exp_f32_e32 v38, v37
	v_exp_f32_e32 v36, v36
	v_mov_b32_e32 v46, v47
	v_pk_mul_f32 v[50:51], v[38:39], v[50:51] op_sel_hi:[0,1]
	v_pk_mul_f32 v[42:43], v[38:39], v[42:43] op_sel_hi:[0,1]
	v_pk_fma_f32 v[32:33], v[32:33], v[36:37], v[50:51] op_sel_hi:[1,0,1]
	v_pk_fma_f32 v[40:41], v[40:41], v[36:37], v[42:43] op_sel_hi:[1,0,1]
	v_cvt_pk_bf16_f32 v30, v32, v33
	v_cvt_pk_bf16_f32 v31, v40, v41
	global_store_dwordx2 v1, v[30:31], s[8:9]
	v_mov_b32_e32 v37, v38
	v_pk_mul_f32 v[10:11], v[10:11], v[36:37]
	s_add_u32 s8, s8, 0x8000
	s_addc_u32 s9, s9, 0
	v_add_f32_e32 v10, v10, v11
	s_mov_b64 exec, s[16:17]
	global_store_dword v2, v10, s[12:13]
	s_mov_b64 exec, s[18:19]
	global_store_dword v0, v47, s[14:15] offset:232
	s_mov_b64 exec, s[20:21]
	s_add_u32 s12, s12, 0x200
	s_addc_u32 s13, s13, 0
	global_load_dwordx2 v[128:129], v1, s[6:7]
	global_load_dword v146, v2, s[10:11]
	s_add_u32 s6, s6, 0x8000
	s_addc_u32 s7, s7, 0
	s_add_u32 s10, s10, 0x200
	s_addc_u32 s11, s11, 0
	v_readlane_b32 s0, v4, 15
	v_readlane_b32 s1, v5, 15
	s_waitcnt vmcnt(45)
	v_lshlrev_b32_e32 v50, 16, v130
	v_and_b32_e32 v51, 0xffff0000, v130
	v_lshlrev_b32_e32 v42, 16, v131
	v_and_b32_e32 v43, 0xffff0000, v131
	v_mov_b32_e32 v11, v147
	v_add_f32_e32 v36, s0, v46
	v_max_f32_e64 v37, s1, s1
	v_max_f32_e32 v47, v36, v37
	v_sub_f32_e32 v37, s1, v47
	v_sub_f32_e32 v36, v36, v47
	v_mul_f32_e32 v37, 0x3fb8aa3b, v37
	v_mul_f32_e32 v36, 0x3fb8aa3b, v36
	v_exp_f32_e32 v38, v37
	v_exp_f32_e32 v36, v36
	v_mov_b32_e32 v46, v47
	v_pk_mul_f32 v[50:51], v[38:39], v[50:51] op_sel_hi:[0,1]
	v_pk_mul_f32 v[42:43], v[38:39], v[42:43] op_sel_hi:[0,1]
	v_pk_fma_f32 v[32:33], v[32:33], v[36:37], v[50:51] op_sel_hi:[1,0,1]
	v_pk_fma_f32 v[40:41], v[40:41], v[36:37], v[42:43] op_sel_hi:[1,0,1]
	v_cvt_pk_bf16_f32 v30, v32, v33
	v_cvt_pk_bf16_f32 v31, v40, v41
	global_store_dwordx2 v1, v[30:31], s[8:9]
	v_mov_b32_e32 v37, v38
	v_pk_mul_f32 v[10:11], v[10:11], v[36:37]
	s_add_u32 s8, s8, 0x8000
	s_addc_u32 s9, s9, 0
	v_add_f32_e32 v10, v10, v11
	s_mov_b64 exec, s[16:17]
	global_store_dword v2, v10, s[12:13]
	s_mov_b64 exec, s[18:19]
	global_store_dword v0, v47, s[14:15] offset:248
	s_mov_b64 exec, s[20:21]
	s_add_u32 s12, s12, 0x200
	s_addc_u32 s13, s13, 0
	global_load_dwordx2 v[130:131], v1, s[6:7]
	global_load_dword v147, v2, s[10:11]
	s_add_u32 s6, s6, 0x8000
	s_addc_u32 s7, s7, 0
	s_add_u32 s10, s10, 0x200
	s_addc_u32 s11, s11, 0
	v_readlane_b32 s0, v4, 16
	v_readlane_b32 s1, v5, 16
	s_waitcnt vmcnt(45)
	v_lshlrev_b32_e32 v50, 16, v100
	v_and_b32_e32 v51, 0xffff0000, v100
	v_lshlrev_b32_e32 v42, 16, v101
	v_and_b32_e32 v43, 0xffff0000, v101
	v_mov_b32_e32 v11, v132
	v_add_f32_e32 v36, s0, v46
	v_max_f32_e64 v37, s1, s1
	v_max_f32_e32 v47, v36, v37
	v_sub_f32_e32 v37, s1, v47
	v_sub_f32_e32 v36, v36, v47
	v_mul_f32_e32 v37, 0x3fb8aa3b, v37
	v_mul_f32_e32 v36, 0x3fb8aa3b, v36
	v_exp_f32_e32 v38, v37
	v_exp_f32_e32 v36, v36
	v_mov_b32_e32 v46, v47
	v_pk_mul_f32 v[50:51], v[38:39], v[50:51] op_sel_hi:[0,1]
	v_pk_mul_f32 v[42:43], v[38:39], v[42:43] op_sel_hi:[0,1]
	v_pk_fma_f32 v[32:33], v[32:33], v[36:37], v[50:51] op_sel_hi:[1,0,1]
	v_pk_fma_f32 v[40:41], v[40:41], v[36:37], v[42:43] op_sel_hi:[1,0,1]
	v_cvt_pk_bf16_f32 v30, v32, v33
	v_cvt_pk_bf16_f32 v31, v40, v41
	global_store_dwordx2 v1, v[30:31], s[8:9]
	v_mov_b32_e32 v37, v38
	v_pk_mul_f32 v[10:11], v[10:11], v[36:37]
	s_add_u32 s8, s8, 0x8000
	s_addc_u32 s9, s9, 0
	v_add_f32_e32 v10, v10, v11
	s_mov_b64 exec, s[16:17]
	global_store_dword v2, v10, s[12:13]
	s_mov_b64 exec, s[18:19]
	global_store_dword v0, v47, s[14:15] offset:264
	s_mov_b64 exec, s[20:21]
	s_add_u32 s12, s12, 0x200
	s_addc_u32 s13, s13, 0
	global_load_dwordx2 v[100:101], v1, s[6:7]
	global_load_dword v132, v2, s[10:11]
	s_add_u32 s6, s6, 0x8000
	s_addc_u32 s7, s7, 0
	s_add_u32 s10, s10, 0x200
	s_addc_u32 s11, s11, 0
	v_readlane_b32 s0, v4, 17
	v_readlane_b32 s1, v5, 17
	s_waitcnt vmcnt(45)
; DI unsigned pack2(float a, float b) { const f32x2 v = {a, b}; return __builtin_bit_cast(unsigned, __builtin_convertvector(v, bf16v2)); }
; DI float bflo(unsigned w) { return __uint_as_float(w << 16); }
; DI float bfhi(unsigned w) { return __uint_as_float(w & 0xffff0000u); }
; DI void phase_mlstm_scan(const Params& p) {
;     ...
;       for (int j = 0; j < 8; ++j) { raw[j] = *(const uint2*)(kv + (size_t)(cb + j) * 16384); kr[j] = don ? ks[(cb + j) * 128] : 0.f; }
; #pragma unroll
;       for (int j = 0; j < 8; ++j) {
;         const float B = csc[(cb + j) * 4], A = csc[(cb + j) * 4 + 1];
;         const float mnew = fmaxf(B + m, A);
;         const float wp = __expf(B + m - mnew), wl = __expf(A - mnew);
;         m = mnew;
;         c0 = wp * c0 + wl * bflo(raw[j].x); c1 = wp * c1 + wl * bfhi(raw[j].x); c2 = wp * c2 + wl * bflo(raw[j].y); c3 = wp * c3 + wl * bfhi(raw[j].y);
;         uint2 o; o.x = pack2(c0, c1); o.y = pack2(c2, c3);
;         *(uint2*)(kv + (size_t)(cb + j) * 16384) = o;
;         if (don) { n = wp * n + wl * kr[j]; ks[(cb + j) * 128] = n; }
;         if (part == 0 && tid == 0) csc[(cb + j) * 4 + 2] = mnew;
	v_lshlrev_b32_e32 v50, 16, v102
	v_and_b32_e32 v51, 0xffff0000, v102
	v_lshlrev_b32_e32 v42, 16, v103
	v_and_b32_e32 v43, 0xffff0000, v103
	v_mov_b32_e32 v11, v133
	v_add_f32_e32 v36, s0, v46
	v_max_f32_e64 v37, s1, s1
	v_max_f32_e32 v47, v36, v37
	v_sub_f32_e32 v37, s1, v47
	v_sub_f32_e32 v36, v36, v47
	v_mul_f32_e32 v37, 0x3fb8aa3b, v37
	v_mul_f32_e32 v36, 0x3fb8aa3b, v36
	v_exp_f32_e32 v38, v37
	v_exp_f32_e32 v36, v36
	v_mov_b32_e32 v46, v47
	v_pk_mul_f32 v[50:51], v[38:39], v[50:51] op_sel_hi:[0,1]
	v_pk_mul_f32 v[42:43], v[38:39], v[42:43] op_sel_hi:[0,1]
	v_pk_fma_f32 v[32:33], v[32:33], v[36:37], v[50:51] op_sel_hi:[1,0,1]
	v_pk_fma_f32 v[40:41], v[40:41], v[36:37], v[42:43] op_sel_hi:[1,0,1]
	v_cvt_pk_bf16_f32 v30, v32, v33
	v_cvt_pk_bf16_f32 v31, v40, v41
	global_store_dwordx2 v1, v[30:31], s[8:9]
	v_mov_b32_e32 v37, v38
	v_pk_mul_f32 v[10:11], v[10:11], v[36:37]
	s_add_u32 s8, s8, 0x8000
	s_addc_u32 s9, s9, 0
	v_add_f32_e32 v10, v10, v11
	s_mov_b64 exec, s[16:17]
	global_store_dword v2, v10, s[12:13]
	s_mov_b64 exec, s[18:19]
	global_store_dword v0, v47, s[14:15] offset:280
	s_mov_b64 exec, s[20:21]
	s_add_u32 s12, s12, 0x200
	s_addc_u32 s13, s13, 0
	global_load_dwordx2 v[102:103], v1, s[6:7]
	global_load_dword v133, v2, s[10:11]
	s_add_u32 s6, s6, 0x8000
	s_addc_u32 s7, s7, 0
	s_add_u32 s10, s10, 0x200
	s_addc_u32 s11, s11, 0
	v_readlane_b32 s0, v4, 18
	v_readlane_b32 s1, v5, 18
	s_waitcnt vmcnt(45)
	v_lshlrev_b32_e32 v50, 16, v104
	v_and_b32_e32 v51, 0xffff0000, v104
	v_lshlrev_b32_e32 v42, 16, v105
	v_and_b32_e32 v43, 0xffff0000, v105
	v_mov_b32_e32 v11, v134
	v_add_f32_e32 v36, s0, v46
	v_max_f32_e64 v37, s1, s1
	v_max_f32_e32 v47, v36, v37
	v_sub_f32_e32 v37, s1, v47
	v_sub_f32_e32 v36, v36, v47
	v_mul_f32_e32 v37, 0x3fb8aa3b, v37
	v_mul_f32_e32 v36, 0x3fb8aa3b, v36
	v_exp_f32_e32 v38, v37
	v_exp_f32_e32 v36, v36
	v_mov_b32_e32 v46, v47
	v_pk_mul_f32 v[50:51], v[38:39], v[50:51] op_sel_hi:[0,1]
	v_pk_mul_f32 v[42:43], v[38:39], v[42:43] op_sel_hi:[0,1]
	v_pk_fma_f32 v[32:33], v[32:33], v[36:37], v[50:51] op_sel_hi:[1,0,1]
	v_pk_fma_f32 v[40:41], v[40:41], v[36:37], v[42:43] op_sel_hi:[1,0,1]
	v_cvt_pk_bf16_f32 v30, v32, v33
	v_cvt_pk_bf16_f32 v31, v40, v41
	global_store_dwordx2 v1, v[30:31], s[8:9]
	v_mov_b32_e32 v37, v38
	v_pk_mul_f32 v[10:11], v[10:11], v[36:37]
	s_add_u32 s8, s8, 0x8000
	s_addc_u32 s9, s9, 0
	v_add_f32_e32 v10, v10, v11
	s_mov_b64 exec, s[16:17]
	global_store_dword v2, v10, s[12:13]
	s_mov_b64 exec, s[18:19]
	global_store_dword v0, v47, s[14:15] offset:296
	s_mov_b64 exec, s[20:21]
	s_add_u32 s12, s12, 0x200
	s_addc_u32 s13, s13, 0
	global_load_dwordx2 v[104:105], v1, s[6:7]
	global_load_dword v134, v2, s[10:11]
	s_add_u32 s6, s6, 0x8000
	s_addc_u32 s7, s7, 0
	s_add_u32 s10, s10, 0x200
	s_addc_u32 s11, s11, 0
	v_readlane_b32 s0, v4, 19
	v_readlane_b32 s1, v5, 19
	s_waitcnt vmcnt(45)
	v_lshlrev_b32_e32 v50, 16, v106
	v_and_b32_e32 v51, 0xffff0000, v106
	v_lshlrev_b32_e32 v42, 16, v107
	v_and_b32_e32 v43, 0xffff0000, v107
	v_mov_b32_e32 v11, v135
	v_add_f32_e32 v36, s0, v46
	v_max_f32_e64 v37, s1, s1
	v_max_f32_e32 v47, v36, v37
	v_sub_f32_e32 v37, s1, v47
	v_sub_f32_e32 v36, v36, v47
	v_mul_f32_e32 v37, 0x3fb8aa3b, v37
	v_mul_f32_e32 v36, 0x3fb8aa3b, v36
	v_exp_f32_e32 v38, v37
	v_exp_f32_e32 v36, v36
	v_mov_b32_e32 v46, v47
	v_pk_mul_f32 v[50:51], v[38:39], v[50:51] op_sel_hi:[0,1]
	v_pk_mul_f32 v[42:43], v[38:39], v[42:43] op_sel_hi:[0,1]
	v_pk_fma_f32 v[32:33], v[32:33], v[36:37], v[50:51] op_sel_hi:[1,0,1]
	v_pk_fma_f32 v[40:41], v[40:41], v[36:37], v[42:43] op_sel_hi:[1,0,1]
	v_cvt_pk_bf16_f32 v30, v32, v33
	v_cvt_pk_bf16_f32 v31, v40, v41
	global_store_dwordx2 v1, v[30:31], s[8:9]
	v_mov_b32_e32 v37, v38
	v_pk_mul_f32 v[10:11], v[10:11], v[36:37]
	s_add_u32 s8, s8, 0x8000
	s_addc_u32 s9, s9, 0
	v_add_f32_e32 v10, v10, v11
	s_mov_b64 exec, s[16:17]
	global_store_dword v2, v10, s[12:13]
	s_mov_b64 exec, s[18:19]
	global_store_dword v0, v47, s[14:15] offset:312
	s_mov_b64 exec, s[20:21]
	s_add_u32 s12, s12, 0x200
	s_addc_u32 s13, s13, 0
	global_load_dwordx2 v[106:107], v1, s[6:7]
	global_load_dword v135, v2, s[10:11]
	s_add_u32 s6, s6, 0x8000
	s_addc_u32 s7, s7, 0
	s_add_u32 s10, s10, 0x200
	s_addc_u32 s11, s11, 0
	v_readlane_b32 s0, v4, 20
	v_readlane_b32 s1, v5, 20
	s_waitcnt vmcnt(45)
	v_lshlrev_b32_e32 v50, 16, v108
	v_and_b32_e32 v51, 0xffff0000, v108
	v_lshlrev_b32_e32 v42, 16, v109
	v_and_b32_e32 v43, 0xffff0000, v109
	v_mov_b32_e32 v11, v136
	v_add_f32_e32 v36, s0, v46
	v_max_f32_e64 v37, s1, s1
	v_max_f32_e32 v47, v36, v37
	v_sub_f32_e32 v37, s1, v47
	v_sub_f32_e32 v36, v36, v47
	v_mul_f32_e32 v37, 0x3fb8aa3b, v37
	v_mul_f32_e32 v36, 0x3fb8aa3b, v36
	v_exp_f32_e32 v38, v37
	v_exp_f32_e32 v36, v36
	v_mov_b32_e32 v46, v47
	v_pk_mul_f32 v[50:51], v[38:39], v[50:51] op_sel_hi:[0,1]
	v_pk_mul_f32 v[42:43], v[38:39], v[42:43] op_sel_hi:[0,1]
	v_pk_fma_f32 v[32:33], v[32:33], v[36:37], v[50:51] op_sel_hi:[1,0,1]
	v_pk_fma_f32 v[40:41], v[40:41], v[36:37], v[42:43] op_sel_hi:[1,0,1]
	v_cvt_pk_bf16_f32 v30, v32, v33
	v_cvt_pk_bf16_f32 v31, v40, v41
	global_store_dwordx2 v1, v[30:31], s[8:9]
	v_mov_b32_e32 v37, v38
	v_pk_mul_f32 v[10:11], v[10:11], v[36:37]
	s_add_u32 s8, s8, 0x8000
	s_addc_u32 s9, s9, 0
	v_add_f32_e32 v10, v10, v11
	s_mov_b64 exec, s[16:17]
	global_store_dword v2, v10, s[12:13]
	s_mov_b64 exec, s[18:19]
	global_store_dword v0, v47, s[14:15] offset:328
	s_mov_b64 exec, s[20:21]
	s_add_u32 s12, s12, 0x200
	s_addc_u32 s13, s13, 0
	global_load_dwordx2 v[108:109], v1, s[6:7]
	global_load_dword v136, v2, s[10:11]
	s_add_u32 s6, s6, 0x8000
	s_addc_u32 s7, s7, 0
	s_add_u32 s10, s10, 0x200
	s_addc_u32 s11, s11, 0
	v_readlane_b32 s0, v4, 21
	v_readlane_b32 s1, v5, 21
	s_waitcnt vmcnt(45)
; DI unsigned pack2(float a, float b) { const f32x2 v = {a, b}; return __builtin_bit_cast(unsigned, __builtin_convertvector(v, bf16v2)); }
; DI float bflo(unsigned w) { return __uint_as_float(w << 16); }
; DI float bfhi(unsigned w) { return __uint_as_float(w & 0xffff0000u); }
; DI void phase_mlstm_scan(const Params& p) {
;     ...
;       for (int j = 0; j < 8; ++j) { raw[j] = *(const uint2*)(kv + (size_t)(cb + j) * 16384); kr[j] = don ? ks[(cb + j) * 128] : 0.f; }
; #pragma unroll
;       for (int j = 0; j < 8; ++j) {
;         const float B = csc[(cb + j) * 4], A = csc[(cb + j) * 4 + 1];
;         const float mnew = fmaxf(B + m, A);
;         const float wp = __expf(B + m - mnew), wl = __expf(A - mnew);
;         m = mnew;
;         c0 = wp * c0 + wl * bflo(raw[j].x); c1 = wp * c1 + wl * bfhi(raw[j].x); c2 = wp * c2 + wl * bflo(raw[j].y); c3 = wp * c3 + wl * bfhi(raw[j].y);
;         uint2 o; o.x = pack2(c0, c1); o.y = pack2(c2, c3);
;         *(uint2*)(kv + (size_t)(cb + j) * 16384) = o;
;         if (don) { n = wp * n + wl * kr[j]; ks[(cb + j) * 128] = n; }
;         if (part == 0 && tid == 0) csc[(cb + j) * 4 + 2] = mnew;
	v_lshlrev_b32_e32 v50, 16, v110
	v_and_b32_e32 v51, 0xffff0000, v110
	v_lshlrev_b32_e32 v42, 16, v111
	v_and_b32_e32 v43, 0xffff0000, v111
	v_mov_b32_e32 v11, v137
	v_add_f32_e32 v36, s0, v46
	v_max_f32_e64 v37, s1, s1
	v_max_f32_e32 v47, v36, v37
	v_sub_f32_e32 v37, s1, v47
	v_sub_f32_e32 v36, v36, v47
	v_mul_f32_e32 v37, 0x3fb8aa3b, v37
	v_mul_f32_e32 v36, 0x3fb8aa3b, v36
	v_exp_f32_e32 v38, v37
	v_exp_f32_e32 v36, v36
	v_mov_b32_e32 v46, v47
	v_pk_mul_f32 v[50:51], v[38:39], v[50:51] op_sel_hi:[0,1]
	v_pk_mul_f32 v[42:43], v[38:39], v[42:43] op_sel_hi:[0,1]
	v_pk_fma_f32 v[32:33], v[32:33], v[36:37], v[50:51] op_sel_hi:[1,0,1]
	v_pk_fma_f32 v[40:41], v[40:41], v[36:37], v[42:43] op_sel_hi:[1,0,1]
	v_cvt_pk_bf16_f32 v30, v32, v33
	v_cvt_pk_bf16_f32 v31, v40, v41
	global_store_dwordx2 v1, v[30:31], s[8:9]
	v_mov_b32_e32 v37, v38
	v_pk_mul_f32 v[10:11], v[10:11], v[36:37]
	s_add_u32 s8, s8, 0x8000
	s_addc_u32 s9, s9, 0
	v_add_f32_e32 v10, v10, v11
	s_mov_b64 exec, s[16:17]
	global_store_dword v2, v10, s[12:13]
	s_mov_b64 exec, s[18:19]
	global_store_dword v0, v47, s[14:15] offset:344
	s_mov_b64 exec, s[20:21]
	s_add_u32 s12, s12, 0x200
	s_addc_u32 s13, s13, 0
	global_load_dwordx2 v[110:111], v1, s[6:7]
	global_load_dword v137, v2, s[10:11]
	s_add_u32 s6, s6, 0x8000
	s_addc_u32 s7, s7, 0
	s_add_u32 s10, s10, 0x200
	s_addc_u32 s11, s11, 0
	v_readlane_b32 s0, v4, 22
	v_readlane_b32 s1, v5, 22
	s_waitcnt vmcnt(45)
	v_lshlrev_b32_e32 v50, 16, v112
	v_and_b32_e32 v51, 0xffff0000, v112
	v_lshlrev_b32_e32 v42, 16, v113
	v_and_b32_e32 v43, 0xffff0000, v113
	v_mov_b32_e32 v11, v138
	v_add_f32_e32 v36, s0, v46
	v_max_f32_e64 v37, s1, s1
	v_max_f32_e32 v47, v36, v37
	v_sub_f32_e32 v37, s1, v47
	v_sub_f32_e32 v36, v36, v47
	v_mul_f32_e32 v37, 0x3fb8aa3b, v37
	v_mul_f32_e32 v36, 0x3fb8aa3b, v36
	v_exp_f32_e32 v38, v37
	v_exp_f32_e32 v36, v36
	v_mov_b32_e32 v46, v47
	v_pk_mul_f32 v[50:51], v[38:39], v[50:51] op_sel_hi:[0,1]
	v_pk_mul_f32 v[42:43], v[38:39], v[42:43] op_sel_hi:[0,1]
	v_pk_fma_f32 v[32:33], v[32:33], v[36:37], v[50:51] op_sel_hi:[1,0,1]
	v_pk_fma_f32 v[40:41], v[40:41], v[36:37], v[42:43] op_sel_hi:[1,0,1]
	v_cvt_pk_bf16_f32 v30, v32, v33
	v_cvt_pk_bf16_f32 v31, v40, v41
	global_store_dwordx2 v1, v[30:31], s[8:9]
	v_mov_b32_e32 v37, v38
	v_pk_mul_f32 v[10:11], v[10:11], v[36:37]
	s_add_u32 s8, s8, 0x8000
	s_addc_u32 s9, s9, 0
	v_add_f32_e32 v10, v10, v11
	s_mov_b64 exec, s[16:17]
	global_store_dword v2, v10, s[12:13]
	s_mov_b64 exec, s[18:19]
	global_store_dword v0, v47, s[14:15] offset:360
	s_mov_b64 exec, s[20:21]
	s_add_u32 s12, s12, 0x200
	s_addc_u32 s13, s13, 0
	global_load_dwordx2 v[112:113], v1, s[6:7]
	global_load_dword v138, v2, s[10:11]
	s_add_u32 s6, s6, 0x8000
	s_addc_u32 s7, s7, 0
	s_add_u32 s10, s10, 0x200
	s_addc_u32 s11, s11, 0
	v_readlane_b32 s0, v4, 23
	v_readlane_b32 s1, v5, 23
	s_waitcnt vmcnt(45)
	v_lshlrev_b32_e32 v50, 16, v114
	v_and_b32_e32 v51, 0xffff0000, v114
	v_lshlrev_b32_e32 v42, 16, v115
	v_and_b32_e32 v43, 0xffff0000, v115
	v_mov_b32_e32 v11, v139
	v_add_f32_e32 v36, s0, v46
	v_max_f32_e64 v37, s1, s1
	v_max_f32_e32 v47, v36, v37
	v_sub_f32_e32 v37, s1, v47
	v_sub_f32_e32 v36, v36, v47
	v_mul_f32_e32 v37, 0x3fb8aa3b, v37
	v_mul_f32_e32 v36, 0x3fb8aa3b, v36
	v_exp_f32_e32 v38, v37
	v_exp_f32_e32 v36, v36
	v_mov_b32_e32 v46, v47
	v_pk_mul_f32 v[50:51], v[38:39], v[50:51] op_sel_hi:[0,1]
	v_pk_mul_f32 v[42:43], v[38:39], v[42:43] op_sel_hi:[0,1]
	v_pk_fma_f32 v[32:33], v[32:33], v[36:37], v[50:51] op_sel_hi:[1,0,1]
	v_pk_fma_f32 v[40:41], v[40:41], v[36:37], v[42:43] op_sel_hi:[1,0,1]
	v_cvt_pk_bf16_f32 v30, v32, v33
	v_cvt_pk_bf16_f32 v31, v40, v41
	global_store_dwordx2 v1, v[30:31], s[8:9]
	v_mov_b32_e32 v37, v38
	v_pk_mul_f32 v[10:11], v[10:11], v[36:37]
	s_add_u32 s8, s8, 0x8000
	s_addc_u32 s9, s9, 0
	v_add_f32_e32 v10, v10, v11
	s_mov_b64 exec, s[16:17]
	global_store_dword v2, v10, s[12:13]
	s_mov_b64 exec, s[18:19]
	global_store_dword v0, v47, s[14:15] offset:376
	s_mov_b64 exec, s[20:21]
	s_add_u32 s12, s12, 0x200
	s_addc_u32 s13, s13, 0
	global_load_dwordx2 v[114:115], v1, s[6:7]
	global_load_dword v139, v2, s[10:11]
	s_add_u32 s6, s6, 0x8000
	s_addc_u32 s7, s7, 0
	s_add_u32 s10, s10, 0x200
	s_addc_u32 s11, s11, 0
	v_readlane_b32 s0, v4, 24
	v_readlane_b32 s1, v5, 24
	s_waitcnt vmcnt(45)
	v_lshlrev_b32_e32 v50, 16, v116
	v_and_b32_e32 v51, 0xffff0000, v116
	v_lshlrev_b32_e32 v42, 16, v117
	v_and_b32_e32 v43, 0xffff0000, v117
	v_mov_b32_e32 v11, v140
	v_add_f32_e32 v36, s0, v46
	v_max_f32_e64 v37, s1, s1
	v_max_f32_e32 v47, v36, v37
	v_sub_f32_e32 v37, s1, v47
	v_sub_f32_e32 v36, v36, v47
	v_mul_f32_e32 v37, 0x3fb8aa3b, v37
	v_mul_f32_e32 v36, 0x3fb8aa3b, v36
	v_exp_f32_e32 v38, v37
	v_exp_f32_e32 v36, v36
	v_mov_b32_e32 v46, v47
	v_pk_mul_f32 v[50:51], v[38:39], v[50:51] op_sel_hi:[0,1]
	v_pk_mul_f32 v[42:43], v[38:39], v[42:43] op_sel_hi:[0,1]
	v_pk_fma_f32 v[32:33], v[32:33], v[36:37], v[50:51] op_sel_hi:[1,0,1]
	v_pk_fma_f32 v[40:41], v[40:41], v[36:37], v[42:43] op_sel_hi:[1,0,1]
	v_cvt_pk_bf16_f32 v30, v32, v33
	v_cvt_pk_bf16_f32 v31, v40, v41
	global_store_dwordx2 v1, v[30:31], s[8:9]
	v_mov_b32_e32 v37, v38
	v_pk_mul_f32 v[10:11], v[10:11], v[36:37]
	s_add_u32 s8, s8, 0x8000
	s_addc_u32 s9, s9, 0
	v_add_f32_e32 v10, v10, v11
	s_mov_b64 exec, s[16:17]
	global_store_dword v2, v10, s[12:13]
	s_mov_b64 exec, s[18:19]
	global_store_dword v0, v47, s[14:15] offset:392
	s_mov_b64 exec, s[20:21]
	s_add_u32 s12, s12, 0x200
	s_addc_u32 s13, s13, 0
	global_load_dwordx2 v[116:117], v1, s[6:7]
	global_load_dword v140, v2, s[10:11]
	s_add_u32 s6, s6, 0x8000
	s_addc_u32 s7, s7, 0
	s_add_u32 s10, s10, 0x200
	s_addc_u32 s11, s11, 0
	v_readlane_b32 s0, v4, 25
	v_readlane_b32 s1, v5, 25
	s_waitcnt vmcnt(45)
; DI unsigned pack2(float a, float b) { const f32x2 v = {a, b}; return __builtin_bit_cast(unsigned, __builtin_convertvector(v, bf16v2)); }
; DI float bflo(unsigned w) { return __uint_as_float(w << 16); }
; DI float bfhi(unsigned w) { return __uint_as_float(w & 0xffff0000u); }
; DI void phase_mlstm_scan(const Params& p) {
;     ...
;       for (int j = 0; j < 8; ++j) { raw[j] = *(const uint2*)(kv + (size_t)(cb + j) * 16384); kr[j] = don ? ks[(cb + j) * 128] : 0.f; }
; #pragma unroll
;       for (int j = 0; j < 8; ++j) {
;         const float B = csc[(cb + j) * 4], A = csc[(cb + j) * 4 + 1];
;         const float mnew = fmaxf(B + m, A);
;         const float wp = __expf(B + m - mnew), wl = __expf(A - mnew);
;         m = mnew;
;         c0 = wp * c0 + wl * bflo(raw[j].x); c1 = wp * c1 + wl * bfhi(raw[j].x); c2 = wp * c2 + wl * bflo(raw[j].y); c3 = wp * c3 + wl * bfhi(raw[j].y);
;         uint2 o; o.x = pack2(c0, c1); o.y = pack2(c2, c3);
;         *(uint2*)(kv + (size_t)(cb + j) * 16384) = o;
;         if (don) { n = wp * n + wl * kr[j]; ks[(cb + j) * 128] = n; }
;         if (part == 0 && tid == 0) csc[(cb + j) * 4 + 2] = mnew;
	v_lshlrev_b32_e32 v50, 16, v118
	v_and_b32_e32 v51, 0xffff0000, v118
	v_lshlrev_b32_e32 v42, 16, v119
	v_and_b32_e32 v43, 0xffff0000, v119
	v_mov_b32_e32 v11, v141
	v_add_f32_e32 v36, s0, v46
	v_max_f32_e64 v37, s1, s1
	v_max_f32_e32 v47, v36, v37
	v_sub_f32_e32 v37, s1, v47
	v_sub_f32_e32 v36, v36, v47
	v_mul_f32_e32 v37, 0x3fb8aa3b, v37
	v_mul_f32_e32 v36, 0x3fb8aa3b, v36
	v_exp_f32_e32 v38, v37
	v_exp_f32_e32 v36, v36
	v_mov_b32_e32 v46, v47
	v_pk_mul_f32 v[50:51], v[38:39], v[50:51] op_sel_hi:[0,1]
	v_pk_mul_f32 v[42:43], v[38:39], v[42:43] op_sel_hi:[0,1]
	v_pk_fma_f32 v[32:33], v[32:33], v[36:37], v[50:51] op_sel_hi:[1,0,1]
	v_pk_fma_f32 v[40:41], v[40:41], v[36:37], v[42:43] op_sel_hi:[1,0,1]
	v_cvt_pk_bf16_f32 v30, v32, v33
	v_cvt_pk_bf16_f32 v31, v40, v41
	global_store_dwordx2 v1, v[30:31], s[8:9]
	v_mov_b32_e32 v37, v38
	v_pk_mul_f32 v[10:11], v[10:11], v[36:37]
	s_add_u32 s8, s8, 0x8000
	s_addc_u32 s9, s9, 0
	v_add_f32_e32 v10, v10, v11
	s_mov_b64 exec, s[16:17]
	global_store_dword v2, v10, s[12:13]
	s_mov_b64 exec, s[18:19]
	global_store_dword v0, v47, s[14:15] offset:408
	s_mov_b64 exec, s[20:21]
	s_add_u32 s12, s12, 0x200
	s_addc_u32 s13, s13, 0
	global_load_dwordx2 v[118:119], v1, s[6:7]
	global_load_dword v141, v2, s[10:11]
	s_add_u32 s6, s6, 0x8000
	s_addc_u32 s7, s7, 0
	s_add_u32 s10, s10, 0x200
	s_addc_u32 s11, s11, 0
	v_readlane_b32 s0, v4, 26
	v_readlane_b32 s1, v5, 26
	s_waitcnt vmcnt(45)
	v_lshlrev_b32_e32 v50, 16, v120
	v_and_b32_e32 v51, 0xffff0000, v120
	v_lshlrev_b32_e32 v42, 16, v121
	v_and_b32_e32 v43, 0xffff0000, v121
	v_mov_b32_e32 v11, v142
	v_add_f32_e32 v36, s0, v46
	v_max_f32_e64 v37, s1, s1
	v_max_f32_e32 v47, v36, v37
	v_sub_f32_e32 v37, s1, v47
	v_sub_f32_e32 v36, v36, v47
	v_mul_f32_e32 v37, 0x3fb8aa3b, v37
	v_mul_f32_e32 v36, 0x3fb8aa3b, v36
	v_exp_f32_e32 v38, v37
	v_exp_f32_e32 v36, v36
	v_mov_b32_e32 v46, v47
	v_pk_mul_f32 v[50:51], v[38:39], v[50:51] op_sel_hi:[0,1]
	v_pk_mul_f32 v[42:43], v[38:39], v[42:43] op_sel_hi:[0,1]
	v_pk_fma_f32 v[32:33], v[32:33], v[36:37], v[50:51] op_sel_hi:[1,0,1]
	v_pk_fma_f32 v[40:41], v[40:41], v[36:37], v[42:43] op_sel_hi:[1,0,1]
	v_cvt_pk_bf16_f32 v30, v32, v33
	v_cvt_pk_bf16_f32 v31, v40, v41
	global_store_dwordx2 v1, v[30:31], s[8:9]
	v_mov_b32_e32 v37, v38
	v_pk_mul_f32 v[10:11], v[10:11], v[36:37]
	s_add_u32 s8, s8, 0x8000
	s_addc_u32 s9, s9, 0
	v_add_f32_e32 v10, v10, v11
	s_mov_b64 exec, s[16:17]
	global_store_dword v2, v10, s[12:13]
	s_mov_b64 exec, s[18:19]
	global_store_dword v0, v47, s[14:15] offset:424
	s_mov_b64 exec, s[20:21]
	s_add_u32 s12, s12, 0x200
	s_addc_u32 s13, s13, 0
	global_load_dwordx2 v[120:121], v1, s[6:7]
	global_load_dword v142, v2, s[10:11]
	s_add_u32 s6, s6, 0x8000
	s_addc_u32 s7, s7, 0
	s_add_u32 s10, s10, 0x200
	s_addc_u32 s11, s11, 0
	v_readlane_b32 s0, v4, 27
	v_readlane_b32 s1, v5, 27
	s_waitcnt vmcnt(45)
	v_lshlrev_b32_e32 v50, 16, v122
	v_and_b32_e32 v51, 0xffff0000, v122
	v_lshlrev_b32_e32 v42, 16, v123
	v_and_b32_e32 v43, 0xffff0000, v123
	v_mov_b32_e32 v11, v143
	v_add_f32_e32 v36, s0, v46
	v_max_f32_e64 v37, s1, s1
	v_max_f32_e32 v47, v36, v37
	v_sub_f32_e32 v37, s1, v47
	v_sub_f32_e32 v36, v36, v47
	v_mul_f32_e32 v37, 0x3fb8aa3b, v37
	v_mul_f32_e32 v36, 0x3fb8aa3b, v36
	v_exp_f32_e32 v38, v37
	v_exp_f32_e32 v36, v36
	v_mov_b32_e32 v46, v47
	v_pk_mul_f32 v[50:51], v[38:39], v[50:51] op_sel_hi:[0,1]
	v_pk_mul_f32 v[42:43], v[38:39], v[42:43] op_sel_hi:[0,1]
	v_pk_fma_f32 v[32:33], v[32:33], v[36:37], v[50:51] op_sel_hi:[1,0,1]
	v_pk_fma_f32 v[40:41], v[40:41], v[36:37], v[42:43] op_sel_hi:[1,0,1]
	v_cvt_pk_bf16_f32 v30, v32, v33
	v_cvt_pk_bf16_f32 v31, v40, v41
	global_store_dwordx2 v1, v[30:31], s[8:9]
	v_mov_b32_e32 v37, v38
	v_pk_mul_f32 v[10:11], v[10:11], v[36:37]
	s_add_u32 s8, s8, 0x8000
	s_addc_u32 s9, s9, 0
	v_add_f32_e32 v10, v10, v11
	s_mov_b64 exec, s[16:17]
	global_store_dword v2, v10, s[12:13]
	s_mov_b64 exec, s[18:19]
	global_store_dword v0, v47, s[14:15] offset:440
	s_mov_b64 exec, s[20:21]
	s_add_u32 s12, s12, 0x200
	s_addc_u32 s13, s13, 0
	global_load_dwordx2 v[122:123], v1, s[6:7]
	global_load_dword v143, v2, s[10:11]
	s_add_u32 s6, s6, 0x8000
	s_addc_u32 s7, s7, 0
	s_add_u32 s10, s10, 0x200
	s_addc_u32 s11, s11, 0
	v_readlane_b32 s0, v4, 28
	v_readlane_b32 s1, v5, 28
	s_waitcnt vmcnt(45)
	v_lshlrev_b32_e32 v50, 16, v124
	v_and_b32_e32 v51, 0xffff0000, v124
	v_lshlrev_b32_e32 v42, 16, v125
	v_and_b32_e32 v43, 0xffff0000, v125
	v_mov_b32_e32 v11, v144
	v_add_f32_e32 v36, s0, v46
	v_max_f32_e64 v37, s1, s1
	v_max_f32_e32 v47, v36, v37
	v_sub_f32_e32 v37, s1, v47
	v_sub_f32_e32 v36, v36, v47
	v_mul_f32_e32 v37, 0x3fb8aa3b, v37
	v_mul_f32_e32 v36, 0x3fb8aa3b, v36
	v_exp_f32_e32 v38, v37
	v_exp_f32_e32 v36, v36
	v_mov_b32_e32 v46, v47
	v_pk_mul_f32 v[50:51], v[38:39], v[50:51] op_sel_hi:[0,1]
	v_pk_mul_f32 v[42:43], v[38:39], v[42:43] op_sel_hi:[0,1]
	v_pk_fma_f32 v[32:33], v[32:33], v[36:37], v[50:51] op_sel_hi:[1,0,1]
	v_pk_fma_f32 v[40:41], v[40:41], v[36:37], v[42:43] op_sel_hi:[1,0,1]
	v_cvt_pk_bf16_f32 v30, v32, v33
	v_cvt_pk_bf16_f32 v31, v40, v41
	global_store_dwordx2 v1, v[30:31], s[8:9]
	v_mov_b32_e32 v37, v38
	v_pk_mul_f32 v[10:11], v[10:11], v[36:37]
	s_add_u32 s8, s8, 0x8000
	s_addc_u32 s9, s9, 0
	v_add_f32_e32 v10, v10, v11
	s_mov_b64 exec, s[16:17]
	global_store_dword v2, v10, s[12:13]
	s_mov_b64 exec, s[18:19]
	global_store_dword v0, v47, s[14:15] offset:456
	s_mov_b64 exec, s[20:21]
	s_add_u32 s12, s12, 0x200
	s_addc_u32 s13, s13, 0
	global_load_dwordx2 v[124:125], v1, s[6:7]
	global_load_dword v144, v2, s[10:11]
	s_add_u32 s6, s6, 0x8000
	s_addc_u32 s7, s7, 0
	s_add_u32 s10, s10, 0x200
	s_addc_u32 s11, s11, 0
	v_readlane_b32 s0, v4, 29
	v_readlane_b32 s1, v5, 29
	s_waitcnt vmcnt(45)
; DI unsigned pack2(float a, float b) { const f32x2 v = {a, b}; return __builtin_bit_cast(unsigned, __builtin_convertvector(v, bf16v2)); }
; DI float bflo(unsigned w) { return __uint_as_float(w << 16); }
; DI float bfhi(unsigned w) { return __uint_as_float(w & 0xffff0000u); }
; DI void phase_mlstm_scan(const Params& p) {
;     ...
;       for (int j = 0; j < 8; ++j) { raw[j] = *(const uint2*)(kv + (size_t)(cb + j) * 16384); kr[j] = don ? ks[(cb + j) * 128] : 0.f; }
; #pragma unroll
;       for (int j = 0; j < 8; ++j) {
;         const float B = csc[(cb + j) * 4], A = csc[(cb + j) * 4 + 1];
;         const float mnew = fmaxf(B + m, A);
;         const float wp = __expf(B + m - mnew), wl = __expf(A - mnew);
;         m = mnew;
;         c0 = wp * c0 + wl * bflo(raw[j].x); c1 = wp * c1 + wl * bfhi(raw[j].x); c2 = wp * c2 + wl * bflo(raw[j].y); c3 = wp * c3 + wl * bfhi(raw[j].y);
;         uint2 o; o.x = pack2(c0, c1); o.y = pack2(c2, c3);
;         *(uint2*)(kv + (size_t)(cb + j) * 16384) = o;
;         if (don) { n = wp * n + wl * kr[j]; ks[(cb + j) * 128] = n; }
;         if (part == 0 && tid == 0) csc[(cb + j) * 4 + 2] = mnew;
	v_lshlrev_b32_e32 v50, 16, v126
	v_and_b32_e32 v51, 0xffff0000, v126
	v_lshlrev_b32_e32 v42, 16, v127
	v_and_b32_e32 v43, 0xffff0000, v127
	v_mov_b32_e32 v11, v145
	v_add_f32_e32 v36, s0, v46
	v_max_f32_e64 v37, s1, s1
	v_max_f32_e32 v47, v36, v37
	v_sub_f32_e32 v37, s1, v47
	v_sub_f32_e32 v36, v36, v47
	v_mul_f32_e32 v37, 0x3fb8aa3b, v37
	v_mul_f32_e32 v36, 0x3fb8aa3b, v36
	v_exp_f32_e32 v38, v37
	v_exp_f32_e32 v36, v36
	v_mov_b32_e32 v46, v47
	v_pk_mul_f32 v[50:51], v[38:39], v[50:51] op_sel_hi:[0,1]
	v_pk_mul_f32 v[42:43], v[38:39], v[42:43] op_sel_hi:[0,1]
	v_pk_fma_f32 v[32:33], v[32:33], v[36:37], v[50:51] op_sel_hi:[1,0,1]
	v_pk_fma_f32 v[40:41], v[40:41], v[36:37], v[42:43] op_sel_hi:[1,0,1]
	v_cvt_pk_bf16_f32 v30, v32, v33
	v_cvt_pk_bf16_f32 v31, v40, v41
	global_store_dwordx2 v1, v[30:31], s[8:9]
	v_mov_b32_e32 v37, v38
	v_pk_mul_f32 v[10:11], v[10:11], v[36:37]
	s_add_u32 s8, s8, 0x8000
	s_addc_u32 s9, s9, 0
	v_add_f32_e32 v10, v10, v11
	s_mov_b64 exec, s[16:17]
	global_store_dword v2, v10, s[12:13]
	s_mov_b64 exec, s[18:19]
	global_store_dword v0, v47, s[14:15] offset:472
	s_mov_b64 exec, s[20:21]
	s_add_u32 s12, s12, 0x200
	s_addc_u32 s13, s13, 0
	global_load_dwordx2 v[126:127], v1, s[6:7]
	global_load_dword v145, v2, s[10:11]
	s_add_u32 s6, s6, 0x8000
	s_addc_u32 s7, s7, 0
	s_add_u32 s10, s10, 0x200
	s_addc_u32 s11, s11, 0
	v_readlane_b32 s0, v4, 30
	v_readlane_b32 s1, v5, 30
	s_waitcnt vmcnt(45)
	v_lshlrev_b32_e32 v50, 16, v128
	v_and_b32_e32 v51, 0xffff0000, v128
	v_lshlrev_b32_e32 v42, 16, v129
	v_and_b32_e32 v43, 0xffff0000, v129
	v_mov_b32_e32 v11, v146
	v_add_f32_e32 v36, s0, v46
	v_max_f32_e64 v37, s1, s1
	v_max_f32_e32 v47, v36, v37
	v_sub_f32_e32 v37, s1, v47
	v_sub_f32_e32 v36, v36, v47
	v_mul_f32_e32 v37, 0x3fb8aa3b, v37
	v_mul_f32_e32 v36, 0x3fb8aa3b, v36
	v_exp_f32_e32 v38, v37
	v_exp_f32_e32 v36, v36
	v_mov_b32_e32 v46, v47
	v_pk_mul_f32 v[50:51], v[38:39], v[50:51] op_sel_hi:[0,1]
	v_pk_mul_f32 v[42:43], v[38:39], v[42:43] op_sel_hi:[0,1]
	v_pk_fma_f32 v[32:33], v[32:33], v[36:37], v[50:51] op_sel_hi:[1,0,1]
	v_pk_fma_f32 v[40:41], v[40:41], v[36:37], v[42:43] op_sel_hi:[1,0,1]
	v_cvt_pk_bf16_f32 v30, v32, v33
	v_cvt_pk_bf16_f32 v31, v40, v41
	global_store_dwordx2 v1, v[30:31], s[8:9]
	v_mov_b32_e32 v37, v38
	v_pk_mul_f32 v[10:11], v[10:11], v[36:37]
	s_add_u32 s8, s8, 0x8000
	s_addc_u32 s9, s9, 0
	v_add_f32_e32 v10, v10, v11
	s_mov_b64 exec, s[16:17]
	global_store_dword v2, v10, s[12:13]
	s_mov_b64 exec, s[18:19]
	global_store_dword v0, v47, s[14:15] offset:488
	s_mov_b64 exec, s[20:21]
	s_add_u32 s12, s12, 0x200
	s_addc_u32 s13, s13, 0
	global_load_dwordx2 v[128:129], v1, s[6:7]
	global_load_dword v146, v2, s[10:11]
	s_add_u32 s6, s6, 0x8000
	s_addc_u32 s7, s7, 0
	s_add_u32 s10, s10, 0x200
	s_addc_u32 s11, s11, 0
	v_readlane_b32 s0, v4, 31
	v_readlane_b32 s1, v5, 31
	s_waitcnt vmcnt(45)
	v_lshlrev_b32_e32 v50, 16, v130
	v_and_b32_e32 v51, 0xffff0000, v130
	v_lshlrev_b32_e32 v42, 16, v131
	v_and_b32_e32 v43, 0xffff0000, v131
	v_mov_b32_e32 v11, v147
	v_add_f32_e32 v36, s0, v46
	v_max_f32_e64 v37, s1, s1
	v_max_f32_e32 v47, v36, v37
	v_sub_f32_e32 v37, s1, v47
	v_sub_f32_e32 v36, v36, v47
	v_mul_f32_e32 v37, 0x3fb8aa3b, v37
	v_mul_f32_e32 v36, 0x3fb8aa3b, v36
	v_exp_f32_e32 v38, v37
	v_exp_f32_e32 v36, v36
	v_mov_b32_e32 v46, v47
	v_pk_mul_f32 v[50:51], v[38:39], v[50:51] op_sel_hi:[0,1]
	v_pk_mul_f32 v[42:43], v[38:39], v[42:43] op_sel_hi:[0,1]
	v_pk_fma_f32 v[32:33], v[32:33], v[36:37], v[50:51] op_sel_hi:[1,0,1]
	v_pk_fma_f32 v[40:41], v[40:41], v[36:37], v[42:43] op_sel_hi:[1,0,1]
	v_cvt_pk_bf16_f32 v30, v32, v33
	v_cvt_pk_bf16_f32 v31, v40, v41
	global_store_dwordx2 v1, v[30:31], s[8:9]
	v_mov_b32_e32 v37, v38
	v_pk_mul_f32 v[10:11], v[10:11], v[36:37]
	s_add_u32 s8, s8, 0x8000
	s_addc_u32 s9, s9, 0
	v_add_f32_e32 v10, v10, v11
	s_mov_b64 exec, s[16:17]
	global_store_dword v2, v10, s[12:13]
	s_mov_b64 exec, s[18:19]
	global_store_dword v0, v47, s[14:15] offset:504
	s_mov_b64 exec, s[20:21]
	s_add_u32 s12, s12, 0x200
	s_addc_u32 s13, s13, 0
	global_load_dwordx2 v[130:131], v1, s[6:7]
	global_load_dword v147, v2, s[10:11]
	s_add_u32 s6, s6, 0x8000
	s_addc_u32 s7, s7, 0
	s_add_u32 s10, s10, 0x200
	s_addc_u32 s11, s11, 0
	v_readlane_b32 s0, v4, 32
	v_readlane_b32 s1, v5, 32
	s_waitcnt vmcnt(45)
	v_lshlrev_b32_e32 v50, 16, v100
	v_and_b32_e32 v51, 0xffff0000, v100
	v_lshlrev_b32_e32 v42, 16, v101
	v_and_b32_e32 v43, 0xffff0000, v101
	v_mov_b32_e32 v11, v132
	v_add_f32_e32 v36, s0, v46
	v_max_f32_e64 v37, s1, s1
	v_max_f32_e32 v47, v36, v37
	v_sub_f32_e32 v37, s1, v47
	v_sub_f32_e32 v36, v36, v47
	v_mul_f32_e32 v37, 0x3fb8aa3b, v37
	v_mul_f32_e32 v36, 0x3fb8aa3b, v36
	v_exp_f32_e32 v38, v37
	v_exp_f32_e32 v36, v36
	v_mov_b32_e32 v46, v47
	v_pk_mul_f32 v[50:51], v[38:39], v[50:51] op_sel_hi:[0,1]
	v_pk_mul_f32 v[42:43], v[38:39], v[42:43] op_sel_hi:[0,1]
	v_pk_fma_f32 v[32:33], v[32:33], v[36:37], v[50:51] op_sel_hi:[1,0,1]
	v_pk_fma_f32 v[40:41], v[40:41], v[36:37], v[42:43] op_sel_hi:[1,0,1]
	v_cvt_pk_bf16_f32 v30, v32, v33
	v_cvt_pk_bf16_f32 v31, v40, v41
	global_store_dwordx2 v1, v[30:31], s[8:9]
	v_mov_b32_e32 v37, v38
	v_pk_mul_f32 v[10:11], v[10:11], v[36:37]
	s_add_u32 s8, s8, 0x8000
	s_addc_u32 s9, s9, 0
	v_add_f32_e32 v10, v10, v11
	s_mov_b64 exec, s[16:17]
	global_store_dword v2, v10, s[12:13]
	s_mov_b64 exec, s[18:19]
	global_store_dword v0, v47, s[14:15] offset:520
	s_mov_b64 exec, s[20:21]
	s_add_u32 s12, s12, 0x200
	s_addc_u32 s13, s13, 0
	global_load_dwordx2 v[100:101], v1, s[6:7]
	global_load_dword v132, v2, s[10:11]
	s_add_u32 s6, s6, 0x8000
	s_addc_u32 s7, s7, 0
	s_add_u32 s10, s10, 0x200
	s_addc_u32 s11, s11, 0
	v_readlane_b32 s0, v4, 33
	v_readlane_b32 s1, v5, 33
	s_waitcnt vmcnt(45)
; DI unsigned pack2(float a, float b) { const f32x2 v = {a, b}; return __builtin_bit_cast(unsigned, __builtin_convertvector(v, bf16v2)); }
; DI float bflo(unsigned w) { return __uint_as_float(w << 16); }
; DI float bfhi(unsigned w) { return __uint_as_float(w & 0xffff0000u); }
; DI void phase_mlstm_scan(const Params& p) {
;     ...
;       for (int j = 0; j < 8; ++j) { raw[j] = *(const uint2*)(kv + (size_t)(cb + j) * 16384); kr[j] = don ? ks[(cb + j) * 128] : 0.f; }
; #pragma unroll
;       for (int j = 0; j < 8; ++j) {
;         const float B = csc[(cb + j) * 4], A = csc[(cb + j) * 4 + 1];
;         const float mnew = fmaxf(B + m, A);
;         const float wp = __expf(B + m - mnew), wl = __expf(A - mnew);
;         m = mnew;
;         c0 = wp * c0 + wl * bflo(raw[j].x); c1 = wp * c1 + wl * bfhi(raw[j].x); c2 = wp * c2 + wl * bflo(raw[j].y); c3 = wp * c3 + wl * bfhi(raw[j].y);
;         uint2 o; o.x = pack2(c0, c1); o.y = pack2(c2, c3);
;         *(uint2*)(kv + (size_t)(cb + j) * 16384) = o;
;         if (don) { n = wp * n + wl * kr[j]; ks[(cb + j) * 128] = n; }
;         if (part == 0 && tid == 0) csc[(cb + j) * 4 + 2] = mnew;
	v_lshlrev_b32_e32 v50, 16, v102
	v_and_b32_e32 v51, 0xffff0000, v102
	v_lshlrev_b32_e32 v42, 16, v103
	v_and_b32_e32 v43, 0xffff0000, v103
	v_mov_b32_e32 v11, v133
	v_add_f32_e32 v36, s0, v46
	v_max_f32_e64 v37, s1, s1
	v_max_f32_e32 v47, v36, v37
	v_sub_f32_e32 v37, s1, v47
	v_sub_f32_e32 v36, v36, v47
	v_mul_f32_e32 v37, 0x3fb8aa3b, v37
	v_mul_f32_e32 v36, 0x3fb8aa3b, v36
	v_exp_f32_e32 v38, v37
	v_exp_f32_e32 v36, v36
	v_mov_b32_e32 v46, v47
	v_pk_mul_f32 v[50:51], v[38:39], v[50:51] op_sel_hi:[0,1]
	v_pk_mul_f32 v[42:43], v[38:39], v[42:43] op_sel_hi:[0,1]
	v_pk_fma_f32 v[32:33], v[32:33], v[36:37], v[50:51] op_sel_hi:[1,0,1]
	v_pk_fma_f32 v[40:41], v[40:41], v[36:37], v[42:43] op_sel_hi:[1,0,1]
	v_cvt_pk_bf16_f32 v30, v32, v33
	v_cvt_pk_bf16_f32 v31, v40, v41
	global_store_dwordx2 v1, v[30:31], s[8:9]
	v_mov_b32_e32 v37, v38
	v_pk_mul_f32 v[10:11], v[10:11], v[36:37]
	s_add_u32 s8, s8, 0x8000
	s_addc_u32 s9, s9, 0
	v_add_f32_e32 v10, v10, v11
	s_mov_b64 exec, s[16:17]
	global_store_dword v2, v10, s[12:13]
	s_mov_b64 exec, s[18:19]
	global_store_dword v0, v47, s[14:15] offset:536
	s_mov_b64 exec, s[20:21]
	s_add_u32 s12, s12, 0x200
	s_addc_u32 s13, s13, 0
	global_load_dwordx2 v[102:103], v1, s[6:7]
	global_load_dword v133, v2, s[10:11]
	s_add_u32 s6, s6, 0x8000
	s_addc_u32 s7, s7, 0
	s_add_u32 s10, s10, 0x200
	s_addc_u32 s11, s11, 0
	v_readlane_b32 s0, v4, 34
	v_readlane_b32 s1, v5, 34
	s_waitcnt vmcnt(45)
	v_lshlrev_b32_e32 v50, 16, v104
	v_and_b32_e32 v51, 0xffff0000, v104
	v_lshlrev_b32_e32 v42, 16, v105
	v_and_b32_e32 v43, 0xffff0000, v105
	v_mov_b32_e32 v11, v134
	v_add_f32_e32 v36, s0, v46
	v_max_f32_e64 v37, s1, s1
	v_max_f32_e32 v47, v36, v37
	v_sub_f32_e32 v37, s1, v47
	v_sub_f32_e32 v36, v36, v47
	v_mul_f32_e32 v37, 0x3fb8aa3b, v37
	v_mul_f32_e32 v36, 0x3fb8aa3b, v36
	v_exp_f32_e32 v38, v37
	v_exp_f32_e32 v36, v36
	v_mov_b32_e32 v46, v47
	v_pk_mul_f32 v[50:51], v[38:39], v[50:51] op_sel_hi:[0,1]
	v_pk_mul_f32 v[42:43], v[38:39], v[42:43] op_sel_hi:[0,1]
	v_pk_fma_f32 v[32:33], v[32:33], v[36:37], v[50:51] op_sel_hi:[1,0,1]
	v_pk_fma_f32 v[40:41], v[40:41], v[36:37], v[42:43] op_sel_hi:[1,0,1]
	v_cvt_pk_bf16_f32 v30, v32, v33
	v_cvt_pk_bf16_f32 v31, v40, v41
	global_store_dwordx2 v1, v[30:31], s[8:9]
	v_mov_b32_e32 v37, v38
	v_pk_mul_f32 v[10:11], v[10:11], v[36:37]
	s_add_u32 s8, s8, 0x8000
	s_addc_u32 s9, s9, 0
	v_add_f32_e32 v10, v10, v11
	s_mov_b64 exec, s[16:17]
	global_store_dword v2, v10, s[12:13]
	s_mov_b64 exec, s[18:19]
	global_store_dword v0, v47, s[14:15] offset:552
	s_mov_b64 exec, s[20:21]
	s_add_u32 s12, s12, 0x200
	s_addc_u32 s13, s13, 0
	global_load_dwordx2 v[104:105], v1, s[6:7]
	global_load_dword v134, v2, s[10:11]
	s_add_u32 s6, s6, 0x8000
	s_addc_u32 s7, s7, 0
	s_add_u32 s10, s10, 0x200
	s_addc_u32 s11, s11, 0
	v_readlane_b32 s0, v4, 35
	v_readlane_b32 s1, v5, 35
	s_waitcnt vmcnt(45)
	v_lshlrev_b32_e32 v50, 16, v106
	v_and_b32_e32 v51, 0xffff0000, v106
	v_lshlrev_b32_e32 v42, 16, v107
	v_and_b32_e32 v43, 0xffff0000, v107
	v_mov_b32_e32 v11, v135
	v_add_f32_e32 v36, s0, v46
	v_max_f32_e64 v37, s1, s1
	v_max_f32_e32 v47, v36, v37
	v_sub_f32_e32 v37, s1, v47
	v_sub_f32_e32 v36, v36, v47
	v_mul_f32_e32 v37, 0x3fb8aa3b, v37
	v_mul_f32_e32 v36, 0x3fb8aa3b, v36
	v_exp_f32_e32 v38, v37
	v_exp_f32_e32 v36, v36
	v_mov_b32_e32 v46, v47
	v_pk_mul_f32 v[50:51], v[38:39], v[50:51] op_sel_hi:[0,1]
	v_pk_mul_f32 v[42:43], v[38:39], v[42:43] op_sel_hi:[0,1]
	v_pk_fma_f32 v[32:33], v[32:33], v[36:37], v[50:51] op_sel_hi:[1,0,1]
	v_pk_fma_f32 v[40:41], v[40:41], v[36:37], v[42:43] op_sel_hi:[1,0,1]
	v_cvt_pk_bf16_f32 v30, v32, v33
	v_cvt_pk_bf16_f32 v31, v40, v41
	global_store_dwordx2 v1, v[30:31], s[8:9]
	v_mov_b32_e32 v37, v38
	v_pk_mul_f32 v[10:11], v[10:11], v[36:37]
	s_add_u32 s8, s8, 0x8000
	s_addc_u32 s9, s9, 0
	v_add_f32_e32 v10, v10, v11
	s_mov_b64 exec, s[16:17]
	global_store_dword v2, v10, s[12:13]
	s_mov_b64 exec, s[18:19]
	global_store_dword v0, v47, s[14:15] offset:568
	s_mov_b64 exec, s[20:21]
	s_add_u32 s12, s12, 0x200
	s_addc_u32 s13, s13, 0
	global_load_dwordx2 v[106:107], v1, s[6:7]
	global_load_dword v135, v2, s[10:11]
	s_add_u32 s6, s6, 0x8000
	s_addc_u32 s7, s7, 0
	s_add_u32 s10, s10, 0x200
	s_addc_u32 s11, s11, 0
	v_readlane_b32 s0, v4, 36
	v_readlane_b32 s1, v5, 36
	s_waitcnt vmcnt(45)
	v_lshlrev_b32_e32 v50, 16, v108
	v_and_b32_e32 v51, 0xffff0000, v108
	v_lshlrev_b32_e32 v42, 16, v109
	v_and_b32_e32 v43, 0xffff0000, v109
	v_mov_b32_e32 v11, v136
	v_add_f32_e32 v36, s0, v46
	v_max_f32_e64 v37, s1, s1
	v_max_f32_e32 v47, v36, v37
	v_sub_f32_e32 v37, s1, v47
	v_sub_f32_e32 v36, v36, v47
	v_mul_f32_e32 v37, 0x3fb8aa3b, v37
	v_mul_f32_e32 v36, 0x3fb8aa3b, v36
	v_exp_f32_e32 v38, v37
	v_exp_f32_e32 v36, v36
	v_mov_b32_e32 v46, v47
	v_pk_mul_f32 v[50:51], v[38:39], v[50:51] op_sel_hi:[0,1]
	v_pk_mul_f32 v[42:43], v[38:39], v[42:43] op_sel_hi:[0,1]
	v_pk_fma_f32 v[32:33], v[32:33], v[36:37], v[50:51] op_sel_hi:[1,0,1]
	v_pk_fma_f32 v[40:41], v[40:41], v[36:37], v[42:43] op_sel_hi:[1,0,1]
	v_cvt_pk_bf16_f32 v30, v32, v33
	v_cvt_pk_bf16_f32 v31, v40, v41
	global_store_dwordx2 v1, v[30:31], s[8:9]
	v_mov_b32_e32 v37, v38
	v_pk_mul_f32 v[10:11], v[10:11], v[36:37]
	s_add_u32 s8, s8, 0x8000
	s_addc_u32 s9, s9, 0
	v_add_f32_e32 v10, v10, v11
	s_mov_b64 exec, s[16:17]
	global_store_dword v2, v10, s[12:13]
	s_mov_b64 exec, s[18:19]
	global_store_dword v0, v47, s[14:15] offset:584
	s_mov_b64 exec, s[20:21]
	s_add_u32 s12, s12, 0x200
	s_addc_u32 s13, s13, 0
	global_load_dwordx2 v[108:109], v1, s[6:7]
	global_load_dword v136, v2, s[10:11]
	s_add_u32 s6, s6, 0x8000
	s_addc_u32 s7, s7, 0
	s_add_u32 s10, s10, 0x200
	s_addc_u32 s11, s11, 0
	v_readlane_b32 s0, v4, 37
	v_readlane_b32 s1, v5, 37
	s_waitcnt vmcnt(45)
; DI unsigned pack2(float a, float b) { const f32x2 v = {a, b}; return __builtin_bit_cast(unsigned, __builtin_convertvector(v, bf16v2)); }
; DI float bflo(unsigned w) { return __uint_as_float(w << 16); }
; DI float bfhi(unsigned w) { return __uint_as_float(w & 0xffff0000u); }
; DI void phase_mlstm_scan(const Params& p) {
;     ...
;       for (int j = 0; j < 8; ++j) { raw[j] = *(const uint2*)(kv + (size_t)(cb + j) * 16384); kr[j] = don ? ks[(cb + j) * 128] : 0.f; }
; #pragma unroll
;       for (int j = 0; j < 8; ++j) {
;         const float B = csc[(cb + j) * 4], A = csc[(cb + j) * 4 + 1];
;         const float mnew = fmaxf(B + m, A);
;         const float wp = __expf(B + m - mnew), wl = __expf(A - mnew);
;         m = mnew;
;         c0 = wp * c0 + wl * bflo(raw[j].x); c1 = wp * c1 + wl * bfhi(raw[j].x); c2 = wp * c2 + wl * bflo(raw[j].y); c3 = wp * c3 + wl * bfhi(raw[j].y);
;         uint2 o; o.x = pack2(c0, c1); o.y = pack2(c2, c3);
;         *(uint2*)(kv + (size_t)(cb + j) * 16384) = o;
;         if (don) { n = wp * n + wl * kr[j]; ks[(cb + j) * 128] = n; }
;         if (part == 0 && tid == 0) csc[(cb + j) * 4 + 2] = mnew;
	v_lshlrev_b32_e32 v50, 16, v110
	v_and_b32_e32 v51, 0xffff0000, v110
	v_lshlrev_b32_e32 v42, 16, v111
	v_and_b32_e32 v43, 0xffff0000, v111
	v_mov_b32_e32 v11, v137
	v_add_f32_e32 v36, s0, v46
	v_max_f32_e64 v37, s1, s1
	v_max_f32_e32 v47, v36, v37
	v_sub_f32_e32 v37, s1, v47
	v_sub_f32_e32 v36, v36, v47
	v_mul_f32_e32 v37, 0x3fb8aa3b, v37
	v_mul_f32_e32 v36, 0x3fb8aa3b, v36
	v_exp_f32_e32 v38, v37
	v_exp_f32_e32 v36, v36
	v_mov_b32_e32 v46, v47
	v_pk_mul_f32 v[50:51], v[38:39], v[50:51] op_sel_hi:[0,1]
	v_pk_mul_f32 v[42:43], v[38:39], v[42:43] op_sel_hi:[0,1]
	v_pk_fma_f32 v[32:33], v[32:33], v[36:37], v[50:51] op_sel_hi:[1,0,1]
	v_pk_fma_f32 v[40:41], v[40:41], v[36:37], v[42:43] op_sel_hi:[1,0,1]
	v_cvt_pk_bf16_f32 v30, v32, v33
	v_cvt_pk_bf16_f32 v31, v40, v41
	global_store_dwordx2 v1, v[30:31], s[8:9]
	v_mov_b32_e32 v37, v38
	v_pk_mul_f32 v[10:11], v[10:11], v[36:37]
	s_add_u32 s8, s8, 0x8000
	s_addc_u32 s9, s9, 0
	v_add_f32_e32 v10, v10, v11
	s_mov_b64 exec, s[16:17]
	global_store_dword v2, v10, s[12:13]
	s_mov_b64 exec, s[18:19]
	global_store_dword v0, v47, s[14:15] offset:600
	s_mov_b64 exec, s[20:21]
	s_add_u32 s12, s12, 0x200
	s_addc_u32 s13, s13, 0
	global_load_dwordx2 v[110:111], v1, s[6:7]
	global_load_dword v137, v2, s[10:11]
	s_add_u32 s6, s6, 0x8000
	s_addc_u32 s7, s7, 0
	s_add_u32 s10, s10, 0x200
	s_addc_u32 s11, s11, 0
	v_readlane_b32 s0, v4, 38
	v_readlane_b32 s1, v5, 38
	s_waitcnt vmcnt(45)
	v_lshlrev_b32_e32 v50, 16, v112
	v_and_b32_e32 v51, 0xffff0000, v112
	v_lshlrev_b32_e32 v42, 16, v113
	v_and_b32_e32 v43, 0xffff0000, v113
	v_mov_b32_e32 v11, v138
	v_add_f32_e32 v36, s0, v46
	v_max_f32_e64 v37, s1, s1
	v_max_f32_e32 v47, v36, v37
	v_sub_f32_e32 v37, s1, v47
	v_sub_f32_e32 v36, v36, v47
	v_mul_f32_e32 v37, 0x3fb8aa3b, v37
	v_mul_f32_e32 v36, 0x3fb8aa3b, v36
	v_exp_f32_e32 v38, v37
	v_exp_f32_e32 v36, v36
	v_mov_b32_e32 v46, v47
	v_pk_mul_f32 v[50:51], v[38:39], v[50:51] op_sel_hi:[0,1]
	v_pk_mul_f32 v[42:43], v[38:39], v[42:43] op_sel_hi:[0,1]
	v_pk_fma_f32 v[32:33], v[32:33], v[36:37], v[50:51] op_sel_hi:[1,0,1]
	v_pk_fma_f32 v[40:41], v[40:41], v[36:37], v[42:43] op_sel_hi:[1,0,1]
	v_cvt_pk_bf16_f32 v30, v32, v33
	v_cvt_pk_bf16_f32 v31, v40, v41
	global_store_dwordx2 v1, v[30:31], s[8:9]
	v_mov_b32_e32 v37, v38
	v_pk_mul_f32 v[10:11], v[10:11], v[36:37]
	s_add_u32 s8, s8, 0x8000
	s_addc_u32 s9, s9, 0
	v_add_f32_e32 v10, v10, v11
	s_mov_b64 exec, s[16:17]
	global_store_dword v2, v10, s[12:13]
	s_mov_b64 exec, s[18:19]
	global_store_dword v0, v47, s[14:15] offset:616
	s_mov_b64 exec, s[20:21]
	s_add_u32 s12, s12, 0x200
	s_addc_u32 s13, s13, 0
	global_load_dwordx2 v[112:113], v1, s[6:7]
	global_load_dword v138, v2, s[10:11]
	s_add_u32 s6, s6, 0x8000
	s_addc_u32 s7, s7, 0
	s_add_u32 s10, s10, 0x200
	s_addc_u32 s11, s11, 0
	v_readlane_b32 s0, v4, 39
	v_readlane_b32 s1, v5, 39
	s_waitcnt vmcnt(45)
	v_lshlrev_b32_e32 v50, 16, v114
	v_and_b32_e32 v51, 0xffff0000, v114
	v_lshlrev_b32_e32 v42, 16, v115
	v_and_b32_e32 v43, 0xffff0000, v115
	v_mov_b32_e32 v11, v139
	v_add_f32_e32 v36, s0, v46
	v_max_f32_e64 v37, s1, s1
	v_max_f32_e32 v47, v36, v37
	v_sub_f32_e32 v37, s1, v47
	v_sub_f32_e32 v36, v36, v47
	v_mul_f32_e32 v37, 0x3fb8aa3b, v37
	v_mul_f32_e32 v36, 0x3fb8aa3b, v36
	v_exp_f32_e32 v38, v37
	v_exp_f32_e32 v36, v36
	v_mov_b32_e32 v46, v47
	v_pk_mul_f32 v[50:51], v[38:39], v[50:51] op_sel_hi:[0,1]
	v_pk_mul_f32 v[42:43], v[38:39], v[42:43] op_sel_hi:[0,1]
	v_pk_fma_f32 v[32:33], v[32:33], v[36:37], v[50:51] op_sel_hi:[1,0,1]
	v_pk_fma_f32 v[40:41], v[40:41], v[36:37], v[42:43] op_sel_hi:[1,0,1]
	v_cvt_pk_bf16_f32 v30, v32, v33
	v_cvt_pk_bf16_f32 v31, v40, v41
	global_store_dwordx2 v1, v[30:31], s[8:9]
	v_mov_b32_e32 v37, v38
	v_pk_mul_f32 v[10:11], v[10:11], v[36:37]
	s_add_u32 s8, s8, 0x8000
	s_addc_u32 s9, s9, 0
	v_add_f32_e32 v10, v10, v11
	s_mov_b64 exec, s[16:17]
	global_store_dword v2, v10, s[12:13]
	s_mov_b64 exec, s[18:19]
	global_store_dword v0, v47, s[14:15] offset:632
	s_mov_b64 exec, s[20:21]
	s_add_u32 s12, s12, 0x200
	s_addc_u32 s13, s13, 0
	global_load_dwordx2 v[114:115], v1, s[6:7]
	global_load_dword v139, v2, s[10:11]
	s_add_u32 s6, s6, 0x8000
	s_addc_u32 s7, s7, 0
	s_add_u32 s10, s10, 0x200
	s_addc_u32 s11, s11, 0
	v_readlane_b32 s0, v4, 40
	v_readlane_b32 s1, v5, 40
	s_waitcnt vmcnt(45)
	v_lshlrev_b32_e32 v50, 16, v116
	v_and_b32_e32 v51, 0xffff0000, v116
	v_lshlrev_b32_e32 v42, 16, v117
	v_and_b32_e32 v43, 0xffff0000, v117
	v_mov_b32_e32 v11, v140
	v_add_f32_e32 v36, s0, v46
	v_max_f32_e64 v37, s1, s1
	v_max_f32_e32 v47, v36, v37
	v_sub_f32_e32 v37, s1, v47
	v_sub_f32_e32 v36, v36, v47
	v_mul_f32_e32 v37, 0x3fb8aa3b, v37
	v_mul_f32_e32 v36, 0x3fb8aa3b, v36
	v_exp_f32_e32 v38, v37
	v_exp_f32_e32 v36, v36
	v_mov_b32_e32 v46, v47
	v_pk_mul_f32 v[50:51], v[38:39], v[50:51] op_sel_hi:[0,1]
	v_pk_mul_f32 v[42:43], v[38:39], v[42:43] op_sel_hi:[0,1]
	v_pk_fma_f32 v[32:33], v[32:33], v[36:37], v[50:51] op_sel_hi:[1,0,1]
	v_pk_fma_f32 v[40:41], v[40:41], v[36:37], v[42:43] op_sel_hi:[1,0,1]
	v_cvt_pk_bf16_f32 v30, v32, v33
	v_cvt_pk_bf16_f32 v31, v40, v41
	global_store_dwordx2 v1, v[30:31], s[8:9]
	v_mov_b32_e32 v37, v38
	v_pk_mul_f32 v[10:11], v[10:11], v[36:37]
	s_add_u32 s8, s8, 0x8000
	s_addc_u32 s9, s9, 0
	v_add_f32_e32 v10, v10, v11
	s_mov_b64 exec, s[16:17]
	global_store_dword v2, v10, s[12:13]
	s_mov_b64 exec, s[18:19]
	global_store_dword v0, v47, s[14:15] offset:648
	s_mov_b64 exec, s[20:21]
	s_add_u32 s12, s12, 0x200
	s_addc_u32 s13, s13, 0
	global_load_dwordx2 v[116:117], v1, s[6:7]
	global_load_dword v140, v2, s[10:11]
	s_add_u32 s6, s6, 0x8000
	s_addc_u32 s7, s7, 0
	s_add_u32 s10, s10, 0x200
	s_addc_u32 s11, s11, 0
	v_readlane_b32 s0, v4, 41
	v_readlane_b32 s1, v5, 41
	s_waitcnt vmcnt(45)
; DI unsigned pack2(float a, float b) { const f32x2 v = {a, b}; return __builtin_bit_cast(unsigned, __builtin_convertvector(v, bf16v2)); }
; DI float bflo(unsigned w) { return __uint_as_float(w << 16); }
; DI float bfhi(unsigned w) { return __uint_as_float(w & 0xffff0000u); }
; DI void phase_mlstm_scan(const Params& p) {
;     ...
;       for (int j = 0; j < 8; ++j) { raw[j] = *(const uint2*)(kv + (size_t)(cb + j) * 16384); kr[j] = don ? ks[(cb + j) * 128] : 0.f; }
; #pragma unroll
;       for (int j = 0; j < 8; ++j) {
;         const float B = csc[(cb + j) * 4], A = csc[(cb + j) * 4 + 1];
;         const float mnew = fmaxf(B + m, A);
;         const float wp = __expf(B + m - mnew), wl = __expf(A - mnew);
;         m = mnew;
;         c0 = wp * c0 + wl * bflo(raw[j].x); c1 = wp * c1 + wl * bfhi(raw[j].x); c2 = wp * c2 + wl * bflo(raw[j].y); c3 = wp * c3 + wl * bfhi(raw[j].y);
;         uint2 o; o.x = pack2(c0, c1); o.y = pack2(c2, c3);
;         *(uint2*)(kv + (size_t)(cb + j) * 16384) = o;
;         if (don) { n = wp * n + wl * kr[j]; ks[(cb + j) * 128] = n; }
;         if (part == 0 && tid == 0) csc[(cb + j) * 4 + 2] = mnew;
	v_lshlrev_b32_e32 v50, 16, v118
	v_and_b32_e32 v51, 0xffff0000, v118
	v_lshlrev_b32_e32 v42, 16, v119
	v_and_b32_e32 v43, 0xffff0000, v119
	v_mov_b32_e32 v11, v141
	v_add_f32_e32 v36, s0, v46
	v_max_f32_e64 v37, s1, s1
	v_max_f32_e32 v47, v36, v37
	v_sub_f32_e32 v37, s1, v47
	v_sub_f32_e32 v36, v36, v47
	v_mul_f32_e32 v37, 0x3fb8aa3b, v37
	v_mul_f32_e32 v36, 0x3fb8aa3b, v36
	v_exp_f32_e32 v38, v37
	v_exp_f32_e32 v36, v36
	v_mov_b32_e32 v46, v47
	v_pk_mul_f32 v[50:51], v[38:39], v[50:51] op_sel_hi:[0,1]
	v_pk_mul_f32 v[42:43], v[38:39], v[42:43] op_sel_hi:[0,1]
	v_pk_fma_f32 v[32:33], v[32:33], v[36:37], v[50:51] op_sel_hi:[1,0,1]
	v_pk_fma_f32 v[40:41], v[40:41], v[36:37], v[42:43] op_sel_hi:[1,0,1]
	v_cvt_pk_bf16_f32 v30, v32, v33
	v_cvt_pk_bf16_f32 v31, v40, v41
	global_store_dwordx2 v1, v[30:31], s[8:9]
	v_mov_b32_e32 v37, v38
	v_pk_mul_f32 v[10:11], v[10:11], v[36:37]
	s_add_u32 s8, s8, 0x8000
	s_addc_u32 s9, s9, 0
	v_add_f32_e32 v10, v10, v11
	s_mov_b64 exec, s[16:17]
	global_store_dword v2, v10, s[12:13]
	s_mov_b64 exec, s[18:19]
	global_store_dword v0, v47, s[14:15] offset:664
	s_mov_b64 exec, s[20:21]
	s_add_u32 s12, s12, 0x200
	s_addc_u32 s13, s13, 0
	global_load_dwordx2 v[118:119], v1, s[6:7]
	global_load_dword v141, v2, s[10:11]
	s_add_u32 s6, s6, 0x8000
	s_addc_u32 s7, s7, 0
	s_add_u32 s10, s10, 0x200
	s_addc_u32 s11, s11, 0
	v_readlane_b32 s0, v4, 42
	v_readlane_b32 s1, v5, 42
	s_waitcnt vmcnt(45)
	v_lshlrev_b32_e32 v50, 16, v120
	v_and_b32_e32 v51, 0xffff0000, v120
	v_lshlrev_b32_e32 v42, 16, v121
	v_and_b32_e32 v43, 0xffff0000, v121
	v_mov_b32_e32 v11, v142
	v_add_f32_e32 v36, s0, v46
	v_max_f32_e64 v37, s1, s1
	v_max_f32_e32 v47, v36, v37
	v_sub_f32_e32 v37, s1, v47
	v_sub_f32_e32 v36, v36, v47
	v_mul_f32_e32 v37, 0x3fb8aa3b, v37
	v_mul_f32_e32 v36, 0x3fb8aa3b, v36
	v_exp_f32_e32 v38, v37
	v_exp_f32_e32 v36, v36
	v_mov_b32_e32 v46, v47
	v_pk_mul_f32 v[50:51], v[38:39], v[50:51] op_sel_hi:[0,1]
	v_pk_mul_f32 v[42:43], v[38:39], v[42:43] op_sel_hi:[0,1]
	v_pk_fma_f32 v[32:33], v[32:33], v[36:37], v[50:51] op_sel_hi:[1,0,1]
	v_pk_fma_f32 v[40:41], v[40:41], v[36:37], v[42:43] op_sel_hi:[1,0,1]
	v_cvt_pk_bf16_f32 v30, v32, v33
	v_cvt_pk_bf16_f32 v31, v40, v41
	global_store_dwordx2 v1, v[30:31], s[8:9]
	v_mov_b32_e32 v37, v38
	v_pk_mul_f32 v[10:11], v[10:11], v[36:37]
	s_add_u32 s8, s8, 0x8000
	s_addc_u32 s9, s9, 0
	v_add_f32_e32 v10, v10, v11
	s_mov_b64 exec, s[16:17]
	global_store_dword v2, v10, s[12:13]
	s_mov_b64 exec, s[18:19]
	global_store_dword v0, v47, s[14:15] offset:680
	s_mov_b64 exec, s[20:21]
	s_add_u32 s12, s12, 0x200
	s_addc_u32 s13, s13, 0
	global_load_dwordx2 v[120:121], v1, s[6:7]
	global_load_dword v142, v2, s[10:11]
	s_add_u32 s6, s6, 0x8000
	s_addc_u32 s7, s7, 0
	s_add_u32 s10, s10, 0x200
	s_addc_u32 s11, s11, 0
	v_readlane_b32 s0, v4, 43
	v_readlane_b32 s1, v5, 43
	s_waitcnt vmcnt(45)
	v_lshlrev_b32_e32 v50, 16, v122
	v_and_b32_e32 v51, 0xffff0000, v122
	v_lshlrev_b32_e32 v42, 16, v123
	v_and_b32_e32 v43, 0xffff0000, v123
	v_mov_b32_e32 v11, v143
	v_add_f32_e32 v36, s0, v46
	v_max_f32_e64 v37, s1, s1
	v_max_f32_e32 v47, v36, v37
	v_sub_f32_e32 v37, s1, v47
	v_sub_f32_e32 v36, v36, v47
	v_mul_f32_e32 v37, 0x3fb8aa3b, v37
	v_mul_f32_e32 v36, 0x3fb8aa3b, v36
	v_exp_f32_e32 v38, v37
	v_exp_f32_e32 v36, v36
	v_mov_b32_e32 v46, v47
	v_pk_mul_f32 v[50:51], v[38:39], v[50:51] op_sel_hi:[0,1]
	v_pk_mul_f32 v[42:43], v[38:39], v[42:43] op_sel_hi:[0,1]
	v_pk_fma_f32 v[32:33], v[32:33], v[36:37], v[50:51] op_sel_hi:[1,0,1]
	v_pk_fma_f32 v[40:41], v[40:41], v[36:37], v[42:43] op_sel_hi:[1,0,1]
	v_cvt_pk_bf16_f32 v30, v32, v33
	v_cvt_pk_bf16_f32 v31, v40, v41
	global_store_dwordx2 v1, v[30:31], s[8:9]
	v_mov_b32_e32 v37, v38
	v_pk_mul_f32 v[10:11], v[10:11], v[36:37]
	s_add_u32 s8, s8, 0x8000
	s_addc_u32 s9, s9, 0
	v_add_f32_e32 v10, v10, v11
	s_mov_b64 exec, s[16:17]
	global_store_dword v2, v10, s[12:13]
	s_mov_b64 exec, s[18:19]
	global_store_dword v0, v47, s[14:15] offset:696
	s_mov_b64 exec, s[20:21]
	s_add_u32 s12, s12, 0x200
	s_addc_u32 s13, s13, 0
	global_load_dwordx2 v[122:123], v1, s[6:7]
	global_load_dword v143, v2, s[10:11]
	s_add_u32 s6, s6, 0x8000
	s_addc_u32 s7, s7, 0
	s_add_u32 s10, s10, 0x200
	s_addc_u32 s11, s11, 0
	v_readlane_b32 s0, v4, 44
	v_readlane_b32 s1, v5, 44
	s_waitcnt vmcnt(45)
	v_lshlrev_b32_e32 v50, 16, v124
	v_and_b32_e32 v51, 0xffff0000, v124
	v_lshlrev_b32_e32 v42, 16, v125
	v_and_b32_e32 v43, 0xffff0000, v125
	v_mov_b32_e32 v11, v144
	v_add_f32_e32 v36, s0, v46
	v_max_f32_e64 v37, s1, s1
	v_max_f32_e32 v47, v36, v37
	v_sub_f32_e32 v37, s1, v47
	v_sub_f32_e32 v36, v36, v47
	v_mul_f32_e32 v37, 0x3fb8aa3b, v37
	v_mul_f32_e32 v36, 0x3fb8aa3b, v36
	v_exp_f32_e32 v38, v37
	v_exp_f32_e32 v36, v36
	v_mov_b32_e32 v46, v47
	v_pk_mul_f32 v[50:51], v[38:39], v[50:51] op_sel_hi:[0,1]
	v_pk_mul_f32 v[42:43], v[38:39], v[42:43] op_sel_hi:[0,1]
	v_pk_fma_f32 v[32:33], v[32:33], v[36:37], v[50:51] op_sel_hi:[1,0,1]
	v_pk_fma_f32 v[40:41], v[40:41], v[36:37], v[42:43] op_sel_hi:[1,0,1]
	v_cvt_pk_bf16_f32 v30, v32, v33
	v_cvt_pk_bf16_f32 v31, v40, v41
	global_store_dwordx2 v1, v[30:31], s[8:9]
	v_mov_b32_e32 v37, v38
	v_pk_mul_f32 v[10:11], v[10:11], v[36:37]
	s_add_u32 s8, s8, 0x8000
	s_addc_u32 s9, s9, 0
	v_add_f32_e32 v10, v10, v11
	s_mov_b64 exec, s[16:17]
	global_store_dword v2, v10, s[12:13]
	s_mov_b64 exec, s[18:19]
	global_store_dword v0, v47, s[14:15] offset:712
	s_mov_b64 exec, s[20:21]
	s_add_u32 s12, s12, 0x200
	s_addc_u32 s13, s13, 0
	global_load_dwordx2 v[124:125], v1, s[6:7]
	global_load_dword v144, v2, s[10:11]
	s_add_u32 s6, s6, 0x8000
	s_addc_u32 s7, s7, 0
	s_add_u32 s10, s10, 0x200
	s_addc_u32 s11, s11, 0
	v_readlane_b32 s0, v4, 45
	v_readlane_b32 s1, v5, 45
	s_waitcnt vmcnt(45)
; DI unsigned pack2(float a, float b) { const f32x2 v = {a, b}; return __builtin_bit_cast(unsigned, __builtin_convertvector(v, bf16v2)); }
; DI float bflo(unsigned w) { return __uint_as_float(w << 16); }
; DI float bfhi(unsigned w) { return __uint_as_float(w & 0xffff0000u); }
; DI void phase_mlstm_scan(const Params& p) {
;     ...
;       for (int j = 0; j < 8; ++j) { raw[j] = *(const uint2*)(kv + (size_t)(cb + j) * 16384); kr[j] = don ? ks[(cb + j) * 128] : 0.f; }
; #pragma unroll
;       for (int j = 0; j < 8; ++j) {
;         const float B = csc[(cb + j) * 4], A = csc[(cb + j) * 4 + 1];
;         const float mnew = fmaxf(B + m, A);
;         const float wp = __expf(B + m - mnew), wl = __expf(A - mnew);
;         m = mnew;
;         c0 = wp * c0 + wl * bflo(raw[j].x); c1 = wp * c1 + wl * bfhi(raw[j].x); c2 = wp * c2 + wl * bflo(raw[j].y); c3 = wp * c3 + wl * bfhi(raw[j].y);
;         uint2 o; o.x = pack2(c0, c1); o.y = pack2(c2, c3);
;         *(uint2*)(kv + (size_t)(cb + j) * 16384) = o;
;         if (don) { n = wp * n + wl * kr[j]; ks[(cb + j) * 128] = n; }
;         if (part == 0 && tid == 0) csc[(cb + j) * 4 + 2] = mnew;
	v_lshlrev_b32_e32 v50, 16, v126
	v_and_b32_e32 v51, 0xffff0000, v126
	v_lshlrev_b32_e32 v42, 16, v127
	v_and_b32_e32 v43, 0xffff0000, v127
	v_mov_b32_e32 v11, v145
	v_add_f32_e32 v36, s0, v46
	v_max_f32_e64 v37, s1, s1
	v_max_f32_e32 v47, v36, v37
	v_sub_f32_e32 v37, s1, v47
	v_sub_f32_e32 v36, v36, v47
	v_mul_f32_e32 v37, 0x3fb8aa3b, v37
	v_mul_f32_e32 v36, 0x3fb8aa3b, v36
	v_exp_f32_e32 v38, v37
	v_exp_f32_e32 v36, v36
	v_mov_b32_e32 v46, v47
	v_pk_mul_f32 v[50:51], v[38:39], v[50:51] op_sel_hi:[0,1]
	v_pk_mul_f32 v[42:43], v[38:39], v[42:43] op_sel_hi:[0,1]
	v_pk_fma_f32 v[32:33], v[32:33], v[36:37], v[50:51] op_sel_hi:[1,0,1]
	v_pk_fma_f32 v[40:41], v[40:41], v[36:37], v[42:43] op_sel_hi:[1,0,1]
	v_cvt_pk_bf16_f32 v30, v32, v33
	v_cvt_pk_bf16_f32 v31, v40, v41
	global_store_dwordx2 v1, v[30:31], s[8:9]
	v_mov_b32_e32 v37, v38
	v_pk_mul_f32 v[10:11], v[10:11], v[36:37]
	s_add_u32 s8, s8, 0x8000
	s_addc_u32 s9, s9, 0
	v_add_f32_e32 v10, v10, v11
	s_mov_b64 exec, s[16:17]
	global_store_dword v2, v10, s[12:13]
	s_mov_b64 exec, s[18:19]
	global_store_dword v0, v47, s[14:15] offset:728
	s_mov_b64 exec, s[20:21]
	s_add_u32 s12, s12, 0x200
	s_addc_u32 s13, s13, 0
	global_load_dwordx2 v[126:127], v1, s[6:7]
	global_load_dword v145, v2, s[10:11]
	s_add_u32 s6, s6, 0x8000
	s_addc_u32 s7, s7, 0
	s_add_u32 s10, s10, 0x200
	s_addc_u32 s11, s11, 0
	v_readlane_b32 s0, v4, 46
	v_readlane_b32 s1, v5, 46
	s_waitcnt vmcnt(45)
	v_lshlrev_b32_e32 v50, 16, v128
	v_and_b32_e32 v51, 0xffff0000, v128
	v_lshlrev_b32_e32 v42, 16, v129
	v_and_b32_e32 v43, 0xffff0000, v129
	v_mov_b32_e32 v11, v146
	v_add_f32_e32 v36, s0, v46
	v_max_f32_e64 v37, s1, s1
	v_max_f32_e32 v47, v36, v37
	v_sub_f32_e32 v37, s1, v47
	v_sub_f32_e32 v36, v36, v47
	v_mul_f32_e32 v37, 0x3fb8aa3b, v37
	v_mul_f32_e32 v36, 0x3fb8aa3b, v36
	v_exp_f32_e32 v38, v37
	v_exp_f32_e32 v36, v36
	v_mov_b32_e32 v46, v47
	v_pk_mul_f32 v[50:51], v[38:39], v[50:51] op_sel_hi:[0,1]
	v_pk_mul_f32 v[42:43], v[38:39], v[42:43] op_sel_hi:[0,1]
	v_pk_fma_f32 v[32:33], v[32:33], v[36:37], v[50:51] op_sel_hi:[1,0,1]
	v_pk_fma_f32 v[40:41], v[40:41], v[36:37], v[42:43] op_sel_hi:[1,0,1]
	v_cvt_pk_bf16_f32 v30, v32, v33
	v_cvt_pk_bf16_f32 v31, v40, v41
	global_store_dwordx2 v1, v[30:31], s[8:9]
	v_mov_b32_e32 v37, v38
	v_pk_mul_f32 v[10:11], v[10:11], v[36:37]
	s_add_u32 s8, s8, 0x8000
	s_addc_u32 s9, s9, 0
	v_add_f32_e32 v10, v10, v11
	s_mov_b64 exec, s[16:17]
	global_store_dword v2, v10, s[12:13]
	s_mov_b64 exec, s[18:19]
	global_store_dword v0, v47, s[14:15] offset:744
	s_mov_b64 exec, s[20:21]
	s_add_u32 s12, s12, 0x200
	s_addc_u32 s13, s13, 0
	global_load_dwordx2 v[128:129], v1, s[6:7]
	global_load_dword v146, v2, s[10:11]
	s_add_u32 s6, s6, 0x8000
	s_addc_u32 s7, s7, 0
	s_add_u32 s10, s10, 0x200
	s_addc_u32 s11, s11, 0
	v_readlane_b32 s0, v4, 47
	v_readlane_b32 s1, v5, 47
	s_waitcnt vmcnt(45)
	v_lshlrev_b32_e32 v50, 16, v130
	v_and_b32_e32 v51, 0xffff0000, v130
	v_lshlrev_b32_e32 v42, 16, v131
	v_and_b32_e32 v43, 0xffff0000, v131
	v_mov_b32_e32 v11, v147
	v_add_f32_e32 v36, s0, v46
	v_max_f32_e64 v37, s1, s1
	v_max_f32_e32 v47, v36, v37
	v_sub_f32_e32 v37, s1, v47
	v_sub_f32_e32 v36, v36, v47
	v_mul_f32_e32 v37, 0x3fb8aa3b, v37
	v_mul_f32_e32 v36, 0x3fb8aa3b, v36
	v_exp_f32_e32 v38, v37
	v_exp_f32_e32 v36, v36
	v_mov_b32_e32 v46, v47
	v_pk_mul_f32 v[50:51], v[38:39], v[50:51] op_sel_hi:[0,1]
	v_pk_mul_f32 v[42:43], v[38:39], v[42:43] op_sel_hi:[0,1]
	v_pk_fma_f32 v[32:33], v[32:33], v[36:37], v[50:51] op_sel_hi:[1,0,1]
	v_pk_fma_f32 v[40:41], v[40:41], v[36:37], v[42:43] op_sel_hi:[1,0,1]
	v_cvt_pk_bf16_f32 v30, v32, v33
	v_cvt_pk_bf16_f32 v31, v40, v41
	global_store_dwordx2 v1, v[30:31], s[8:9]
	v_mov_b32_e32 v37, v38
	v_pk_mul_f32 v[10:11], v[10:11], v[36:37]
	s_add_u32 s8, s8, 0x8000
	s_addc_u32 s9, s9, 0
	v_add_f32_e32 v10, v10, v11
	s_mov_b64 exec, s[16:17]
	global_store_dword v2, v10, s[12:13]
	s_mov_b64 exec, s[18:19]
	global_store_dword v0, v47, s[14:15] offset:760
	s_mov_b64 exec, s[20:21]
	s_add_u32 s12, s12, 0x200
	s_addc_u32 s13, s13, 0
	global_load_dwordx2 v[130:131], v1, s[6:7]
	global_load_dword v147, v2, s[10:11]
	s_add_u32 s6, s6, 0x8000
	s_addc_u32 s7, s7, 0
	s_add_u32 s10, s10, 0x200
	s_addc_u32 s11, s11, 0
	v_readlane_b32 s0, v4, 48
	v_readlane_b32 s1, v5, 48
	s_waitcnt vmcnt(45)
	v_lshlrev_b32_e32 v50, 16, v100
	v_and_b32_e32 v51, 0xffff0000, v100
	v_lshlrev_b32_e32 v42, 16, v101
	v_and_b32_e32 v43, 0xffff0000, v101
	v_mov_b32_e32 v11, v132
	v_add_f32_e32 v36, s0, v46
	v_max_f32_e64 v37, s1, s1
	v_max_f32_e32 v47, v36, v37
	v_sub_f32_e32 v37, s1, v47
	v_sub_f32_e32 v36, v36, v47
	v_mul_f32_e32 v37, 0x3fb8aa3b, v37
	v_mul_f32_e32 v36, 0x3fb8aa3b, v36
	v_exp_f32_e32 v38, v37
	v_exp_f32_e32 v36, v36
	v_mov_b32_e32 v46, v47
	v_pk_mul_f32 v[50:51], v[38:39], v[50:51] op_sel_hi:[0,1]
	v_pk_mul_f32 v[42:43], v[38:39], v[42:43] op_sel_hi:[0,1]
	v_pk_fma_f32 v[32:33], v[32:33], v[36:37], v[50:51] op_sel_hi:[1,0,1]
	v_pk_fma_f32 v[40:41], v[40:41], v[36:37], v[42:43] op_sel_hi:[1,0,1]
	v_cvt_pk_bf16_f32 v30, v32, v33
	v_cvt_pk_bf16_f32 v31, v40, v41
	global_store_dwordx2 v1, v[30:31], s[8:9]
	v_mov_b32_e32 v37, v38
	v_pk_mul_f32 v[10:11], v[10:11], v[36:37]
	s_add_u32 s8, s8, 0x8000
	s_addc_u32 s9, s9, 0
	v_add_f32_e32 v10, v10, v11
	s_mov_b64 exec, s[16:17]
	global_store_dword v2, v10, s[12:13]
	s_mov_b64 exec, s[18:19]
	global_store_dword v0, v47, s[14:15] offset:776
	s_mov_b64 exec, s[20:21]
	s_add_u32 s12, s12, 0x200
	s_addc_u32 s13, s13, 0
	global_load_dwordx2 v[100:101], v1, s[6:7]
	global_load_dword v132, v2, s[10:11]
	s_add_u32 s6, s6, 0x8000
	s_addc_u32 s7, s7, 0
	s_add_u32 s10, s10, 0x200
	s_addc_u32 s11, s11, 0
	v_readlane_b32 s0, v4, 49
	v_readlane_b32 s1, v5, 49
	s_waitcnt vmcnt(45)
; DI unsigned pack2(float a, float b) { const f32x2 v = {a, b}; return __builtin_bit_cast(unsigned, __builtin_convertvector(v, bf16v2)); }
; DI float bflo(unsigned w) { return __uint_as_float(w << 16); }
; DI float bfhi(unsigned w) { return __uint_as_float(w & 0xffff0000u); }
; DI void phase_mlstm_scan(const Params& p) {
;     ...
;       for (int j = 0; j < 8; ++j) { raw[j] = *(const uint2*)(kv + (size_t)(cb + j) * 16384); kr[j] = don ? ks[(cb + j) * 128] : 0.f; }
; #pragma unroll
;       for (int j = 0; j < 8; ++j) {
;         const float B = csc[(cb + j) * 4], A = csc[(cb + j) * 4 + 1];
;         const float mnew = fmaxf(B + m, A);
;         const float wp = __expf(B + m - mnew), wl = __expf(A - mnew);
;         m = mnew;
;         c0 = wp * c0 + wl * bflo(raw[j].x); c1 = wp * c1 + wl * bfhi(raw[j].x); c2 = wp * c2 + wl * bflo(raw[j].y); c3 = wp * c3 + wl * bfhi(raw[j].y);
;         uint2 o; o.x = pack2(c0, c1); o.y = pack2(c2, c3);
;         *(uint2*)(kv + (size_t)(cb + j) * 16384) = o;
;         if (don) { n = wp * n + wl * kr[j]; ks[(cb + j) * 128] = n; }
;         if (part == 0 && tid == 0) csc[(cb + j) * 4 + 2] = mnew;
	v_lshlrev_b32_e32 v50, 16, v102
	v_and_b32_e32 v51, 0xffff0000, v102
	v_lshlrev_b32_e32 v42, 16, v103
	v_and_b32_e32 v43, 0xffff0000, v103
	v_mov_b32_e32 v11, v133
	v_add_f32_e32 v36, s0, v46
	v_max_f32_e64 v37, s1, s1
	v_max_f32_e32 v47, v36, v37
	v_sub_f32_e32 v37, s1, v47
	v_sub_f32_e32 v36, v36, v47
	v_mul_f32_e32 v37, 0x3fb8aa3b, v37
	v_mul_f32_e32 v36, 0x3fb8aa3b, v36
	v_exp_f32_e32 v38, v37
	v_exp_f32_e32 v36, v36
	v_mov_b32_e32 v46, v47
	v_pk_mul_f32 v[50:51], v[38:39], v[50:51] op_sel_hi:[0,1]
	v_pk_mul_f32 v[42:43], v[38:39], v[42:43] op_sel_hi:[0,1]
	v_pk_fma_f32 v[32:33], v[32:33], v[36:37], v[50:51] op_sel_hi:[1,0,1]
	v_pk_fma_f32 v[40:41], v[40:41], v[36:37], v[42:43] op_sel_hi:[1,0,1]
	v_cvt_pk_bf16_f32 v30, v32, v33
	v_cvt_pk_bf16_f32 v31, v40, v41
	global_store_dwordx2 v1, v[30:31], s[8:9]
	v_mov_b32_e32 v37, v38
	v_pk_mul_f32 v[10:11], v[10:11], v[36:37]
	s_add_u32 s8, s8, 0x8000
	s_addc_u32 s9, s9, 0
	v_add_f32_e32 v10, v10, v11
	s_mov_b64 exec, s[16:17]
	global_store_dword v2, v10, s[12:13]
	s_mov_b64 exec, s[18:19]
	global_store_dword v0, v47, s[14:15] offset:792
	s_mov_b64 exec, s[20:21]
	s_add_u32 s12, s12, 0x200
	s_addc_u32 s13, s13, 0
	global_load_dwordx2 v[102:103], v1, s[6:7]
	global_load_dword v133, v2, s[10:11]
	s_add_u32 s6, s6, 0x8000
	s_addc_u32 s7, s7, 0
	s_add_u32 s10, s10, 0x200
	s_addc_u32 s11, s11, 0
	v_readlane_b32 s0, v4, 50
	v_readlane_b32 s1, v5, 50
	s_waitcnt vmcnt(45)
	v_lshlrev_b32_e32 v50, 16, v104
	v_and_b32_e32 v51, 0xffff0000, v104
	v_lshlrev_b32_e32 v42, 16, v105
	v_and_b32_e32 v43, 0xffff0000, v105
	v_mov_b32_e32 v11, v134
	v_add_f32_e32 v36, s0, v46
	v_max_f32_e64 v37, s1, s1
	v_max_f32_e32 v47, v36, v37
	v_sub_f32_e32 v37, s1, v47
	v_sub_f32_e32 v36, v36, v47
	v_mul_f32_e32 v37, 0x3fb8aa3b, v37
	v_mul_f32_e32 v36, 0x3fb8aa3b, v36
	v_exp_f32_e32 v38, v37
	v_exp_f32_e32 v36, v36
	v_mov_b32_e32 v46, v47
	v_pk_mul_f32 v[50:51], v[38:39], v[50:51] op_sel_hi:[0,1]
	v_pk_mul_f32 v[42:43], v[38:39], v[42:43] op_sel_hi:[0,1]
	v_pk_fma_f32 v[32:33], v[32:33], v[36:37], v[50:51] op_sel_hi:[1,0,1]
	v_pk_fma_f32 v[40:41], v[40:41], v[36:37], v[42:43] op_sel_hi:[1,0,1]
	v_cvt_pk_bf16_f32 v30, v32, v33
	v_cvt_pk_bf16_f32 v31, v40, v41
	global_store_dwordx2 v1, v[30:31], s[8:9]
	v_mov_b32_e32 v37, v38
	v_pk_mul_f32 v[10:11], v[10:11], v[36:37]
	s_add_u32 s8, s8, 0x8000
	s_addc_u32 s9, s9, 0
	v_add_f32_e32 v10, v10, v11
	s_mov_b64 exec, s[16:17]
	global_store_dword v2, v10, s[12:13]
	s_mov_b64 exec, s[18:19]
	global_store_dword v0, v47, s[14:15] offset:808
	s_mov_b64 exec, s[20:21]
	s_add_u32 s12, s12, 0x200
	s_addc_u32 s13, s13, 0
	global_load_dwordx2 v[104:105], v1, s[6:7]
	global_load_dword v134, v2, s[10:11]
	s_add_u32 s6, s6, 0x8000
	s_addc_u32 s7, s7, 0
	s_add_u32 s10, s10, 0x200
	s_addc_u32 s11, s11, 0
	v_readlane_b32 s0, v4, 51
	v_readlane_b32 s1, v5, 51
	s_waitcnt vmcnt(45)
	v_lshlrev_b32_e32 v50, 16, v106
	v_and_b32_e32 v51, 0xffff0000, v106
	v_lshlrev_b32_e32 v42, 16, v107
	v_and_b32_e32 v43, 0xffff0000, v107
	v_mov_b32_e32 v11, v135
	v_add_f32_e32 v36, s0, v46
	v_max_f32_e64 v37, s1, s1
	v_max_f32_e32 v47, v36, v37
	v_sub_f32_e32 v37, s1, v47
	v_sub_f32_e32 v36, v36, v47
	v_mul_f32_e32 v37, 0x3fb8aa3b, v37
	v_mul_f32_e32 v36, 0x3fb8aa3b, v36
	v_exp_f32_e32 v38, v37
	v_exp_f32_e32 v36, v36
	v_mov_b32_e32 v46, v47
	v_pk_mul_f32 v[50:51], v[38:39], v[50:51] op_sel_hi:[0,1]
	v_pk_mul_f32 v[42:43], v[38:39], v[42:43] op_sel_hi:[0,1]
	v_pk_fma_f32 v[32:33], v[32:33], v[36:37], v[50:51] op_sel_hi:[1,0,1]
	v_pk_fma_f32 v[40:41], v[40:41], v[36:37], v[42:43] op_sel_hi:[1,0,1]
	v_cvt_pk_bf16_f32 v30, v32, v33
	v_cvt_pk_bf16_f32 v31, v40, v41
	global_store_dwordx2 v1, v[30:31], s[8:9]
	v_mov_b32_e32 v37, v38
	v_pk_mul_f32 v[10:11], v[10:11], v[36:37]
	s_add_u32 s8, s8, 0x8000
	s_addc_u32 s9, s9, 0
	v_add_f32_e32 v10, v10, v11
	s_mov_b64 exec, s[16:17]
	global_store_dword v2, v10, s[12:13]
	s_mov_b64 exec, s[18:19]
	global_store_dword v0, v47, s[14:15] offset:824
	s_mov_b64 exec, s[20:21]
	s_add_u32 s12, s12, 0x200
	s_addc_u32 s13, s13, 0
	global_load_dwordx2 v[106:107], v1, s[6:7]
	global_load_dword v135, v2, s[10:11]
	s_add_u32 s6, s6, 0x8000
	s_addc_u32 s7, s7, 0
	s_add_u32 s10, s10, 0x200
	s_addc_u32 s11, s11, 0
	v_readlane_b32 s0, v4, 52
	v_readlane_b32 s1, v5, 52
	s_waitcnt vmcnt(45)
	v_lshlrev_b32_e32 v50, 16, v108
	v_and_b32_e32 v51, 0xffff0000, v108
	v_lshlrev_b32_e32 v42, 16, v109
	v_and_b32_e32 v43, 0xffff0000, v109
	v_mov_b32_e32 v11, v136
	v_add_f32_e32 v36, s0, v46
	v_max_f32_e64 v37, s1, s1
	v_max_f32_e32 v47, v36, v37
	v_sub_f32_e32 v37, s1, v47
	v_sub_f32_e32 v36, v36, v47
	v_mul_f32_e32 v37, 0x3fb8aa3b, v37
	v_mul_f32_e32 v36, 0x3fb8aa3b, v36
	v_exp_f32_e32 v38, v37
	v_exp_f32_e32 v36, v36
	v_mov_b32_e32 v46, v47
	v_pk_mul_f32 v[50:51], v[38:39], v[50:51] op_sel_hi:[0,1]
	v_pk_mul_f32 v[42:43], v[38:39], v[42:43] op_sel_hi:[0,1]
	v_pk_fma_f32 v[32:33], v[32:33], v[36:37], v[50:51] op_sel_hi:[1,0,1]
	v_pk_fma_f32 v[40:41], v[40:41], v[36:37], v[42:43] op_sel_hi:[1,0,1]
	v_cvt_pk_bf16_f32 v30, v32, v33
	v_cvt_pk_bf16_f32 v31, v40, v41
	global_store_dwordx2 v1, v[30:31], s[8:9]
	v_mov_b32_e32 v37, v38
	v_pk_mul_f32 v[10:11], v[10:11], v[36:37]
	s_add_u32 s8, s8, 0x8000
	s_addc_u32 s9, s9, 0
	v_add_f32_e32 v10, v10, v11
	s_mov_b64 exec, s[16:17]
	global_store_dword v2, v10, s[12:13]
	s_mov_b64 exec, s[18:19]
	global_store_dword v0, v47, s[14:15] offset:840
	s_mov_b64 exec, s[20:21]
	s_add_u32 s12, s12, 0x200
	s_addc_u32 s13, s13, 0
	global_load_dwordx2 v[108:109], v1, s[6:7]
	global_load_dword v136, v2, s[10:11]
	s_add_u32 s6, s6, 0x8000
	s_addc_u32 s7, s7, 0
	s_add_u32 s10, s10, 0x200
	s_addc_u32 s11, s11, 0
	v_readlane_b32 s0, v4, 53
	v_readlane_b32 s1, v5, 53
	s_waitcnt vmcnt(45)
; DI unsigned pack2(float a, float b) { const f32x2 v = {a, b}; return __builtin_bit_cast(unsigned, __builtin_convertvector(v, bf16v2)); }
; DI float bflo(unsigned w) { return __uint_as_float(w << 16); }
; DI float bfhi(unsigned w) { return __uint_as_float(w & 0xffff0000u); }
; DI void phase_mlstm_scan(const Params& p) {
;     ...
;       for (int j = 0; j < 8; ++j) { raw[j] = *(const uint2*)(kv + (size_t)(cb + j) * 16384); kr[j] = don ? ks[(cb + j) * 128] : 0.f; }
; #pragma unroll
;       for (int j = 0; j < 8; ++j) {
;         const float B = csc[(cb + j) * 4], A = csc[(cb + j) * 4 + 1];
;         const float mnew = fmaxf(B + m, A);
;         const float wp = __expf(B + m - mnew), wl = __expf(A - mnew);
;         m = mnew;
;         c0 = wp * c0 + wl * bflo(raw[j].x); c1 = wp * c1 + wl * bfhi(raw[j].x); c2 = wp * c2 + wl * bflo(raw[j].y); c3 = wp * c3 + wl * bfhi(raw[j].y);
;         uint2 o; o.x = pack2(c0, c1); o.y = pack2(c2, c3);
;         *(uint2*)(kv + (size_t)(cb + j) * 16384) = o;
;         if (don) { n = wp * n + wl * kr[j]; ks[(cb + j) * 128] = n; }
;         if (part == 0 && tid == 0) csc[(cb + j) * 4 + 2] = mnew;
	v_lshlrev_b32_e32 v50, 16, v110
	v_and_b32_e32 v51, 0xffff0000, v110
	v_lshlrev_b32_e32 v42, 16, v111
	v_and_b32_e32 v43, 0xffff0000, v111
	v_mov_b32_e32 v11, v137
	v_add_f32_e32 v36, s0, v46
	v_max_f32_e64 v37, s1, s1
	v_max_f32_e32 v47, v36, v37
	v_sub_f32_e32 v37, s1, v47
	v_sub_f32_e32 v36, v36, v47
	v_mul_f32_e32 v37, 0x3fb8aa3b, v37
	v_mul_f32_e32 v36, 0x3fb8aa3b, v36
	v_exp_f32_e32 v38, v37
	v_exp_f32_e32 v36, v36
	v_mov_b32_e32 v46, v47
	v_pk_mul_f32 v[50:51], v[38:39], v[50:51] op_sel_hi:[0,1]
	v_pk_mul_f32 v[42:43], v[38:39], v[42:43] op_sel_hi:[0,1]
	v_pk_fma_f32 v[32:33], v[32:33], v[36:37], v[50:51] op_sel_hi:[1,0,1]
	v_pk_fma_f32 v[40:41], v[40:41], v[36:37], v[42:43] op_sel_hi:[1,0,1]
	v_cvt_pk_bf16_f32 v30, v32, v33
	v_cvt_pk_bf16_f32 v31, v40, v41
	global_store_dwordx2 v1, v[30:31], s[8:9]
	v_mov_b32_e32 v37, v38
	v_pk_mul_f32 v[10:11], v[10:11], v[36:37]
	s_add_u32 s8, s8, 0x8000
	s_addc_u32 s9, s9, 0
	v_add_f32_e32 v10, v10, v11
	s_mov_b64 exec, s[16:17]
	global_store_dword v2, v10, s[12:13]
	s_mov_b64 exec, s[18:19]
	global_store_dword v0, v47, s[14:15] offset:856
	s_mov_b64 exec, s[20:21]
	s_add_u32 s12, s12, 0x200
	s_addc_u32 s13, s13, 0
	global_load_dwordx2 v[110:111], v1, s[6:7]
	global_load_dword v137, v2, s[10:11]
	s_add_u32 s6, s6, 0x8000
	s_addc_u32 s7, s7, 0
	s_add_u32 s10, s10, 0x200
	s_addc_u32 s11, s11, 0
	v_readlane_b32 s0, v4, 54
	v_readlane_b32 s1, v5, 54
	s_waitcnt vmcnt(45)
	v_lshlrev_b32_e32 v50, 16, v112
	v_and_b32_e32 v51, 0xffff0000, v112
	v_lshlrev_b32_e32 v42, 16, v113
	v_and_b32_e32 v43, 0xffff0000, v113
	v_mov_b32_e32 v11, v138
	v_add_f32_e32 v36, s0, v46
	v_max_f32_e64 v37, s1, s1
	v_max_f32_e32 v47, v36, v37
	v_sub_f32_e32 v37, s1, v47
	v_sub_f32_e32 v36, v36, v47
	v_mul_f32_e32 v37, 0x3fb8aa3b, v37
	v_mul_f32_e32 v36, 0x3fb8aa3b, v36
	v_exp_f32_e32 v38, v37
	v_exp_f32_e32 v36, v36
	v_mov_b32_e32 v46, v47
	v_pk_mul_f32 v[50:51], v[38:39], v[50:51] op_sel_hi:[0,1]
	v_pk_mul_f32 v[42:43], v[38:39], v[42:43] op_sel_hi:[0,1]
	v_pk_fma_f32 v[32:33], v[32:33], v[36:37], v[50:51] op_sel_hi:[1,0,1]
	v_pk_fma_f32 v[40:41], v[40:41], v[36:37], v[42:43] op_sel_hi:[1,0,1]
	v_cvt_pk_bf16_f32 v30, v32, v33
	v_cvt_pk_bf16_f32 v31, v40, v41
	global_store_dwordx2 v1, v[30:31], s[8:9]
	v_mov_b32_e32 v37, v38
	v_pk_mul_f32 v[10:11], v[10:11], v[36:37]
	s_add_u32 s8, s8, 0x8000
	s_addc_u32 s9, s9, 0
	v_add_f32_e32 v10, v10, v11
	s_mov_b64 exec, s[16:17]
	global_store_dword v2, v10, s[12:13]
	s_mov_b64 exec, s[18:19]
	global_store_dword v0, v47, s[14:15] offset:872
	s_mov_b64 exec, s[20:21]
	s_add_u32 s12, s12, 0x200
	s_addc_u32 s13, s13, 0
	global_load_dwordx2 v[112:113], v1, s[6:7]
	global_load_dword v138, v2, s[10:11]
	s_add_u32 s6, s6, 0x8000
	s_addc_u32 s7, s7, 0
	s_add_u32 s10, s10, 0x200
	s_addc_u32 s11, s11, 0
	v_readlane_b32 s0, v4, 55
	v_readlane_b32 s1, v5, 55
	s_waitcnt vmcnt(45)
	v_lshlrev_b32_e32 v50, 16, v114
	v_and_b32_e32 v51, 0xffff0000, v114
	v_lshlrev_b32_e32 v42, 16, v115
	v_and_b32_e32 v43, 0xffff0000, v115
	v_mov_b32_e32 v11, v139
	v_add_f32_e32 v36, s0, v46
	v_max_f32_e64 v37, s1, s1
	v_max_f32_e32 v47, v36, v37
	v_sub_f32_e32 v37, s1, v47
	v_sub_f32_e32 v36, v36, v47
	v_mul_f32_e32 v37, 0x3fb8aa3b, v37
	v_mul_f32_e32 v36, 0x3fb8aa3b, v36
	v_exp_f32_e32 v38, v37
	v_exp_f32_e32 v36, v36
	v_mov_b32_e32 v46, v47
	v_pk_mul_f32 v[50:51], v[38:39], v[50:51] op_sel_hi:[0,1]
	v_pk_mul_f32 v[42:43], v[38:39], v[42:43] op_sel_hi:[0,1]
	v_pk_fma_f32 v[32:33], v[32:33], v[36:37], v[50:51] op_sel_hi:[1,0,1]
	v_pk_fma_f32 v[40:41], v[40:41], v[36:37], v[42:43] op_sel_hi:[1,0,1]
	v_cvt_pk_bf16_f32 v30, v32, v33
	v_cvt_pk_bf16_f32 v31, v40, v41
	global_store_dwordx2 v1, v[30:31], s[8:9]
	v_mov_b32_e32 v37, v38
	v_pk_mul_f32 v[10:11], v[10:11], v[36:37]
	s_add_u32 s8, s8, 0x8000
	s_addc_u32 s9, s9, 0
	v_add_f32_e32 v10, v10, v11
	s_mov_b64 exec, s[16:17]
	global_store_dword v2, v10, s[12:13]
	s_mov_b64 exec, s[18:19]
	global_store_dword v0, v47, s[14:15] offset:888
	s_mov_b64 exec, s[20:21]
	s_add_u32 s12, s12, 0x200
	s_addc_u32 s13, s13, 0
	global_load_dwordx2 v[114:115], v1, s[6:7]
	global_load_dword v139, v2, s[10:11]
	s_add_u32 s6, s6, 0x8000
	s_addc_u32 s7, s7, 0
	s_add_u32 s10, s10, 0x200
	s_addc_u32 s11, s11, 0
	v_readlane_b32 s0, v4, 56
	v_readlane_b32 s1, v5, 56
	s_waitcnt vmcnt(45)
	v_lshlrev_b32_e32 v50, 16, v116
	v_and_b32_e32 v51, 0xffff0000, v116
	v_lshlrev_b32_e32 v42, 16, v117
	v_and_b32_e32 v43, 0xffff0000, v117
	v_mov_b32_e32 v11, v140
	v_add_f32_e32 v36, s0, v46
	v_max_f32_e64 v37, s1, s1
	v_max_f32_e32 v47, v36, v37
	v_sub_f32_e32 v37, s1, v47
	v_sub_f32_e32 v36, v36, v47
	v_mul_f32_e32 v37, 0x3fb8aa3b, v37
	v_mul_f32_e32 v36, 0x3fb8aa3b, v36
	v_exp_f32_e32 v38, v37
	v_exp_f32_e32 v36, v36
	v_mov_b32_e32 v46, v47
	v_pk_mul_f32 v[50:51], v[38:39], v[50:51] op_sel_hi:[0,1]
	v_pk_mul_f32 v[42:43], v[38:39], v[42:43] op_sel_hi:[0,1]
	v_pk_fma_f32 v[32:33], v[32:33], v[36:37], v[50:51] op_sel_hi:[1,0,1]
	v_pk_fma_f32 v[40:41], v[40:41], v[36:37], v[42:43] op_sel_hi:[1,0,1]
	v_cvt_pk_bf16_f32 v30, v32, v33
	v_cvt_pk_bf16_f32 v31, v40, v41
	global_store_dwordx2 v1, v[30:31], s[8:9]
	v_mov_b32_e32 v37, v38
	v_pk_mul_f32 v[10:11], v[10:11], v[36:37]
	s_add_u32 s8, s8, 0x8000
	s_addc_u32 s9, s9, 0
	v_add_f32_e32 v10, v10, v11
	s_mov_b64 exec, s[16:17]
	global_store_dword v2, v10, s[12:13]
	s_mov_b64 exec, s[18:19]
	global_store_dword v0, v47, s[14:15] offset:904
	s_mov_b64 exec, s[20:21]
	s_add_u32 s12, s12, 0x200
	s_addc_u32 s13, s13, 0
	global_load_dwordx2 v[116:117], v1, s[6:7]
	global_load_dword v140, v2, s[10:11]
	s_add_u32 s6, s6, 0x8000
	s_addc_u32 s7, s7, 0
	s_add_u32 s10, s10, 0x200
	s_addc_u32 s11, s11, 0
	v_readlane_b32 s0, v4, 57
	v_readlane_b32 s1, v5, 57
	s_waitcnt vmcnt(45)
; DI unsigned pack2(float a, float b) { const f32x2 v = {a, b}; return __builtin_bit_cast(unsigned, __builtin_convertvector(v, bf16v2)); }
; DI float bflo(unsigned w) { return __uint_as_float(w << 16); }
; DI float bfhi(unsigned w) { return __uint_as_float(w & 0xffff0000u); }
; DI void phase_mlstm_scan(const Params& p) {
;     ...
;       for (int j = 0; j < 8; ++j) { raw[j] = *(const uint2*)(kv + (size_t)(cb + j) * 16384); kr[j] = don ? ks[(cb + j) * 128] : 0.f; }
; #pragma unroll
;       for (int j = 0; j < 8; ++j) {
;         const float B = csc[(cb + j) * 4], A = csc[(cb + j) * 4 + 1];
;         const float mnew = fmaxf(B + m, A);
;         const float wp = __expf(B + m - mnew), wl = __expf(A - mnew);
;         m = mnew;
;         c0 = wp * c0 + wl * bflo(raw[j].x); c1 = wp * c1 + wl * bfhi(raw[j].x); c2 = wp * c2 + wl * bflo(raw[j].y); c3 = wp * c3 + wl * bfhi(raw[j].y);
;         uint2 o; o.x = pack2(c0, c1); o.y = pack2(c2, c3);
;         *(uint2*)(kv + (size_t)(cb + j) * 16384) = o;
;         if (don) { n = wp * n + wl * kr[j]; ks[(cb + j) * 128] = n; }
;         if (part == 0 && tid == 0) csc[(cb + j) * 4 + 2] = mnew;
	v_lshlrev_b32_e32 v50, 16, v118
	v_and_b32_e32 v51, 0xffff0000, v118
	v_lshlrev_b32_e32 v42, 16, v119
	v_and_b32_e32 v43, 0xffff0000, v119
	v_mov_b32_e32 v11, v141
	v_add_f32_e32 v36, s0, v46
	v_max_f32_e64 v37, s1, s1
	v_max_f32_e32 v47, v36, v37
	v_sub_f32_e32 v37, s1, v47
	v_sub_f32_e32 v36, v36, v47
	v_mul_f32_e32 v37, 0x3fb8aa3b, v37
	v_mul_f32_e32 v36, 0x3fb8aa3b, v36
	v_exp_f32_e32 v38, v37
	v_exp_f32_e32 v36, v36
	v_mov_b32_e32 v46, v47
	v_pk_mul_f32 v[50:51], v[38:39], v[50:51] op_sel_hi:[0,1]
	v_pk_mul_f32 v[42:43], v[38:39], v[42:43] op_sel_hi:[0,1]
	v_pk_fma_f32 v[32:33], v[32:33], v[36:37], v[50:51] op_sel_hi:[1,0,1]
	v_pk_fma_f32 v[40:41], v[40:41], v[36:37], v[42:43] op_sel_hi:[1,0,1]
	v_cvt_pk_bf16_f32 v30, v32, v33
	v_cvt_pk_bf16_f32 v31, v40, v41
	global_store_dwordx2 v1, v[30:31], s[8:9]
	v_mov_b32_e32 v37, v38
	v_pk_mul_f32 v[10:11], v[10:11], v[36:37]
	s_add_u32 s8, s8, 0x8000
	s_addc_u32 s9, s9, 0
	v_add_f32_e32 v10, v10, v11
	s_mov_b64 exec, s[16:17]
	global_store_dword v2, v10, s[12:13]
	s_mov_b64 exec, s[18:19]
	global_store_dword v0, v47, s[14:15] offset:920
	s_mov_b64 exec, s[20:21]
	s_add_u32 s12, s12, 0x200
	s_addc_u32 s13, s13, 0
	global_load_dwordx2 v[118:119], v1, s[6:7]
	global_load_dword v141, v2, s[10:11]
	s_add_u32 s6, s6, 0x8000
	s_addc_u32 s7, s7, 0
	s_add_u32 s10, s10, 0x200
	s_addc_u32 s11, s11, 0
	v_readlane_b32 s0, v4, 58
	v_readlane_b32 s1, v5, 58
	s_waitcnt vmcnt(45)
	v_lshlrev_b32_e32 v50, 16, v120
	v_and_b32_e32 v51, 0xffff0000, v120
	v_lshlrev_b32_e32 v42, 16, v121
	v_and_b32_e32 v43, 0xffff0000, v121
	v_mov_b32_e32 v11, v142
	v_add_f32_e32 v36, s0, v46
	v_max_f32_e64 v37, s1, s1
	v_max_f32_e32 v47, v36, v37
	v_sub_f32_e32 v37, s1, v47
	v_sub_f32_e32 v36, v36, v47
	v_mul_f32_e32 v37, 0x3fb8aa3b, v37
	v_mul_f32_e32 v36, 0x3fb8aa3b, v36
	v_exp_f32_e32 v38, v37
	v_exp_f32_e32 v36, v36
	v_mov_b32_e32 v46, v47
	v_pk_mul_f32 v[50:51], v[38:39], v[50:51] op_sel_hi:[0,1]
	v_pk_mul_f32 v[42:43], v[38:39], v[42:43] op_sel_hi:[0,1]
	v_pk_fma_f32 v[32:33], v[32:33], v[36:37], v[50:51] op_sel_hi:[1,0,1]
	v_pk_fma_f32 v[40:41], v[40:41], v[36:37], v[42:43] op_sel_hi:[1,0,1]
	v_cvt_pk_bf16_f32 v30, v32, v33
	v_cvt_pk_bf16_f32 v31, v40, v41
	global_store_dwordx2 v1, v[30:31], s[8:9]
	v_mov_b32_e32 v37, v38
	v_pk_mul_f32 v[10:11], v[10:11], v[36:37]
	s_add_u32 s8, s8, 0x8000
	s_addc_u32 s9, s9, 0
	v_add_f32_e32 v10, v10, v11
	s_mov_b64 exec, s[16:17]
	global_store_dword v2, v10, s[12:13]
	s_mov_b64 exec, s[18:19]
	global_store_dword v0, v47, s[14:15] offset:936
	s_mov_b64 exec, s[20:21]
	s_add_u32 s12, s12, 0x200
	s_addc_u32 s13, s13, 0
	global_load_dwordx2 v[120:121], v1, s[6:7]
	global_load_dword v142, v2, s[10:11]
	s_add_u32 s6, s6, 0x8000
	s_addc_u32 s7, s7, 0
	s_add_u32 s10, s10, 0x200
	s_addc_u32 s11, s11, 0
	v_readlane_b32 s0, v4, 59
	v_readlane_b32 s1, v5, 59
	s_waitcnt vmcnt(45)
	v_lshlrev_b32_e32 v50, 16, v122
	v_and_b32_e32 v51, 0xffff0000, v122
	v_lshlrev_b32_e32 v42, 16, v123
	v_and_b32_e32 v43, 0xffff0000, v123
	v_mov_b32_e32 v11, v143
	v_add_f32_e32 v36, s0, v46
	v_max_f32_e64 v37, s1, s1
	v_max_f32_e32 v47, v36, v37
	v_sub_f32_e32 v37, s1, v47
	v_sub_f32_e32 v36, v36, v47
	v_mul_f32_e32 v37, 0x3fb8aa3b, v37
	v_mul_f32_e32 v36, 0x3fb8aa3b, v36
	v_exp_f32_e32 v38, v37
	v_exp_f32_e32 v36, v36
	v_mov_b32_e32 v46, v47
	v_pk_mul_f32 v[50:51], v[38:39], v[50:51] op_sel_hi:[0,1]
	v_pk_mul_f32 v[42:43], v[38:39], v[42:43] op_sel_hi:[0,1]
	v_pk_fma_f32 v[32:33], v[32:33], v[36:37], v[50:51] op_sel_hi:[1,0,1]
	v_pk_fma_f32 v[40:41], v[40:41], v[36:37], v[42:43] op_sel_hi:[1,0,1]
	v_cvt_pk_bf16_f32 v30, v32, v33
	v_cvt_pk_bf16_f32 v31, v40, v41
	global_store_dwordx2 v1, v[30:31], s[8:9]
	v_mov_b32_e32 v37, v38
	v_pk_mul_f32 v[10:11], v[10:11], v[36:37]
	s_add_u32 s8, s8, 0x8000
	s_addc_u32 s9, s9, 0
	v_add_f32_e32 v10, v10, v11
	s_mov_b64 exec, s[16:17]
	global_store_dword v2, v10, s[12:13]
	s_mov_b64 exec, s[18:19]
	global_store_dword v0, v47, s[14:15] offset:952
	s_mov_b64 exec, s[20:21]
	s_add_u32 s12, s12, 0x200
	s_addc_u32 s13, s13, 0
	global_load_dwordx2 v[122:123], v1, s[6:7]
	global_load_dword v143, v2, s[10:11]
	s_add_u32 s6, s6, 0x8000
	s_addc_u32 s7, s7, 0
	s_add_u32 s10, s10, 0x200
	s_addc_u32 s11, s11, 0
	v_readlane_b32 s0, v4, 60
	v_readlane_b32 s1, v5, 60
	s_waitcnt vmcnt(45)
	v_lshlrev_b32_e32 v50, 16, v124
	v_and_b32_e32 v51, 0xffff0000, v124
	v_lshlrev_b32_e32 v42, 16, v125
	v_and_b32_e32 v43, 0xffff0000, v125
	v_mov_b32_e32 v11, v144
	v_add_f32_e32 v36, s0, v46
	v_max_f32_e64 v37, s1, s1
	v_max_f32_e32 v47, v36, v37
	v_sub_f32_e32 v37, s1, v47
	v_sub_f32_e32 v36, v36, v47
	v_mul_f32_e32 v37, 0x3fb8aa3b, v37
	v_mul_f32_e32 v36, 0x3fb8aa3b, v36
	v_exp_f32_e32 v38, v37
	v_exp_f32_e32 v36, v36
	v_mov_b32_e32 v46, v47
	v_pk_mul_f32 v[50:51], v[38:39], v[50:51] op_sel_hi:[0,1]
	v_pk_mul_f32 v[42:43], v[38:39], v[42:43] op_sel_hi:[0,1]
	v_pk_fma_f32 v[32:33], v[32:33], v[36:37], v[50:51] op_sel_hi:[1,0,1]
	v_pk_fma_f32 v[40:41], v[40:41], v[36:37], v[42:43] op_sel_hi:[1,0,1]
	v_cvt_pk_bf16_f32 v30, v32, v33
	v_cvt_pk_bf16_f32 v31, v40, v41
	global_store_dwordx2 v1, v[30:31], s[8:9]
	v_mov_b32_e32 v37, v38
	v_pk_mul_f32 v[10:11], v[10:11], v[36:37]
	s_add_u32 s8, s8, 0x8000
	s_addc_u32 s9, s9, 0
	v_add_f32_e32 v10, v10, v11
	s_mov_b64 exec, s[16:17]
	global_store_dword v2, v10, s[12:13]
	s_mov_b64 exec, s[18:19]
	global_store_dword v0, v47, s[14:15] offset:968
	s_mov_b64 exec, s[20:21]
	s_add_u32 s12, s12, 0x200
	s_addc_u32 s13, s13, 0
	global_load_dwordx2 v[124:125], v1, s[6:7]
	global_load_dword v144, v2, s[10:11]
	s_add_u32 s6, s6, 0x8000
	s_addc_u32 s7, s7, 0
	s_add_u32 s10, s10, 0x200
	s_addc_u32 s11, s11, 0
	v_readlane_b32 s0, v4, 61
	v_readlane_b32 s1, v5, 61
	s_waitcnt vmcnt(45)
; DI unsigned pack2(float a, float b) { const f32x2 v = {a, b}; return __builtin_bit_cast(unsigned, __builtin_convertvector(v, bf16v2)); }
; DI float bflo(unsigned w) { return __uint_as_float(w << 16); }
; DI float bfhi(unsigned w) { return __uint_as_float(w & 0xffff0000u); }
; DI void phase_mlstm_scan(const Params& p) {
;     ...
;     for (int cb = 0; cb < 128; cb += 8) {
;       uint2 raw[8]; float kr[8];
; #pragma unroll
;       for (int j = 0; j < 8; ++j) { raw[j] = *(const uint2*)(kv + (size_t)(cb + j) * 16384); kr[j] = don ? ks[(cb + j) * 128] : 0.f; }
; #pragma unroll
;       for (int j = 0; j < 8; ++j) {
;         const float B = csc[(cb + j) * 4], A = csc[(cb + j) * 4 + 1];
;         const float mnew = fmaxf(B + m, A);
;         const float wp = __expf(B + m - mnew), wl = __expf(A - mnew);
;         m = mnew;
;         c0 = wp * c0 + wl * bflo(raw[j].x); c1 = wp * c1 + wl * bfhi(raw[j].x); c2 = wp * c2 + wl * bflo(raw[j].y); c3 = wp * c3 + wl * bfhi(raw[j].y);
;         uint2 o; o.x = pack2(c0, c1); o.y = pack2(c2, c3);
;         *(uint2*)(kv + (size_t)(cb + j) * 16384) = o;
;         if (don) { n = wp * n + wl * kr[j]; ks[(cb + j) * 128] = n; }
;         if (part == 0 && tid == 0) csc[(cb + j) * 4 + 2] = mnew;
;       }
;     }
	v_lshlrev_b32_e32 v50, 16, v126
	v_and_b32_e32 v51, 0xffff0000, v126
	v_lshlrev_b32_e32 v42, 16, v127
	v_and_b32_e32 v43, 0xffff0000, v127
	v_mov_b32_e32 v11, v145
	v_add_f32_e32 v36, s0, v46
	v_max_f32_e64 v37, s1, s1
	v_max_f32_e32 v47, v36, v37
	v_sub_f32_e32 v37, s1, v47
	v_sub_f32_e32 v36, v36, v47
	v_mul_f32_e32 v37, 0x3fb8aa3b, v37
	v_mul_f32_e32 v36, 0x3fb8aa3b, v36
	v_exp_f32_e32 v38, v37
	v_exp_f32_e32 v36, v36
	v_mov_b32_e32 v46, v47
	v_pk_mul_f32 v[50:51], v[38:39], v[50:51] op_sel_hi:[0,1]
	v_pk_mul_f32 v[42:43], v[38:39], v[42:43] op_sel_hi:[0,1]
	v_pk_fma_f32 v[32:33], v[32:33], v[36:37], v[50:51] op_sel_hi:[1,0,1]
	v_pk_fma_f32 v[40:41], v[40:41], v[36:37], v[42:43] op_sel_hi:[1,0,1]
	v_cvt_pk_bf16_f32 v30, v32, v33
	v_cvt_pk_bf16_f32 v31, v40, v41
	global_store_dwordx2 v1, v[30:31], s[8:9]
	v_mov_b32_e32 v37, v38
	v_pk_mul_f32 v[10:11], v[10:11], v[36:37]
	s_add_u32 s8, s8, 0x8000
	s_addc_u32 s9, s9, 0
	v_add_f32_e32 v10, v10, v11
	s_mov_b64 exec, s[16:17]
	global_store_dword v2, v10, s[12:13]
	s_mov_b64 exec, s[18:19]
	global_store_dword v0, v47, s[14:15] offset:984
	s_mov_b64 exec, s[20:21]
	s_add_u32 s12, s12, 0x200
	s_addc_u32 s13, s13, 0
	global_load_dwordx2 v[126:127], v1, s[6:7]
	global_load_dword v145, v2, s[10:11]
	s_add_u32 s6, s6, 0x8000
	s_addc_u32 s7, s7, 0
	s_add_u32 s10, s10, 0x200
	s_addc_u32 s11, s11, 0
	v_readlane_b32 s0, v4, 62
	v_readlane_b32 s1, v5, 62
	s_waitcnt vmcnt(45)
	v_lshlrev_b32_e32 v50, 16, v128
	v_and_b32_e32 v51, 0xffff0000, v128
	v_lshlrev_b32_e32 v42, 16, v129
	v_and_b32_e32 v43, 0xffff0000, v129
	v_mov_b32_e32 v11, v146
	v_add_f32_e32 v36, s0, v46
	v_max_f32_e64 v37, s1, s1
	v_max_f32_e32 v47, v36, v37
	v_sub_f32_e32 v37, s1, v47
	v_sub_f32_e32 v36, v36, v47
	v_mul_f32_e32 v37, 0x3fb8aa3b, v37
	v_mul_f32_e32 v36, 0x3fb8aa3b, v36
	v_exp_f32_e32 v38, v37
	v_exp_f32_e32 v36, v36
	v_mov_b32_e32 v46, v47
	v_pk_mul_f32 v[50:51], v[38:39], v[50:51] op_sel_hi:[0,1]
	v_pk_mul_f32 v[42:43], v[38:39], v[42:43] op_sel_hi:[0,1]
	v_pk_fma_f32 v[32:33], v[32:33], v[36:37], v[50:51] op_sel_hi:[1,0,1]
	v_pk_fma_f32 v[40:41], v[40:41], v[36:37], v[42:43] op_sel_hi:[1,0,1]
	v_cvt_pk_bf16_f32 v30, v32, v33
	v_cvt_pk_bf16_f32 v31, v40, v41
	global_store_dwordx2 v1, v[30:31], s[8:9]
	v_mov_b32_e32 v37, v38
	v_pk_mul_f32 v[10:11], v[10:11], v[36:37]
	s_add_u32 s8, s8, 0x8000
	s_addc_u32 s9, s9, 0
	v_add_f32_e32 v10, v10, v11
	s_mov_b64 exec, s[16:17]
	global_store_dword v2, v10, s[12:13]
	s_mov_b64 exec, s[18:19]
	global_store_dword v0, v47, s[14:15] offset:1000
	s_mov_b64 exec, s[20:21]
	s_add_u32 s12, s12, 0x200
	s_addc_u32 s13, s13, 0
	global_load_dwordx2 v[128:129], v1, s[6:7]
	global_load_dword v146, v2, s[10:11]
	s_add_u32 s6, s6, 0x8000
	s_addc_u32 s7, s7, 0
	s_add_u32 s10, s10, 0x200
	s_addc_u32 s11, s11, 0
	v_readlane_b32 s0, v4, 63
	v_readlane_b32 s1, v5, 63
	s_waitcnt vmcnt(45)
	v_lshlrev_b32_e32 v50, 16, v130
	v_and_b32_e32 v51, 0xffff0000, v130
	v_lshlrev_b32_e32 v42, 16, v131
	v_and_b32_e32 v43, 0xffff0000, v131
	v_mov_b32_e32 v11, v147
	v_add_f32_e32 v36, s0, v46
	v_max_f32_e64 v37, s1, s1
	v_max_f32_e32 v47, v36, v37
	v_sub_f32_e32 v37, s1, v47
	v_sub_f32_e32 v36, v36, v47
	v_mul_f32_e32 v37, 0x3fb8aa3b, v37
	v_mul_f32_e32 v36, 0x3fb8aa3b, v36
	v_exp_f32_e32 v38, v37
	v_exp_f32_e32 v36, v36
	v_mov_b32_e32 v46, v47
	v_pk_mul_f32 v[50:51], v[38:39], v[50:51] op_sel_hi:[0,1]
	v_pk_mul_f32 v[42:43], v[38:39], v[42:43] op_sel_hi:[0,1]
	v_pk_fma_f32 v[32:33], v[32:33], v[36:37], v[50:51] op_sel_hi:[1,0,1]
	v_pk_fma_f32 v[40:41], v[40:41], v[36:37], v[42:43] op_sel_hi:[1,0,1]
	v_cvt_pk_bf16_f32 v30, v32, v33
	v_cvt_pk_bf16_f32 v31, v40, v41
	global_store_dwordx2 v1, v[30:31], s[8:9]
	v_mov_b32_e32 v37, v38
	v_pk_mul_f32 v[10:11], v[10:11], v[36:37]
	s_add_u32 s8, s8, 0x8000
	s_addc_u32 s9, s9, 0
	v_add_f32_e32 v10, v10, v11
	s_mov_b64 exec, s[16:17]
	global_store_dword v2, v10, s[12:13]
	s_mov_b64 exec, s[18:19]
	global_store_dword v0, v47, s[14:15] offset:1016
	s_mov_b64 exec, s[20:21]
	s_add_u32 s12, s12, 0x200
	s_addc_u32 s13, s13, 0
	global_load_dwordx2 v[130:131], v1, s[6:7]
	global_load_dword v147, v2, s[10:11]
	s_add_u32 s6, s6, 0x8000
	s_addc_u32 s7, s7, 0
	s_add_u32 s10, s10, 0x200
	s_addc_u32 s11, s11, 0
	v_readlane_b32 s0, v6, 0
	v_readlane_b32 s1, v7, 0
	s_waitcnt vmcnt(45)
	v_lshlrev_b32_e32 v50, 16, v100
	v_and_b32_e32 v51, 0xffff0000, v100
	v_lshlrev_b32_e32 v42, 16, v101
	v_and_b32_e32 v43, 0xffff0000, v101
	v_mov_b32_e32 v11, v132
	v_add_f32_e32 v36, s0, v46
	v_max_f32_e64 v37, s1, s1
	v_max_f32_e32 v47, v36, v37
	v_sub_f32_e32 v37, s1, v47
	v_sub_f32_e32 v36, v36, v47
	v_mul_f32_e32 v37, 0x3fb8aa3b, v37
	v_mul_f32_e32 v36, 0x3fb8aa3b, v36
	v_exp_f32_e32 v38, v37
	v_exp_f32_e32 v36, v36
	v_mov_b32_e32 v46, v47
	v_pk_mul_f32 v[50:51], v[38:39], v[50:51] op_sel_hi:[0,1]
	v_pk_mul_f32 v[42:43], v[38:39], v[42:43] op_sel_hi:[0,1]
	v_pk_fma_f32 v[32:33], v[32:33], v[36:37], v[50:51] op_sel_hi:[1,0,1]
	v_pk_fma_f32 v[40:41], v[40:41], v[36:37], v[42:43] op_sel_hi:[1,0,1]
	v_cvt_pk_bf16_f32 v30, v32, v33
	v_cvt_pk_bf16_f32 v31, v40, v41
	global_store_dwordx2 v1, v[30:31], s[8:9]
	v_mov_b32_e32 v37, v38
	v_pk_mul_f32 v[10:11], v[10:11], v[36:37]
	s_add_u32 s8, s8, 0x8000
	s_addc_u32 s9, s9, 0
	v_add_f32_e32 v10, v10, v11
	s_mov_b64 exec, s[16:17]
	global_store_dword v2, v10, s[12:13]
	s_mov_b64 exec, s[18:19]
	global_store_dword v0, v47, s[14:15] offset:1032
	s_mov_b64 exec, s[20:21]
	s_add_u32 s12, s12, 0x200
	s_addc_u32 s13, s13, 0
	global_load_dwordx2 v[100:101], v1, s[6:7]
	global_load_dword v132, v2, s[10:11]
	s_add_u32 s6, s6, 0x8000
	s_addc_u32 s7, s7, 0
	s_add_u32 s10, s10, 0x200
	s_addc_u32 s11, s11, 0
	v_readlane_b32 s0, v6, 1
	v_readlane_b32 s1, v7, 1
	s_waitcnt vmcnt(45)
; DI unsigned pack2(float a, float b) { const f32x2 v = {a, b}; return __builtin_bit_cast(unsigned, __builtin_convertvector(v, bf16v2)); }
; DI float bflo(unsigned w) { return __uint_as_float(w << 16); }
; DI float bfhi(unsigned w) { return __uint_as_float(w & 0xffff0000u); }
; DI void phase_mlstm_scan(const Params& p) {
;     ...
;     for (int cb = 0; cb < 128; cb += 8) {
;       uint2 raw[8]; float kr[8];
; #pragma unroll
;       for (int j = 0; j < 8; ++j) { raw[j] = *(const uint2*)(kv + (size_t)(cb + j) * 16384); kr[j] = don ? ks[(cb + j) * 128] : 0.f; }
; #pragma unroll
;       for (int j = 0; j < 8; ++j) {
;         const float B = csc[(cb + j) * 4], A = csc[(cb + j) * 4 + 1];
;         const float mnew = fmaxf(B + m, A);
;         const float wp = __expf(B + m - mnew), wl = __expf(A - mnew);
;         m = mnew;
;         c0 = wp * c0 + wl * bflo(raw[j].x); c1 = wp * c1 + wl * bfhi(raw[j].x); c2 = wp * c2 + wl * bflo(raw[j].y); c3 = wp * c3 + wl * bfhi(raw[j].y);
;         uint2 o; o.x = pack2(c0, c1); o.y = pack2(c2, c3);
;         *(uint2*)(kv + (size_t)(cb + j) * 16384) = o;
;         if (don) { n = wp * n + wl * kr[j]; ks[(cb + j) * 128] = n; }
;         if (part == 0 && tid == 0) csc[(cb + j) * 4 + 2] = mnew;
;       }
;     }
	v_lshlrev_b32_e32 v50, 16, v102
	v_and_b32_e32 v51, 0xffff0000, v102
	v_lshlrev_b32_e32 v42, 16, v103
	v_and_b32_e32 v43, 0xffff0000, v103
	v_mov_b32_e32 v11, v133
	v_add_f32_e32 v36, s0, v46
	v_max_f32_e64 v37, s1, s1
	v_max_f32_e32 v47, v36, v37
	v_sub_f32_e32 v37, s1, v47
	v_sub_f32_e32 v36, v36, v47
	v_mul_f32_e32 v37, 0x3fb8aa3b, v37
	v_mul_f32_e32 v36, 0x3fb8aa3b, v36
	v_exp_f32_e32 v38, v37
	v_exp_f32_e32 v36, v36
	v_mov_b32_e32 v46, v47
	v_pk_mul_f32 v[50:51], v[38:39], v[50:51] op_sel_hi:[0,1]
	v_pk_mul_f32 v[42:43], v[38:39], v[42:43] op_sel_hi:[0,1]
	v_pk_fma_f32 v[32:33], v[32:33], v[36:37], v[50:51] op_sel_hi:[1,0,1]
	v_pk_fma_f32 v[40:41], v[40:41], v[36:37], v[42:43] op_sel_hi:[1,0,1]
	v_cvt_pk_bf16_f32 v30, v32, v33
	v_cvt_pk_bf16_f32 v31, v40, v41
	global_store_dwordx2 v1, v[30:31], s[8:9]
	v_mov_b32_e32 v37, v38
	v_pk_mul_f32 v[10:11], v[10:11], v[36:37]
	s_add_u32 s8, s8, 0x8000
	s_addc_u32 s9, s9, 0
	v_add_f32_e32 v10, v10, v11
	s_mov_b64 exec, s[16:17]
	global_store_dword v2, v10, s[12:13]
	s_mov_b64 exec, s[18:19]
	global_store_dword v0, v47, s[14:15] offset:1048
	s_mov_b64 exec, s[20:21]
	s_add_u32 s12, s12, 0x200
	s_addc_u32 s13, s13, 0
	global_load_dwordx2 v[102:103], v1, s[6:7]
	global_load_dword v133, v2, s[10:11]
	s_add_u32 s6, s6, 0x8000
	s_addc_u32 s7, s7, 0
	s_add_u32 s10, s10, 0x200
	s_addc_u32 s11, s11, 0
	v_readlane_b32 s0, v6, 2
	v_readlane_b32 s1, v7, 2
	s_waitcnt vmcnt(45)
	v_lshlrev_b32_e32 v50, 16, v104
	v_and_b32_e32 v51, 0xffff0000, v104
	v_lshlrev_b32_e32 v42, 16, v105
	v_and_b32_e32 v43, 0xffff0000, v105
	v_mov_b32_e32 v11, v134
	v_add_f32_e32 v36, s0, v46
	v_max_f32_e64 v37, s1, s1
	v_max_f32_e32 v47, v36, v37
	v_sub_f32_e32 v37, s1, v47
	v_sub_f32_e32 v36, v36, v47
	v_mul_f32_e32 v37, 0x3fb8aa3b, v37
	v_mul_f32_e32 v36, 0x3fb8aa3b, v36
	v_exp_f32_e32 v38, v37
	v_exp_f32_e32 v36, v36
	v_mov_b32_e32 v46, v47
	v_pk_mul_f32 v[50:51], v[38:39], v[50:51] op_sel_hi:[0,1]
	v_pk_mul_f32 v[42:43], v[38:39], v[42:43] op_sel_hi:[0,1]
	v_pk_fma_f32 v[32:33], v[32:33], v[36:37], v[50:51] op_sel_hi:[1,0,1]
	v_pk_fma_f32 v[40:41], v[40:41], v[36:37], v[42:43] op_sel_hi:[1,0,1]
	v_cvt_pk_bf16_f32 v30, v32, v33
	v_cvt_pk_bf16_f32 v31, v40, v41
	global_store_dwordx2 v1, v[30:31], s[8:9]
	v_mov_b32_e32 v37, v38
	v_pk_mul_f32 v[10:11], v[10:11], v[36:37]
	s_add_u32 s8, s8, 0x8000
	s_addc_u32 s9, s9, 0
	v_add_f32_e32 v10, v10, v11
	s_mov_b64 exec, s[16:17]
	global_store_dword v2, v10, s[12:13]
	s_mov_b64 exec, s[18:19]
	global_store_dword v0, v47, s[14:15] offset:1064
	s_mov_b64 exec, s[20:21]
	s_add_u32 s12, s12, 0x200
	s_addc_u32 s13, s13, 0
	global_load_dwordx2 v[104:105], v1, s[6:7]
	global_load_dword v134, v2, s[10:11]
	s_add_u32 s6, s6, 0x8000
	s_addc_u32 s7, s7, 0
	s_add_u32 s10, s10, 0x200
	s_addc_u32 s11, s11, 0
	v_readlane_b32 s0, v6, 3
	v_readlane_b32 s1, v7, 3
	s_waitcnt vmcnt(45)
	v_lshlrev_b32_e32 v50, 16, v106
	v_and_b32_e32 v51, 0xffff0000, v106
	v_lshlrev_b32_e32 v42, 16, v107
	v_and_b32_e32 v43, 0xffff0000, v107
	v_mov_b32_e32 v11, v135
	v_add_f32_e32 v36, s0, v46
	v_max_f32_e64 v37, s1, s1
	v_max_f32_e32 v47, v36, v37
	v_sub_f32_e32 v37, s1, v47
	v_sub_f32_e32 v36, v36, v47
	v_mul_f32_e32 v37, 0x3fb8aa3b, v37
	v_mul_f32_e32 v36, 0x3fb8aa3b, v36
	v_exp_f32_e32 v38, v37
	v_exp_f32_e32 v36, v36
	v_mov_b32_e32 v46, v47
	v_pk_mul_f32 v[50:51], v[38:39], v[50:51] op_sel_hi:[0,1]
	v_pk_mul_f32 v[42:43], v[38:39], v[42:43] op_sel_hi:[0,1]
	v_pk_fma_f32 v[32:33], v[32:33], v[36:37], v[50:51] op_sel_hi:[1,0,1]
	v_pk_fma_f32 v[40:41], v[40:41], v[36:37], v[42:43] op_sel_hi:[1,0,1]
	v_cvt_pk_bf16_f32 v30, v32, v33
	v_cvt_pk_bf16_f32 v31, v40, v41
	global_store_dwordx2 v1, v[30:31], s[8:9]
	v_mov_b32_e32 v37, v38
	v_pk_mul_f32 v[10:11], v[10:11], v[36:37]
	s_add_u32 s8, s8, 0x8000
	s_addc_u32 s9, s9, 0
	v_add_f32_e32 v10, v10, v11
	s_mov_b64 exec, s[16:17]
	global_store_dword v2, v10, s[12:13]
	s_mov_b64 exec, s[18:19]
	global_store_dword v0, v47, s[14:15] offset:1080
	s_mov_b64 exec, s[20:21]
	s_add_u32 s12, s12, 0x200
	s_addc_u32 s13, s13, 0
	global_load_dwordx2 v[106:107], v1, s[6:7]
	global_load_dword v135, v2, s[10:11]
	s_add_u32 s6, s6, 0x8000
	s_addc_u32 s7, s7, 0
	s_add_u32 s10, s10, 0x200
	s_addc_u32 s11, s11, 0
	v_readlane_b32 s0, v6, 4
	v_readlane_b32 s1, v7, 4
	s_waitcnt vmcnt(45)
	v_lshlrev_b32_e32 v50, 16, v108
	v_and_b32_e32 v51, 0xffff0000, v108
	v_lshlrev_b32_e32 v42, 16, v109
	v_and_b32_e32 v43, 0xffff0000, v109
	v_mov_b32_e32 v11, v136
	v_add_f32_e32 v36, s0, v46
	v_max_f32_e64 v37, s1, s1
	v_max_f32_e32 v47, v36, v37
	v_sub_f32_e32 v37, s1, v47
	v_sub_f32_e32 v36, v36, v47
	v_mul_f32_e32 v37, 0x3fb8aa3b, v37
	v_mul_f32_e32 v36, 0x3fb8aa3b, v36
	v_exp_f32_e32 v38, v37
	v_exp_f32_e32 v36, v36
	v_mov_b32_e32 v46, v47
	v_pk_mul_f32 v[50:51], v[38:39], v[50:51] op_sel_hi:[0,1]
	v_pk_mul_f32 v[42:43], v[38:39], v[42:43] op_sel_hi:[0,1]
	v_pk_fma_f32 v[32:33], v[32:33], v[36:37], v[50:51] op_sel_hi:[1,0,1]
	v_pk_fma_f32 v[40:41], v[40:41], v[36:37], v[42:43] op_sel_hi:[1,0,1]
	v_cvt_pk_bf16_f32 v30, v32, v33
	v_cvt_pk_bf16_f32 v31, v40, v41
	global_store_dwordx2 v1, v[30:31], s[8:9]
	v_mov_b32_e32 v37, v38
	v_pk_mul_f32 v[10:11], v[10:11], v[36:37]
	s_add_u32 s8, s8, 0x8000
	s_addc_u32 s9, s9, 0
	v_add_f32_e32 v10, v10, v11
	s_mov_b64 exec, s[16:17]
	global_store_dword v2, v10, s[12:13]
	s_mov_b64 exec, s[18:19]
	global_store_dword v0, v47, s[14:15] offset:1096
	s_mov_b64 exec, s[20:21]
	s_add_u32 s12, s12, 0x200
	s_addc_u32 s13, s13, 0
	global_load_dwordx2 v[108:109], v1, s[6:7]
	global_load_dword v136, v2, s[10:11]
	s_add_u32 s6, s6, 0x8000
	s_addc_u32 s7, s7, 0
	s_add_u32 s10, s10, 0x200
	s_addc_u32 s11, s11, 0
	v_readlane_b32 s0, v6, 5
	v_readlane_b32 s1, v7, 5
	s_waitcnt vmcnt(45)
; DI unsigned pack2(float a, float b) { const f32x2 v = {a, b}; return __builtin_bit_cast(unsigned, __builtin_convertvector(v, bf16v2)); }
; DI float bflo(unsigned w) { return __uint_as_float(w << 16); }
; DI float bfhi(unsigned w) { return __uint_as_float(w & 0xffff0000u); }
; DI void phase_mlstm_scan(const Params& p) {
;     ...
;       for (int j = 0; j < 8; ++j) {
;         const float B = csc[(cb + j) * 4], A = csc[(cb + j) * 4 + 1];
;         const float mnew = fmaxf(B + m, A);
;         const float wp = __expf(B + m - mnew), wl = __expf(A - mnew);
;         m = mnew;
;         c0 = wp * c0 + wl * bflo(raw[j].x); c1 = wp * c1 + wl * bfhi(raw[j].x); c2 = wp * c2 + wl * bflo(raw[j].y); c3 = wp * c3 + wl * bfhi(raw[j].y);
;         uint2 o; o.x = pack2(c0, c1); o.y = pack2(c2, c3);
;         *(uint2*)(kv + (size_t)(cb + j) * 16384) = o;
;         if (don) { n = wp * n + wl * kr[j]; ks[(cb + j) * 128] = n; }
;         if (part == 0 && tid == 0) csc[(cb + j) * 4 + 2] = mnew;
	v_lshlrev_b32_e32 v50, 16, v110
	v_and_b32_e32 v51, 0xffff0000, v110
	v_lshlrev_b32_e32 v42, 16, v111
	v_and_b32_e32 v43, 0xffff0000, v111
	v_mov_b32_e32 v11, v137
	v_add_f32_e32 v36, s0, v46
	v_max_f32_e64 v37, s1, s1
	v_max_f32_e32 v47, v36, v37
	v_sub_f32_e32 v37, s1, v47
	v_sub_f32_e32 v36, v36, v47
	v_mul_f32_e32 v37, 0x3fb8aa3b, v37
	v_mul_f32_e32 v36, 0x3fb8aa3b, v36
	v_exp_f32_e32 v38, v37
	v_exp_f32_e32 v36, v36
	v_mov_b32_e32 v46, v47
	v_pk_mul_f32 v[50:51], v[38:39], v[50:51] op_sel_hi:[0,1]
	v_pk_mul_f32 v[42:43], v[38:39], v[42:43] op_sel_hi:[0,1]
	v_pk_fma_f32 v[32:33], v[32:33], v[36:37], v[50:51] op_sel_hi:[1,0,1]
	v_pk_fma_f32 v[40:41], v[40:41], v[36:37], v[42:43] op_sel_hi:[1,0,1]
	v_cvt_pk_bf16_f32 v30, v32, v33
	v_cvt_pk_bf16_f32 v31, v40, v41
	global_store_dwordx2 v1, v[30:31], s[8:9]
	v_mov_b32_e32 v37, v38
	v_pk_mul_f32 v[10:11], v[10:11], v[36:37]
	s_add_u32 s8, s8, 0x8000
	s_addc_u32 s9, s9, 0
	v_add_f32_e32 v10, v10, v11
	s_mov_b64 exec, s[16:17]
	global_store_dword v2, v10, s[12:13]
	s_mov_b64 exec, s[18:19]
	global_store_dword v0, v47, s[14:15] offset:1112
	s_mov_b64 exec, s[20:21]
	s_add_u32 s12, s12, 0x200
	s_addc_u32 s13, s13, 0
	global_load_dwordx2 v[110:111], v1, s[6:7]
	global_load_dword v137, v2, s[10:11]
	s_add_u32 s6, s6, 0x8000
	s_addc_u32 s7, s7, 0
	s_add_u32 s10, s10, 0x200
	s_addc_u32 s11, s11, 0
	v_readlane_b32 s0, v6, 6
	v_readlane_b32 s1, v7, 6
	s_waitcnt vmcnt(45)
	v_lshlrev_b32_e32 v50, 16, v112
	v_and_b32_e32 v51, 0xffff0000, v112
	v_lshlrev_b32_e32 v42, 16, v113
	v_and_b32_e32 v43, 0xffff0000, v113
	v_mov_b32_e32 v11, v138
	v_add_f32_e32 v36, s0, v46
	v_max_f32_e64 v37, s1, s1
	v_max_f32_e32 v47, v36, v37
	v_sub_f32_e32 v37, s1, v47
	v_sub_f32_e32 v36, v36, v47
	v_mul_f32_e32 v37, 0x3fb8aa3b, v37
	v_mul_f32_e32 v36, 0x3fb8aa3b, v36
	v_exp_f32_e32 v38, v37
	v_exp_f32_e32 v36, v36
	v_mov_b32_e32 v46, v47
	v_pk_mul_f32 v[50:51], v[38:39], v[50:51] op_sel_hi:[0,1]
	v_pk_mul_f32 v[42:43], v[38:39], v[42:43] op_sel_hi:[0,1]
	v_pk_fma_f32 v[32:33], v[32:33], v[36:37], v[50:51] op_sel_hi:[1,0,1]
	v_pk_fma_f32 v[40:41], v[40:41], v[36:37], v[42:43] op_sel_hi:[1,0,1]
	v_cvt_pk_bf16_f32 v30, v32, v33
	v_cvt_pk_bf16_f32 v31, v40, v41
	global_store_dwordx2 v1, v[30:31], s[8:9]
	v_mov_b32_e32 v37, v38
	v_pk_mul_f32 v[10:11], v[10:11], v[36:37]
	s_add_u32 s8, s8, 0x8000
	s_addc_u32 s9, s9, 0
	v_add_f32_e32 v10, v10, v11
	s_mov_b64 exec, s[16:17]
	global_store_dword v2, v10, s[12:13]
	s_mov_b64 exec, s[18:19]
	global_store_dword v0, v47, s[14:15] offset:1128
	s_mov_b64 exec, s[20:21]
	s_add_u32 s12, s12, 0x200
	s_addc_u32 s13, s13, 0
	global_load_dwordx2 v[112:113], v1, s[6:7]
	global_load_dword v138, v2, s[10:11]
	s_add_u32 s6, s6, 0x8000
	s_addc_u32 s7, s7, 0
	s_add_u32 s10, s10, 0x200
	s_addc_u32 s11, s11, 0
	v_readlane_b32 s0, v6, 7
	v_readlane_b32 s1, v7, 7
	s_waitcnt vmcnt(45)
	v_lshlrev_b32_e32 v50, 16, v114
	v_and_b32_e32 v51, 0xffff0000, v114
	v_lshlrev_b32_e32 v42, 16, v115
	v_and_b32_e32 v43, 0xffff0000, v115
	v_mov_b32_e32 v11, v139
	v_add_f32_e32 v36, s0, v46
	v_max_f32_e64 v37, s1, s1
	v_max_f32_e32 v47, v36, v37
	v_sub_f32_e32 v37, s1, v47
	v_sub_f32_e32 v36, v36, v47
	v_mul_f32_e32 v37, 0x3fb8aa3b, v37
	v_mul_f32_e32 v36, 0x3fb8aa3b, v36
	v_exp_f32_e32 v38, v37
	v_exp_f32_e32 v36, v36
	v_mov_b32_e32 v46, v47
	v_pk_mul_f32 v[50:51], v[38:39], v[50:51] op_sel_hi:[0,1]
	v_pk_mul_f32 v[42:43], v[38:39], v[42:43] op_sel_hi:[0,1]
	v_pk_fma_f32 v[32:33], v[32:33], v[36:37], v[50:51] op_sel_hi:[1,0,1]
	v_pk_fma_f32 v[40:41], v[40:41], v[36:37], v[42:43] op_sel_hi:[1,0,1]
	v_cvt_pk_bf16_f32 v30, v32, v33
	v_cvt_pk_bf16_f32 v31, v40, v41
	global_store_dwordx2 v1, v[30:31], s[8:9]
	v_mov_b32_e32 v37, v38
	v_pk_mul_f32 v[10:11], v[10:11], v[36:37]
	s_add_u32 s8, s8, 0x8000
	s_addc_u32 s9, s9, 0
	v_add_f32_e32 v10, v10, v11
	s_mov_b64 exec, s[16:17]
	global_store_dword v2, v10, s[12:13]
	s_mov_b64 exec, s[18:19]
	global_store_dword v0, v47, s[14:15] offset:1144
	s_mov_b64 exec, s[20:21]
	s_add_u32 s12, s12, 0x200
	s_addc_u32 s13, s13, 0
	global_load_dwordx2 v[114:115], v1, s[6:7]
	global_load_dword v139, v2, s[10:11]
	s_add_u32 s6, s6, 0x8000
	s_addc_u32 s7, s7, 0
	s_add_u32 s10, s10, 0x200
	s_addc_u32 s11, s11, 0
	v_readlane_b32 s0, v6, 8
	v_readlane_b32 s1, v7, 8
	s_waitcnt vmcnt(45)
	v_lshlrev_b32_e32 v50, 16, v116
	v_and_b32_e32 v51, 0xffff0000, v116
	v_lshlrev_b32_e32 v42, 16, v117
	v_and_b32_e32 v43, 0xffff0000, v117
	v_mov_b32_e32 v11, v140
	v_add_f32_e32 v36, s0, v46
	v_max_f32_e64 v37, s1, s1
	v_max_f32_e32 v47, v36, v37
	v_sub_f32_e32 v37, s1, v47
	v_sub_f32_e32 v36, v36, v47
	v_mul_f32_e32 v37, 0x3fb8aa3b, v37
	v_mul_f32_e32 v36, 0x3fb8aa3b, v36
	v_exp_f32_e32 v38, v37
	v_exp_f32_e32 v36, v36
	v_mov_b32_e32 v46, v47
	v_pk_mul_f32 v[50:51], v[38:39], v[50:51] op_sel_hi:[0,1]
	v_pk_mul_f32 v[42:43], v[38:39], v[42:43] op_sel_hi:[0,1]
	v_pk_fma_f32 v[32:33], v[32:33], v[36:37], v[50:51] op_sel_hi:[1,0,1]
	v_pk_fma_f32 v[40:41], v[40:41], v[36:37], v[42:43] op_sel_hi:[1,0,1]
	v_cvt_pk_bf16_f32 v30, v32, v33
	v_cvt_pk_bf16_f32 v31, v40, v41
	global_store_dwordx2 v1, v[30:31], s[8:9]
	v_mov_b32_e32 v37, v38
	v_pk_mul_f32 v[10:11], v[10:11], v[36:37]
	s_add_u32 s8, s8, 0x8000
	s_addc_u32 s9, s9, 0
	v_add_f32_e32 v10, v10, v11
	s_mov_b64 exec, s[16:17]
	global_store_dword v2, v10, s[12:13]
	s_mov_b64 exec, s[18:19]
	global_store_dword v0, v47, s[14:15] offset:1160
	s_mov_b64 exec, s[20:21]
	s_add_u32 s12, s12, 0x200
	s_addc_u32 s13, s13, 0
	global_load_dwordx2 v[116:117], v1, s[6:7]
	global_load_dword v140, v2, s[10:11]
	s_add_u32 s6, s6, 0x8000
	s_addc_u32 s7, s7, 0
	s_add_u32 s10, s10, 0x200
	s_addc_u32 s11, s11, 0
	v_readlane_b32 s0, v6, 9
	v_readlane_b32 s1, v7, 9
	s_waitcnt vmcnt(45)
; DI unsigned pack2(float a, float b) { const f32x2 v = {a, b}; return __builtin_bit_cast(unsigned, __builtin_convertvector(v, bf16v2)); }
; DI float bflo(unsigned w) { return __uint_as_float(w << 16); }
; DI float bfhi(unsigned w) { return __uint_as_float(w & 0xffff0000u); }
; DI void phase_mlstm_scan(const Params& p) {
;     ...
;       for (int j = 0; j < 8; ++j) { raw[j] = *(const uint2*)(kv + (size_t)(cb + j) * 16384); kr[j] = don ? ks[(cb + j) * 128] : 0.f; }
; #pragma unroll
;       for (int j = 0; j < 8; ++j) {
;         const float B = csc[(cb + j) * 4], A = csc[(cb + j) * 4 + 1];
;         const float mnew = fmaxf(B + m, A);
;         const float wp = __expf(B + m - mnew), wl = __expf(A - mnew);
;         m = mnew;
;         c0 = wp * c0 + wl * bflo(raw[j].x); c1 = wp * c1 + wl * bfhi(raw[j].x); c2 = wp * c2 + wl * bflo(raw[j].y); c3 = wp * c3 + wl * bfhi(raw[j].y);
;         uint2 o; o.x = pack2(c0, c1); o.y = pack2(c2, c3);
;         *(uint2*)(kv + (size_t)(cb + j) * 16384) = o;
;         if (don) { n = wp * n + wl * kr[j]; ks[(cb + j) * 128] = n; }
;         if (part == 0 && tid == 0) csc[(cb + j) * 4 + 2] = mnew;
	v_lshlrev_b32_e32 v50, 16, v118
	v_and_b32_e32 v51, 0xffff0000, v118
	v_lshlrev_b32_e32 v42, 16, v119
	v_and_b32_e32 v43, 0xffff0000, v119
	v_mov_b32_e32 v11, v141
	v_add_f32_e32 v36, s0, v46
	v_max_f32_e64 v37, s1, s1
	v_max_f32_e32 v47, v36, v37
	v_sub_f32_e32 v37, s1, v47
	v_sub_f32_e32 v36, v36, v47
	v_mul_f32_e32 v37, 0x3fb8aa3b, v37
	v_mul_f32_e32 v36, 0x3fb8aa3b, v36
	v_exp_f32_e32 v38, v37
	v_exp_f32_e32 v36, v36
	v_mov_b32_e32 v46, v47
	v_pk_mul_f32 v[50:51], v[38:39], v[50:51] op_sel_hi:[0,1]
	v_pk_mul_f32 v[42:43], v[38:39], v[42:43] op_sel_hi:[0,1]
	v_pk_fma_f32 v[32:33], v[32:33], v[36:37], v[50:51] op_sel_hi:[1,0,1]
	v_pk_fma_f32 v[40:41], v[40:41], v[36:37], v[42:43] op_sel_hi:[1,0,1]
	v_cvt_pk_bf16_f32 v30, v32, v33
	v_cvt_pk_bf16_f32 v31, v40, v41
	global_store_dwordx2 v1, v[30:31], s[8:9]
	v_mov_b32_e32 v37, v38
	v_pk_mul_f32 v[10:11], v[10:11], v[36:37]
	s_add_u32 s8, s8, 0x8000
	s_addc_u32 s9, s9, 0
	v_add_f32_e32 v10, v10, v11
	s_mov_b64 exec, s[16:17]
	global_store_dword v2, v10, s[12:13]
	s_mov_b64 exec, s[18:19]
	global_store_dword v0, v47, s[14:15] offset:1176
	s_mov_b64 exec, s[20:21]
	s_add_u32 s12, s12, 0x200
	s_addc_u32 s13, s13, 0
	global_load_dwordx2 v[118:119], v1, s[6:7]
	global_load_dword v141, v2, s[10:11]
	s_add_u32 s6, s6, 0x8000
	s_addc_u32 s7, s7, 0
	s_add_u32 s10, s10, 0x200
	s_addc_u32 s11, s11, 0
	v_readlane_b32 s0, v6, 10
	v_readlane_b32 s1, v7, 10
	s_waitcnt vmcnt(45)
	v_lshlrev_b32_e32 v50, 16, v120
	v_and_b32_e32 v51, 0xffff0000, v120
	v_lshlrev_b32_e32 v42, 16, v121
	v_and_b32_e32 v43, 0xffff0000, v121
	v_mov_b32_e32 v11, v142
	v_add_f32_e32 v36, s0, v46
	v_max_f32_e64 v37, s1, s1
	v_max_f32_e32 v47, v36, v37
	v_sub_f32_e32 v37, s1, v47
	v_sub_f32_e32 v36, v36, v47
	v_mul_f32_e32 v37, 0x3fb8aa3b, v37
	v_mul_f32_e32 v36, 0x3fb8aa3b, v36
	v_exp_f32_e32 v38, v37
	v_exp_f32_e32 v36, v36
	v_mov_b32_e32 v46, v47
	v_pk_mul_f32 v[50:51], v[38:39], v[50:51] op_sel_hi:[0,1]
	v_pk_mul_f32 v[42:43], v[38:39], v[42:43] op_sel_hi:[0,1]
	v_pk_fma_f32 v[32:33], v[32:33], v[36:37], v[50:51] op_sel_hi:[1,0,1]
	v_pk_fma_f32 v[40:41], v[40:41], v[36:37], v[42:43] op_sel_hi:[1,0,1]
	v_cvt_pk_bf16_f32 v30, v32, v33
	v_cvt_pk_bf16_f32 v31, v40, v41
	global_store_dwordx2 v1, v[30:31], s[8:9]
	v_mov_b32_e32 v37, v38
	v_pk_mul_f32 v[10:11], v[10:11], v[36:37]
	s_add_u32 s8, s8, 0x8000
	s_addc_u32 s9, s9, 0
	v_add_f32_e32 v10, v10, v11
	s_mov_b64 exec, s[16:17]
	global_store_dword v2, v10, s[12:13]
	s_mov_b64 exec, s[18:19]
	global_store_dword v0, v47, s[14:15] offset:1192
	s_mov_b64 exec, s[20:21]
	s_add_u32 s12, s12, 0x200
	s_addc_u32 s13, s13, 0
	global_load_dwordx2 v[120:121], v1, s[6:7]
	global_load_dword v142, v2, s[10:11]
	s_add_u32 s6, s6, 0x8000
	s_addc_u32 s7, s7, 0
	s_add_u32 s10, s10, 0x200
	s_addc_u32 s11, s11, 0
	v_readlane_b32 s0, v6, 11
	v_readlane_b32 s1, v7, 11
	s_waitcnt vmcnt(45)
	v_lshlrev_b32_e32 v50, 16, v122
	v_and_b32_e32 v51, 0xffff0000, v122
	v_lshlrev_b32_e32 v42, 16, v123
	v_and_b32_e32 v43, 0xffff0000, v123
	v_mov_b32_e32 v11, v143
	v_add_f32_e32 v36, s0, v46
	v_max_f32_e64 v37, s1, s1
	v_max_f32_e32 v47, v36, v37
	v_sub_f32_e32 v37, s1, v47
	v_sub_f32_e32 v36, v36, v47
	v_mul_f32_e32 v37, 0x3fb8aa3b, v37
	v_mul_f32_e32 v36, 0x3fb8aa3b, v36
	v_exp_f32_e32 v38, v37
	v_exp_f32_e32 v36, v36
	v_mov_b32_e32 v46, v47
	v_pk_mul_f32 v[50:51], v[38:39], v[50:51] op_sel_hi:[0,1]
	v_pk_mul_f32 v[42:43], v[38:39], v[42:43] op_sel_hi:[0,1]
	v_pk_fma_f32 v[32:33], v[32:33], v[36:37], v[50:51] op_sel_hi:[1,0,1]
	v_pk_fma_f32 v[40:41], v[40:41], v[36:37], v[42:43] op_sel_hi:[1,0,1]
	v_cvt_pk_bf16_f32 v30, v32, v33
	v_cvt_pk_bf16_f32 v31, v40, v41
	global_store_dwordx2 v1, v[30:31], s[8:9]
	v_mov_b32_e32 v37, v38
	v_pk_mul_f32 v[10:11], v[10:11], v[36:37]
	s_add_u32 s8, s8, 0x8000
	s_addc_u32 s9, s9, 0
	v_add_f32_e32 v10, v10, v11
	s_mov_b64 exec, s[16:17]
	global_store_dword v2, v10, s[12:13]
	s_mov_b64 exec, s[18:19]
	global_store_dword v0, v47, s[14:15] offset:1208
	s_mov_b64 exec, s[20:21]
	s_add_u32 s12, s12, 0x200
	s_addc_u32 s13, s13, 0
	global_load_dwordx2 v[122:123], v1, s[6:7]
	global_load_dword v143, v2, s[10:11]
	s_add_u32 s6, s6, 0x8000
	s_addc_u32 s7, s7, 0
	s_add_u32 s10, s10, 0x200
	s_addc_u32 s11, s11, 0
	v_readlane_b32 s0, v6, 12
	v_readlane_b32 s1, v7, 12
	s_waitcnt vmcnt(45)
	v_lshlrev_b32_e32 v50, 16, v124
	v_and_b32_e32 v51, 0xffff0000, v124
	v_lshlrev_b32_e32 v42, 16, v125
	v_and_b32_e32 v43, 0xffff0000, v125
	v_mov_b32_e32 v11, v144
	v_add_f32_e32 v36, s0, v46
	v_max_f32_e64 v37, s1, s1
	v_max_f32_e32 v47, v36, v37
	v_sub_f32_e32 v37, s1, v47
	v_sub_f32_e32 v36, v36, v47
	v_mul_f32_e32 v37, 0x3fb8aa3b, v37
	v_mul_f32_e32 v36, 0x3fb8aa3b, v36
	v_exp_f32_e32 v38, v37
	v_exp_f32_e32 v36, v36
	v_mov_b32_e32 v46, v47
	v_pk_mul_f32 v[50:51], v[38:39], v[50:51] op_sel_hi:[0,1]
	v_pk_mul_f32 v[42:43], v[38:39], v[42:43] op_sel_hi:[0,1]
	v_pk_fma_f32 v[32:33], v[32:33], v[36:37], v[50:51] op_sel_hi:[1,0,1]
	v_pk_fma_f32 v[40:41], v[40:41], v[36:37], v[42:43] op_sel_hi:[1,0,1]
	v_cvt_pk_bf16_f32 v30, v32, v33
	v_cvt_pk_bf16_f32 v31, v40, v41
	global_store_dwordx2 v1, v[30:31], s[8:9]
	v_mov_b32_e32 v37, v38
	v_pk_mul_f32 v[10:11], v[10:11], v[36:37]
	s_add_u32 s8, s8, 0x8000
	s_addc_u32 s9, s9, 0
	v_add_f32_e32 v10, v10, v11
	s_mov_b64 exec, s[16:17]
	global_store_dword v2, v10, s[12:13]
	s_mov_b64 exec, s[18:19]
	global_store_dword v0, v47, s[14:15] offset:1224
	s_mov_b64 exec, s[20:21]
	s_add_u32 s12, s12, 0x200
	s_addc_u32 s13, s13, 0
	global_load_dwordx2 v[124:125], v1, s[6:7]
	global_load_dword v144, v2, s[10:11]
	s_add_u32 s6, s6, 0x8000
	s_addc_u32 s7, s7, 0
	s_add_u32 s10, s10, 0x200
	s_addc_u32 s11, s11, 0
	v_readlane_b32 s0, v6, 13
	v_readlane_b32 s1, v7, 13
	s_waitcnt vmcnt(45)
; DI unsigned pack2(float a, float b) { const f32x2 v = {a, b}; return __builtin_bit_cast(unsigned, __builtin_convertvector(v, bf16v2)); }
; DI float bflo(unsigned w) { return __uint_as_float(w << 16); }
; DI float bfhi(unsigned w) { return __uint_as_float(w & 0xffff0000u); }
; DI void phase_mlstm_scan(const Params& p) {
;     ...
;     for (int cb = 0; cb < 128; cb += 8) {
;       uint2 raw[8]; float kr[8];
; #pragma unroll
;       for (int j = 0; j < 8; ++j) { raw[j] = *(const uint2*)(kv + (size_t)(cb + j) * 16384); kr[j] = don ? ks[(cb + j) * 128] : 0.f; }
; #pragma unroll
;       for (int j = 0; j < 8; ++j) {
;         const float B = csc[(cb + j) * 4], A = csc[(cb + j) * 4 + 1];
;         const float mnew = fmaxf(B + m, A);
;         const float wp = __expf(B + m - mnew), wl = __expf(A - mnew);
;         m = mnew;
;         c0 = wp * c0 + wl * bflo(raw[j].x); c1 = wp * c1 + wl * bfhi(raw[j].x); c2 = wp * c2 + wl * bflo(raw[j].y); c3 = wp * c3 + wl * bfhi(raw[j].y);
;         uint2 o; o.x = pack2(c0, c1); o.y = pack2(c2, c3);
;         *(uint2*)(kv + (size_t)(cb + j) * 16384) = o;
;         if (don) { n = wp * n + wl * kr[j]; ks[(cb + j) * 128] = n; }
;         if (part == 0 && tid == 0) csc[(cb + j) * 4 + 2] = mnew;
;       }
;     }
	v_lshlrev_b32_e32 v50, 16, v126
	v_and_b32_e32 v51, 0xffff0000, v126
	v_lshlrev_b32_e32 v42, 16, v127
	v_and_b32_e32 v43, 0xffff0000, v127
	v_mov_b32_e32 v11, v145
	v_add_f32_e32 v36, s0, v46
	v_max_f32_e64 v37, s1, s1
	v_max_f32_e32 v47, v36, v37
	v_sub_f32_e32 v37, s1, v47
	v_sub_f32_e32 v36, v36, v47
	v_mul_f32_e32 v37, 0x3fb8aa3b, v37
	v_mul_f32_e32 v36, 0x3fb8aa3b, v36
	v_exp_f32_e32 v38, v37
	v_exp_f32_e32 v36, v36
	v_mov_b32_e32 v46, v47
	v_pk_mul_f32 v[50:51], v[38:39], v[50:51] op_sel_hi:[0,1]
	v_pk_mul_f32 v[42:43], v[38:39], v[42:43] op_sel_hi:[0,1]
	v_pk_fma_f32 v[32:33], v[32:33], v[36:37], v[50:51] op_sel_hi:[1,0,1]
	v_pk_fma_f32 v[40:41], v[40:41], v[36:37], v[42:43] op_sel_hi:[1,0,1]
	v_cvt_pk_bf16_f32 v30, v32, v33
	v_cvt_pk_bf16_f32 v31, v40, v41
	global_store_dwordx2 v1, v[30:31], s[8:9]
	v_mov_b32_e32 v37, v38
	v_pk_mul_f32 v[10:11], v[10:11], v[36:37]
	s_add_u32 s8, s8, 0x8000
	s_addc_u32 s9, s9, 0
	v_add_f32_e32 v10, v10, v11
	s_mov_b64 exec, s[16:17]
	global_store_dword v2, v10, s[12:13]
	s_mov_b64 exec, s[18:19]
	global_store_dword v0, v47, s[14:15] offset:1240
	s_mov_b64 exec, s[20:21]
	s_add_u32 s12, s12, 0x200
	s_addc_u32 s13, s13, 0
	global_load_dwordx2 v[126:127], v1, s[6:7]
	global_load_dword v145, v2, s[10:11]
	s_add_u32 s6, s6, 0x8000
	s_addc_u32 s7, s7, 0
	s_add_u32 s10, s10, 0x200
	s_addc_u32 s11, s11, 0
	v_readlane_b32 s0, v6, 14
	v_readlane_b32 s1, v7, 14
	s_waitcnt vmcnt(45)
	v_lshlrev_b32_e32 v50, 16, v128
	v_and_b32_e32 v51, 0xffff0000, v128
	v_lshlrev_b32_e32 v42, 16, v129
	v_and_b32_e32 v43, 0xffff0000, v129
	v_mov_b32_e32 v11, v146
	v_add_f32_e32 v36, s0, v46
	v_max_f32_e64 v37, s1, s1
	v_max_f32_e32 v47, v36, v37
	v_sub_f32_e32 v37, s1, v47
	v_sub_f32_e32 v36, v36, v47
	v_mul_f32_e32 v37, 0x3fb8aa3b, v37
	v_mul_f32_e32 v36, 0x3fb8aa3b, v36
	v_exp_f32_e32 v38, v37
	v_exp_f32_e32 v36, v36
	v_mov_b32_e32 v46, v47
	v_pk_mul_f32 v[50:51], v[38:39], v[50:51] op_sel_hi:[0,1]
	v_pk_mul_f32 v[42:43], v[38:39], v[42:43] op_sel_hi:[0,1]
	v_pk_fma_f32 v[32:33], v[32:33], v[36:37], v[50:51] op_sel_hi:[1,0,1]
	v_pk_fma_f32 v[40:41], v[40:41], v[36:37], v[42:43] op_sel_hi:[1,0,1]
	v_cvt_pk_bf16_f32 v30, v32, v33
	v_cvt_pk_bf16_f32 v31, v40, v41
	global_store_dwordx2 v1, v[30:31], s[8:9]
	v_mov_b32_e32 v37, v38
	v_pk_mul_f32 v[10:11], v[10:11], v[36:37]
	s_add_u32 s8, s8, 0x8000
	s_addc_u32 s9, s9, 0
	v_add_f32_e32 v10, v10, v11
	s_mov_b64 exec, s[16:17]
	global_store_dword v2, v10, s[12:13]
	s_mov_b64 exec, s[18:19]
	global_store_dword v0, v47, s[14:15] offset:1256
	s_mov_b64 exec, s[20:21]
	s_add_u32 s12, s12, 0x200
	s_addc_u32 s13, s13, 0
	global_load_dwordx2 v[128:129], v1, s[6:7]
	global_load_dword v146, v2, s[10:11]
	s_add_u32 s6, s6, 0x8000
	s_addc_u32 s7, s7, 0
	s_add_u32 s10, s10, 0x200
	s_addc_u32 s11, s11, 0
	v_readlane_b32 s0, v6, 15
	v_readlane_b32 s1, v7, 15
	s_waitcnt vmcnt(45)
	v_lshlrev_b32_e32 v50, 16, v130
	v_and_b32_e32 v51, 0xffff0000, v130
	v_lshlrev_b32_e32 v42, 16, v131
	v_and_b32_e32 v43, 0xffff0000, v131
	v_mov_b32_e32 v11, v147
	v_add_f32_e32 v36, s0, v46
	v_max_f32_e64 v37, s1, s1
	v_max_f32_e32 v47, v36, v37
	v_sub_f32_e32 v37, s1, v47
	v_sub_f32_e32 v36, v36, v47
	v_mul_f32_e32 v37, 0x3fb8aa3b, v37
	v_mul_f32_e32 v36, 0x3fb8aa3b, v36
	v_exp_f32_e32 v38, v37
	v_exp_f32_e32 v36, v36
	v_mov_b32_e32 v46, v47
	v_pk_mul_f32 v[50:51], v[38:39], v[50:51] op_sel_hi:[0,1]
	v_pk_mul_f32 v[42:43], v[38:39], v[42:43] op_sel_hi:[0,1]
	v_pk_fma_f32 v[32:33], v[32:33], v[36:37], v[50:51] op_sel_hi:[1,0,1]
	v_pk_fma_f32 v[40:41], v[40:41], v[36:37], v[42:43] op_sel_hi:[1,0,1]
	v_cvt_pk_bf16_f32 v30, v32, v33
	v_cvt_pk_bf16_f32 v31, v40, v41
	global_store_dwordx2 v1, v[30:31], s[8:9]
	v_mov_b32_e32 v37, v38
	v_pk_mul_f32 v[10:11], v[10:11], v[36:37]
	s_add_u32 s8, s8, 0x8000
	s_addc_u32 s9, s9, 0
	v_add_f32_e32 v10, v10, v11
	s_mov_b64 exec, s[16:17]
	global_store_dword v2, v10, s[12:13]
	s_mov_b64 exec, s[18:19]
	global_store_dword v0, v47, s[14:15] offset:1272
	s_mov_b64 exec, s[20:21]
	s_add_u32 s12, s12, 0x200
	s_addc_u32 s13, s13, 0
	global_load_dwordx2 v[130:131], v1, s[6:7]
	global_load_dword v147, v2, s[10:11]
	s_add_u32 s6, s6, 0x8000
	s_addc_u32 s7, s7, 0
	s_add_u32 s10, s10, 0x200
	s_addc_u32 s11, s11, 0
	v_readlane_b32 s0, v6, 16
	v_readlane_b32 s1, v7, 16
	s_waitcnt vmcnt(45)
	v_lshlrev_b32_e32 v50, 16, v100
	v_and_b32_e32 v51, 0xffff0000, v100
	v_lshlrev_b32_e32 v42, 16, v101
	v_and_b32_e32 v43, 0xffff0000, v101
	v_mov_b32_e32 v11, v132
	v_add_f32_e32 v36, s0, v46
	v_max_f32_e64 v37, s1, s1
	v_max_f32_e32 v47, v36, v37
	v_sub_f32_e32 v37, s1, v47
	v_sub_f32_e32 v36, v36, v47
	v_mul_f32_e32 v37, 0x3fb8aa3b, v37
	v_mul_f32_e32 v36, 0x3fb8aa3b, v36
	v_exp_f32_e32 v38, v37
	v_exp_f32_e32 v36, v36
	v_mov_b32_e32 v46, v47
	v_pk_mul_f32 v[50:51], v[38:39], v[50:51] op_sel_hi:[0,1]
	v_pk_mul_f32 v[42:43], v[38:39], v[42:43] op_sel_hi:[0,1]
	v_pk_fma_f32 v[32:33], v[32:33], v[36:37], v[50:51] op_sel_hi:[1,0,1]
	v_pk_fma_f32 v[40:41], v[40:41], v[36:37], v[42:43] op_sel_hi:[1,0,1]
	v_cvt_pk_bf16_f32 v30, v32, v33
	v_cvt_pk_bf16_f32 v31, v40, v41
	global_store_dwordx2 v1, v[30:31], s[8:9]
	v_mov_b32_e32 v37, v38
	v_pk_mul_f32 v[10:11], v[10:11], v[36:37]
	s_add_u32 s8, s8, 0x8000
	s_addc_u32 s9, s9, 0
	v_add_f32_e32 v10, v10, v11
	s_mov_b64 exec, s[16:17]
	global_store_dword v2, v10, s[12:13]
	s_mov_b64 exec, s[18:19]
	global_store_dword v0, v47, s[14:15] offset:1288
	s_mov_b64 exec, s[20:21]
	s_add_u32 s12, s12, 0x200
	s_addc_u32 s13, s13, 0
	global_load_dwordx2 v[100:101], v1, s[6:7]
	global_load_dword v132, v2, s[10:11]
	s_add_u32 s6, s6, 0x8000
	s_addc_u32 s7, s7, 0
	s_add_u32 s10, s10, 0x200
	s_addc_u32 s11, s11, 0
	v_readlane_b32 s0, v6, 17
	v_readlane_b32 s1, v7, 17
	s_waitcnt vmcnt(45)
; DI unsigned pack2(float a, float b) { const f32x2 v = {a, b}; return __builtin_bit_cast(unsigned, __builtin_convertvector(v, bf16v2)); }
; DI float bflo(unsigned w) { return __uint_as_float(w << 16); }
; DI float bfhi(unsigned w) { return __uint_as_float(w & 0xffff0000u); }
; DI void phase_mlstm_scan(const Params& p) {
;     ...
;     for (int cb = 0; cb < 128; cb += 8) {
;       uint2 raw[8]; float kr[8];
; #pragma unroll
;       for (int j = 0; j < 8; ++j) { raw[j] = *(const uint2*)(kv + (size_t)(cb + j) * 16384); kr[j] = don ? ks[(cb + j) * 128] : 0.f; }
; #pragma unroll
;       for (int j = 0; j < 8; ++j) {
;         const float B = csc[(cb + j) * 4], A = csc[(cb + j) * 4 + 1];
;         const float mnew = fmaxf(B + m, A);
;         const float wp = __expf(B + m - mnew), wl = __expf(A - mnew);
;         m = mnew;
;         c0 = wp * c0 + wl * bflo(raw[j].x); c1 = wp * c1 + wl * bfhi(raw[j].x); c2 = wp * c2 + wl * bflo(raw[j].y); c3 = wp * c3 + wl * bfhi(raw[j].y);
;         uint2 o; o.x = pack2(c0, c1); o.y = pack2(c2, c3);
;         *(uint2*)(kv + (size_t)(cb + j) * 16384) = o;
;         if (don) { n = wp * n + wl * kr[j]; ks[(cb + j) * 128] = n; }
;         if (part == 0 && tid == 0) csc[(cb + j) * 4 + 2] = mnew;
;       }
;     }
	v_lshlrev_b32_e32 v50, 16, v102
	v_and_b32_e32 v51, 0xffff0000, v102
	v_lshlrev_b32_e32 v42, 16, v103
	v_and_b32_e32 v43, 0xffff0000, v103
	v_mov_b32_e32 v11, v133
	v_add_f32_e32 v36, s0, v46
	v_max_f32_e64 v37, s1, s1
	v_max_f32_e32 v47, v36, v37
	v_sub_f32_e32 v37, s1, v47
	v_sub_f32_e32 v36, v36, v47
	v_mul_f32_e32 v37, 0x3fb8aa3b, v37
	v_mul_f32_e32 v36, 0x3fb8aa3b, v36
	v_exp_f32_e32 v38, v37
	v_exp_f32_e32 v36, v36
	v_mov_b32_e32 v46, v47
	v_pk_mul_f32 v[50:51], v[38:39], v[50:51] op_sel_hi:[0,1]
	v_pk_mul_f32 v[42:43], v[38:39], v[42:43] op_sel_hi:[0,1]
	v_pk_fma_f32 v[32:33], v[32:33], v[36:37], v[50:51] op_sel_hi:[1,0,1]
	v_pk_fma_f32 v[40:41], v[40:41], v[36:37], v[42:43] op_sel_hi:[1,0,1]
	v_cvt_pk_bf16_f32 v30, v32, v33
	v_cvt_pk_bf16_f32 v31, v40, v41
	global_store_dwordx2 v1, v[30:31], s[8:9]
	v_mov_b32_e32 v37, v38
	v_pk_mul_f32 v[10:11], v[10:11], v[36:37]
	s_add_u32 s8, s8, 0x8000
	s_addc_u32 s9, s9, 0
	v_add_f32_e32 v10, v10, v11
	s_mov_b64 exec, s[16:17]
	global_store_dword v2, v10, s[12:13]
	s_mov_b64 exec, s[18:19]
	global_store_dword v0, v47, s[14:15] offset:1304
	s_mov_b64 exec, s[20:21]
	s_add_u32 s12, s12, 0x200
	s_addc_u32 s13, s13, 0
	global_load_dwordx2 v[102:103], v1, s[6:7]
	global_load_dword v133, v2, s[10:11]
	s_add_u32 s6, s6, 0x8000
	s_addc_u32 s7, s7, 0
	s_add_u32 s10, s10, 0x200
	s_addc_u32 s11, s11, 0
	v_readlane_b32 s0, v6, 18
	v_readlane_b32 s1, v7, 18
	s_waitcnt vmcnt(45)
	v_lshlrev_b32_e32 v50, 16, v104
	v_and_b32_e32 v51, 0xffff0000, v104
	v_lshlrev_b32_e32 v42, 16, v105
	v_and_b32_e32 v43, 0xffff0000, v105
	v_mov_b32_e32 v11, v134
	v_add_f32_e32 v36, s0, v46
	v_max_f32_e64 v37, s1, s1
	v_max_f32_e32 v47, v36, v37
	v_sub_f32_e32 v37, s1, v47
	v_sub_f32_e32 v36, v36, v47
	v_mul_f32_e32 v37, 0x3fb8aa3b, v37
	v_mul_f32_e32 v36, 0x3fb8aa3b, v36
	v_exp_f32_e32 v38, v37
	v_exp_f32_e32 v36, v36
	v_mov_b32_e32 v46, v47
	v_pk_mul_f32 v[50:51], v[38:39], v[50:51] op_sel_hi:[0,1]
	v_pk_mul_f32 v[42:43], v[38:39], v[42:43] op_sel_hi:[0,1]
	v_pk_fma_f32 v[32:33], v[32:33], v[36:37], v[50:51] op_sel_hi:[1,0,1]
	v_pk_fma_f32 v[40:41], v[40:41], v[36:37], v[42:43] op_sel_hi:[1,0,1]
	v_cvt_pk_bf16_f32 v30, v32, v33
	v_cvt_pk_bf16_f32 v31, v40, v41
	global_store_dwordx2 v1, v[30:31], s[8:9]
	v_mov_b32_e32 v37, v38
	v_pk_mul_f32 v[10:11], v[10:11], v[36:37]
	s_add_u32 s8, s8, 0x8000
	s_addc_u32 s9, s9, 0
	v_add_f32_e32 v10, v10, v11
	s_mov_b64 exec, s[16:17]
	global_store_dword v2, v10, s[12:13]
	s_mov_b64 exec, s[18:19]
	global_store_dword v0, v47, s[14:15] offset:1320
	s_mov_b64 exec, s[20:21]
	s_add_u32 s12, s12, 0x200
	s_addc_u32 s13, s13, 0
	global_load_dwordx2 v[104:105], v1, s[6:7]
	global_load_dword v134, v2, s[10:11]
	s_add_u32 s6, s6, 0x8000
	s_addc_u32 s7, s7, 0
	s_add_u32 s10, s10, 0x200
	s_addc_u32 s11, s11, 0
	v_readlane_b32 s0, v6, 19
	v_readlane_b32 s1, v7, 19
	s_waitcnt vmcnt(45)
	v_lshlrev_b32_e32 v50, 16, v106
	v_and_b32_e32 v51, 0xffff0000, v106
	v_lshlrev_b32_e32 v42, 16, v107
	v_and_b32_e32 v43, 0xffff0000, v107
	v_mov_b32_e32 v11, v135
	v_add_f32_e32 v36, s0, v46
	v_max_f32_e64 v37, s1, s1
	v_max_f32_e32 v47, v36, v37
	v_sub_f32_e32 v37, s1, v47
	v_sub_f32_e32 v36, v36, v47
	v_mul_f32_e32 v37, 0x3fb8aa3b, v37
	v_mul_f32_e32 v36, 0x3fb8aa3b, v36
	v_exp_f32_e32 v38, v37
	v_exp_f32_e32 v36, v36
	v_mov_b32_e32 v46, v47
	v_pk_mul_f32 v[50:51], v[38:39], v[50:51] op_sel_hi:[0,1]
	v_pk_mul_f32 v[42:43], v[38:39], v[42:43] op_sel_hi:[0,1]
	v_pk_fma_f32 v[32:33], v[32:33], v[36:37], v[50:51] op_sel_hi:[1,0,1]
	v_pk_fma_f32 v[40:41], v[40:41], v[36:37], v[42:43] op_sel_hi:[1,0,1]
	v_cvt_pk_bf16_f32 v30, v32, v33
	v_cvt_pk_bf16_f32 v31, v40, v41
	global_store_dwordx2 v1, v[30:31], s[8:9]
	v_mov_b32_e32 v37, v38
	v_pk_mul_f32 v[10:11], v[10:11], v[36:37]
	s_add_u32 s8, s8, 0x8000
	s_addc_u32 s9, s9, 0
	v_add_f32_e32 v10, v10, v11
	s_mov_b64 exec, s[16:17]
	global_store_dword v2, v10, s[12:13]
	s_mov_b64 exec, s[18:19]
	global_store_dword v0, v47, s[14:15] offset:1336
	s_mov_b64 exec, s[20:21]
	s_add_u32 s12, s12, 0x200
	s_addc_u32 s13, s13, 0
	global_load_dwordx2 v[106:107], v1, s[6:7]
	global_load_dword v135, v2, s[10:11]
	s_add_u32 s6, s6, 0x8000
	s_addc_u32 s7, s7, 0
	s_add_u32 s10, s10, 0x200
	s_addc_u32 s11, s11, 0
	v_readlane_b32 s0, v6, 20
	v_readlane_b32 s1, v7, 20
	s_waitcnt vmcnt(45)
	v_lshlrev_b32_e32 v50, 16, v108
	v_and_b32_e32 v51, 0xffff0000, v108
	v_lshlrev_b32_e32 v42, 16, v109
	v_and_b32_e32 v43, 0xffff0000, v109
	v_mov_b32_e32 v11, v136
	v_add_f32_e32 v36, s0, v46
	v_max_f32_e64 v37, s1, s1
	v_max_f32_e32 v47, v36, v37
	v_sub_f32_e32 v37, s1, v47
	v_sub_f32_e32 v36, v36, v47
	v_mul_f32_e32 v37, 0x3fb8aa3b, v37
	v_mul_f32_e32 v36, 0x3fb8aa3b, v36
	v_exp_f32_e32 v38, v37
	v_exp_f32_e32 v36, v36
	v_mov_b32_e32 v46, v47
	v_pk_mul_f32 v[50:51], v[38:39], v[50:51] op_sel_hi:[0,1]
	v_pk_mul_f32 v[42:43], v[38:39], v[42:43] op_sel_hi:[0,1]
	v_pk_fma_f32 v[32:33], v[32:33], v[36:37], v[50:51] op_sel_hi:[1,0,1]
	v_pk_fma_f32 v[40:41], v[40:41], v[36:37], v[42:43] op_sel_hi:[1,0,1]
	v_cvt_pk_bf16_f32 v30, v32, v33
	v_cvt_pk_bf16_f32 v31, v40, v41
	global_store_dwordx2 v1, v[30:31], s[8:9]
	v_mov_b32_e32 v37, v38
	v_pk_mul_f32 v[10:11], v[10:11], v[36:37]
	s_add_u32 s8, s8, 0x8000
	s_addc_u32 s9, s9, 0
	v_add_f32_e32 v10, v10, v11
	s_mov_b64 exec, s[16:17]
	global_store_dword v2, v10, s[12:13]
	s_mov_b64 exec, s[18:19]
	global_store_dword v0, v47, s[14:15] offset:1352
	s_mov_b64 exec, s[20:21]
	s_add_u32 s12, s12, 0x200
	s_addc_u32 s13, s13, 0
	global_load_dwordx2 v[108:109], v1, s[6:7]
	global_load_dword v136, v2, s[10:11]
	s_add_u32 s6, s6, 0x8000
	s_addc_u32 s7, s7, 0
	s_add_u32 s10, s10, 0x200
	s_addc_u32 s11, s11, 0
	v_readlane_b32 s0, v6, 21
	v_readlane_b32 s1, v7, 21
	s_waitcnt vmcnt(45)
; DI unsigned pack2(float a, float b) { const f32x2 v = {a, b}; return __builtin_bit_cast(unsigned, __builtin_convertvector(v, bf16v2)); }
; DI float bflo(unsigned w) { return __uint_as_float(w << 16); }
; DI float bfhi(unsigned w) { return __uint_as_float(w & 0xffff0000u); }
; DI void phase_mlstm_scan(const Params& p) {
;     ...
;     for (int cb = 0; cb < 128; cb += 8) {
;       uint2 raw[8]; float kr[8];
; #pragma unroll
;       for (int j = 0; j < 8; ++j) { raw[j] = *(const uint2*)(kv + (size_t)(cb + j) * 16384); kr[j] = don ? ks[(cb + j) * 128] : 0.f; }
; #pragma unroll
;       for (int j = 0; j < 8; ++j) {
;         const float B = csc[(cb + j) * 4], A = csc[(cb + j) * 4 + 1];
;         const float mnew = fmaxf(B + m, A);
;         const float wp = __expf(B + m - mnew), wl = __expf(A - mnew);
;         m = mnew;
;         c0 = wp * c0 + wl * bflo(raw[j].x); c1 = wp * c1 + wl * bfhi(raw[j].x); c2 = wp * c2 + wl * bflo(raw[j].y); c3 = wp * c3 + wl * bfhi(raw[j].y);
;         uint2 o; o.x = pack2(c0, c1); o.y = pack2(c2, c3);
;         *(uint2*)(kv + (size_t)(cb + j) * 16384) = o;
;         if (don) { n = wp * n + wl * kr[j]; ks[(cb + j) * 128] = n; }
;         if (part == 0 && tid == 0) csc[(cb + j) * 4 + 2] = mnew;
;       }
;     }
	v_lshlrev_b32_e32 v50, 16, v110
	v_and_b32_e32 v51, 0xffff0000, v110
	v_lshlrev_b32_e32 v42, 16, v111
	v_and_b32_e32 v43, 0xffff0000, v111
	v_mov_b32_e32 v11, v137
	v_add_f32_e32 v36, s0, v46
	v_max_f32_e64 v37, s1, s1
	v_max_f32_e32 v47, v36, v37
	v_sub_f32_e32 v37, s1, v47
	v_sub_f32_e32 v36, v36, v47
	v_mul_f32_e32 v37, 0x3fb8aa3b, v37
	v_mul_f32_e32 v36, 0x3fb8aa3b, v36
	v_exp_f32_e32 v38, v37
	v_exp_f32_e32 v36, v36
	v_mov_b32_e32 v46, v47
	v_pk_mul_f32 v[50:51], v[38:39], v[50:51] op_sel_hi:[0,1]
	v_pk_mul_f32 v[42:43], v[38:39], v[42:43] op_sel_hi:[0,1]
	v_pk_fma_f32 v[32:33], v[32:33], v[36:37], v[50:51] op_sel_hi:[1,0,1]
	v_pk_fma_f32 v[40:41], v[40:41], v[36:37], v[42:43] op_sel_hi:[1,0,1]
	v_cvt_pk_bf16_f32 v30, v32, v33
	v_cvt_pk_bf16_f32 v31, v40, v41
	global_store_dwordx2 v1, v[30:31], s[8:9]
	v_mov_b32_e32 v37, v38
	v_pk_mul_f32 v[10:11], v[10:11], v[36:37]
	s_add_u32 s8, s8, 0x8000
	s_addc_u32 s9, s9, 0
	v_add_f32_e32 v10, v10, v11
	s_mov_b64 exec, s[16:17]
	global_store_dword v2, v10, s[12:13]
	s_mov_b64 exec, s[18:19]
	global_store_dword v0, v47, s[14:15] offset:1368
	s_mov_b64 exec, s[20:21]
	s_add_u32 s12, s12, 0x200
	s_addc_u32 s13, s13, 0
	global_load_dwordx2 v[110:111], v1, s[6:7]
	global_load_dword v137, v2, s[10:11]
	s_add_u32 s6, s6, 0x8000
	s_addc_u32 s7, s7, 0
	s_add_u32 s10, s10, 0x200
	s_addc_u32 s11, s11, 0
	v_readlane_b32 s0, v6, 22
	v_readlane_b32 s1, v7, 22
	s_waitcnt vmcnt(45)
	v_lshlrev_b32_e32 v50, 16, v112
	v_and_b32_e32 v51, 0xffff0000, v112
	v_lshlrev_b32_e32 v42, 16, v113
	v_and_b32_e32 v43, 0xffff0000, v113
	v_mov_b32_e32 v11, v138
	v_add_f32_e32 v36, s0, v46
	v_max_f32_e64 v37, s1, s1
	v_max_f32_e32 v47, v36, v37
	v_sub_f32_e32 v37, s1, v47
	v_sub_f32_e32 v36, v36, v47
	v_mul_f32_e32 v37, 0x3fb8aa3b, v37
	v_mul_f32_e32 v36, 0x3fb8aa3b, v36
	v_exp_f32_e32 v38, v37
	v_exp_f32_e32 v36, v36
	v_mov_b32_e32 v46, v47
	v_pk_mul_f32 v[50:51], v[38:39], v[50:51] op_sel_hi:[0,1]
	v_pk_mul_f32 v[42:43], v[38:39], v[42:43] op_sel_hi:[0,1]
	v_pk_fma_f32 v[32:33], v[32:33], v[36:37], v[50:51] op_sel_hi:[1,0,1]
	v_pk_fma_f32 v[40:41], v[40:41], v[36:37], v[42:43] op_sel_hi:[1,0,1]
	v_cvt_pk_bf16_f32 v30, v32, v33
	v_cvt_pk_bf16_f32 v31, v40, v41
	global_store_dwordx2 v1, v[30:31], s[8:9]
	v_mov_b32_e32 v37, v38
	v_pk_mul_f32 v[10:11], v[10:11], v[36:37]
	s_add_u32 s8, s8, 0x8000
	s_addc_u32 s9, s9, 0
	v_add_f32_e32 v10, v10, v11
	s_mov_b64 exec, s[16:17]
	global_store_dword v2, v10, s[12:13]
	s_mov_b64 exec, s[18:19]
	global_store_dword v0, v47, s[14:15] offset:1384
	s_mov_b64 exec, s[20:21]
	s_add_u32 s12, s12, 0x200
	s_addc_u32 s13, s13, 0
	global_load_dwordx2 v[112:113], v1, s[6:7]
	global_load_dword v138, v2, s[10:11]
	s_add_u32 s6, s6, 0x8000
	s_addc_u32 s7, s7, 0
	s_add_u32 s10, s10, 0x200
	s_addc_u32 s11, s11, 0
	v_readlane_b32 s0, v6, 23
	v_readlane_b32 s1, v7, 23
	s_waitcnt vmcnt(45)
	v_lshlrev_b32_e32 v50, 16, v114
	v_and_b32_e32 v51, 0xffff0000, v114
	v_lshlrev_b32_e32 v42, 16, v115
	v_and_b32_e32 v43, 0xffff0000, v115
	v_mov_b32_e32 v11, v139
	v_add_f32_e32 v36, s0, v46
	v_max_f32_e64 v37, s1, s1
	v_max_f32_e32 v47, v36, v37
	v_sub_f32_e32 v37, s1, v47
	v_sub_f32_e32 v36, v36, v47
	v_mul_f32_e32 v37, 0x3fb8aa3b, v37
	v_mul_f32_e32 v36, 0x3fb8aa3b, v36
	v_exp_f32_e32 v38, v37
	v_exp_f32_e32 v36, v36
	v_mov_b32_e32 v46, v47
	v_pk_mul_f32 v[50:51], v[38:39], v[50:51] op_sel_hi:[0,1]
	v_pk_mul_f32 v[42:43], v[38:39], v[42:43] op_sel_hi:[0,1]
	v_pk_fma_f32 v[32:33], v[32:33], v[36:37], v[50:51] op_sel_hi:[1,0,1]
	v_pk_fma_f32 v[40:41], v[40:41], v[36:37], v[42:43] op_sel_hi:[1,0,1]
	v_cvt_pk_bf16_f32 v30, v32, v33
	v_cvt_pk_bf16_f32 v31, v40, v41
	global_store_dwordx2 v1, v[30:31], s[8:9]
	v_mov_b32_e32 v37, v38
	v_pk_mul_f32 v[10:11], v[10:11], v[36:37]
	s_add_u32 s8, s8, 0x8000
	s_addc_u32 s9, s9, 0
	v_add_f32_e32 v10, v10, v11
	s_mov_b64 exec, s[16:17]
	global_store_dword v2, v10, s[12:13]
	s_mov_b64 exec, s[18:19]
	global_store_dword v0, v47, s[14:15] offset:1400
	s_mov_b64 exec, s[20:21]
	s_add_u32 s12, s12, 0x200
	s_addc_u32 s13, s13, 0
	global_load_dwordx2 v[114:115], v1, s[6:7]
	global_load_dword v139, v2, s[10:11]
	s_add_u32 s6, s6, 0x8000
	s_addc_u32 s7, s7, 0
	s_add_u32 s10, s10, 0x200
	s_addc_u32 s11, s11, 0
	v_readlane_b32 s0, v6, 24
	v_readlane_b32 s1, v7, 24
	s_waitcnt vmcnt(45)
	v_lshlrev_b32_e32 v50, 16, v116
	v_and_b32_e32 v51, 0xffff0000, v116
	v_lshlrev_b32_e32 v42, 16, v117
	v_and_b32_e32 v43, 0xffff0000, v117
	v_mov_b32_e32 v11, v140
	v_add_f32_e32 v36, s0, v46
	v_max_f32_e64 v37, s1, s1
	v_max_f32_e32 v47, v36, v37
	v_sub_f32_e32 v37, s1, v47
	v_sub_f32_e32 v36, v36, v47
	v_mul_f32_e32 v37, 0x3fb8aa3b, v37
	v_mul_f32_e32 v36, 0x3fb8aa3b, v36
	v_exp_f32_e32 v38, v37
	v_exp_f32_e32 v36, v36
	v_mov_b32_e32 v46, v47
	v_pk_mul_f32 v[50:51], v[38:39], v[50:51] op_sel_hi:[0,1]
	v_pk_mul_f32 v[42:43], v[38:39], v[42:43] op_sel_hi:[0,1]
	v_pk_fma_f32 v[32:33], v[32:33], v[36:37], v[50:51] op_sel_hi:[1,0,1]
	v_pk_fma_f32 v[40:41], v[40:41], v[36:37], v[42:43] op_sel_hi:[1,0,1]
	v_cvt_pk_bf16_f32 v30, v32, v33
	v_cvt_pk_bf16_f32 v31, v40, v41
	global_store_dwordx2 v1, v[30:31], s[8:9]
	v_mov_b32_e32 v37, v38
	v_pk_mul_f32 v[10:11], v[10:11], v[36:37]
	s_add_u32 s8, s8, 0x8000
	s_addc_u32 s9, s9, 0
	v_add_f32_e32 v10, v10, v11
	s_mov_b64 exec, s[16:17]
	global_store_dword v2, v10, s[12:13]
	s_mov_b64 exec, s[18:19]
	global_store_dword v0, v47, s[14:15] offset:1416
	s_mov_b64 exec, s[20:21]
	s_add_u32 s12, s12, 0x200
	s_addc_u32 s13, s13, 0
	global_load_dwordx2 v[116:117], v1, s[6:7]
	global_load_dword v140, v2, s[10:11]
	s_add_u32 s6, s6, 0x8000
	s_addc_u32 s7, s7, 0
	s_add_u32 s10, s10, 0x200
	s_addc_u32 s11, s11, 0
	v_readlane_b32 s0, v6, 25
	v_readlane_b32 s1, v7, 25
	s_waitcnt vmcnt(45)
; DI unsigned pack2(float a, float b) { const f32x2 v = {a, b}; return __builtin_bit_cast(unsigned, __builtin_convertvector(v, bf16v2)); }
; DI float bflo(unsigned w) { return __uint_as_float(w << 16); }
; DI float bfhi(unsigned w) { return __uint_as_float(w & 0xffff0000u); }
; DI void phase_mlstm_scan(const Params& p) {
;     ...
;       for (int j = 0; j < 8; ++j) { raw[j] = *(const uint2*)(kv + (size_t)(cb + j) * 16384); kr[j] = don ? ks[(cb + j) * 128] : 0.f; }
; #pragma unroll
;       for (int j = 0; j < 8; ++j) {
;         const float B = csc[(cb + j) * 4], A = csc[(cb + j) * 4 + 1];
;         const float mnew = fmaxf(B + m, A);
;         const float wp = __expf(B + m - mnew), wl = __expf(A - mnew);
;         m = mnew;
;         c0 = wp * c0 + wl * bflo(raw[j].x); c1 = wp * c1 + wl * bfhi(raw[j].x); c2 = wp * c2 + wl * bflo(raw[j].y); c3 = wp * c3 + wl * bfhi(raw[j].y);
;         uint2 o; o.x = pack2(c0, c1); o.y = pack2(c2, c3);
;         *(uint2*)(kv + (size_t)(cb + j) * 16384) = o;
;         if (don) { n = wp * n + wl * kr[j]; ks[(cb + j) * 128] = n; }
;         if (part == 0 && tid == 0) csc[(cb + j) * 4 + 2] = mnew;
	v_lshlrev_b32_e32 v50, 16, v118
	v_and_b32_e32 v51, 0xffff0000, v118
	v_lshlrev_b32_e32 v42, 16, v119
	v_and_b32_e32 v43, 0xffff0000, v119
	v_mov_b32_e32 v11, v141
	v_add_f32_e32 v36, s0, v46
	v_max_f32_e64 v37, s1, s1
	v_max_f32_e32 v47, v36, v37
	v_sub_f32_e32 v37, s1, v47
	v_sub_f32_e32 v36, v36, v47
	v_mul_f32_e32 v37, 0x3fb8aa3b, v37
	v_mul_f32_e32 v36, 0x3fb8aa3b, v36
	v_exp_f32_e32 v38, v37
	v_exp_f32_e32 v36, v36
	v_mov_b32_e32 v46, v47
	v_pk_mul_f32 v[50:51], v[38:39], v[50:51] op_sel_hi:[0,1]
	v_pk_mul_f32 v[42:43], v[38:39], v[42:43] op_sel_hi:[0,1]
	v_pk_fma_f32 v[32:33], v[32:33], v[36:37], v[50:51] op_sel_hi:[1,0,1]
	v_pk_fma_f32 v[40:41], v[40:41], v[36:37], v[42:43] op_sel_hi:[1,0,1]
	v_cvt_pk_bf16_f32 v30, v32, v33
	v_cvt_pk_bf16_f32 v31, v40, v41
	global_store_dwordx2 v1, v[30:31], s[8:9]
	v_mov_b32_e32 v37, v38
	v_pk_mul_f32 v[10:11], v[10:11], v[36:37]
	s_add_u32 s8, s8, 0x8000
	s_addc_u32 s9, s9, 0
	v_add_f32_e32 v10, v10, v11
	s_mov_b64 exec, s[16:17]
	global_store_dword v2, v10, s[12:13]
	s_mov_b64 exec, s[18:19]
	global_store_dword v0, v47, s[14:15] offset:1432
	s_mov_b64 exec, s[20:21]
	s_add_u32 s12, s12, 0x200
	s_addc_u32 s13, s13, 0
	global_load_dwordx2 v[118:119], v1, s[6:7]
	global_load_dword v141, v2, s[10:11]
	s_add_u32 s6, s6, 0x8000
	s_addc_u32 s7, s7, 0
	s_add_u32 s10, s10, 0x200
	s_addc_u32 s11, s11, 0
	v_readlane_b32 s0, v6, 26
	v_readlane_b32 s1, v7, 26
	s_waitcnt vmcnt(45)
	v_lshlrev_b32_e32 v50, 16, v120
	v_and_b32_e32 v51, 0xffff0000, v120
	v_lshlrev_b32_e32 v42, 16, v121
	v_and_b32_e32 v43, 0xffff0000, v121
	v_mov_b32_e32 v11, v142
	v_add_f32_e32 v36, s0, v46
	v_max_f32_e64 v37, s1, s1
	v_max_f32_e32 v47, v36, v37
	v_sub_f32_e32 v37, s1, v47
	v_sub_f32_e32 v36, v36, v47
	v_mul_f32_e32 v37, 0x3fb8aa3b, v37
	v_mul_f32_e32 v36, 0x3fb8aa3b, v36
	v_exp_f32_e32 v38, v37
	v_exp_f32_e32 v36, v36
	v_mov_b32_e32 v46, v47
	v_pk_mul_f32 v[50:51], v[38:39], v[50:51] op_sel_hi:[0,1]
	v_pk_mul_f32 v[42:43], v[38:39], v[42:43] op_sel_hi:[0,1]
	v_pk_fma_f32 v[32:33], v[32:33], v[36:37], v[50:51] op_sel_hi:[1,0,1]
	v_pk_fma_f32 v[40:41], v[40:41], v[36:37], v[42:43] op_sel_hi:[1,0,1]
	v_cvt_pk_bf16_f32 v30, v32, v33
	v_cvt_pk_bf16_f32 v31, v40, v41
	global_store_dwordx2 v1, v[30:31], s[8:9]
	v_mov_b32_e32 v37, v38
	v_pk_mul_f32 v[10:11], v[10:11], v[36:37]
	s_add_u32 s8, s8, 0x8000
	s_addc_u32 s9, s9, 0
	v_add_f32_e32 v10, v10, v11
	s_mov_b64 exec, s[16:17]
	global_store_dword v2, v10, s[12:13]
	s_mov_b64 exec, s[18:19]
	global_store_dword v0, v47, s[14:15] offset:1448
	s_mov_b64 exec, s[20:21]
	s_add_u32 s12, s12, 0x200
	s_addc_u32 s13, s13, 0
	global_load_dwordx2 v[120:121], v1, s[6:7]
	global_load_dword v142, v2, s[10:11]
	s_add_u32 s6, s6, 0x8000
	s_addc_u32 s7, s7, 0
	s_add_u32 s10, s10, 0x200
	s_addc_u32 s11, s11, 0
	v_readlane_b32 s0, v6, 27
	v_readlane_b32 s1, v7, 27
	s_waitcnt vmcnt(45)
	v_lshlrev_b32_e32 v50, 16, v122
	v_and_b32_e32 v51, 0xffff0000, v122
	v_lshlrev_b32_e32 v42, 16, v123
	v_and_b32_e32 v43, 0xffff0000, v123
	v_mov_b32_e32 v11, v143
	v_add_f32_e32 v36, s0, v46
	v_max_f32_e64 v37, s1, s1
	v_max_f32_e32 v47, v36, v37
	v_sub_f32_e32 v37, s1, v47
	v_sub_f32_e32 v36, v36, v47
	v_mul_f32_e32 v37, 0x3fb8aa3b, v37
	v_mul_f32_e32 v36, 0x3fb8aa3b, v36
	v_exp_f32_e32 v38, v37
	v_exp_f32_e32 v36, v36
	v_mov_b32_e32 v46, v47
	v_pk_mul_f32 v[50:51], v[38:39], v[50:51] op_sel_hi:[0,1]
	v_pk_mul_f32 v[42:43], v[38:39], v[42:43] op_sel_hi:[0,1]
	v_pk_fma_f32 v[32:33], v[32:33], v[36:37], v[50:51] op_sel_hi:[1,0,1]
	v_pk_fma_f32 v[40:41], v[40:41], v[36:37], v[42:43] op_sel_hi:[1,0,1]
	v_cvt_pk_bf16_f32 v30, v32, v33
	v_cvt_pk_bf16_f32 v31, v40, v41
	global_store_dwordx2 v1, v[30:31], s[8:9]
	v_mov_b32_e32 v37, v38
	v_pk_mul_f32 v[10:11], v[10:11], v[36:37]
	s_add_u32 s8, s8, 0x8000
	s_addc_u32 s9, s9, 0
	v_add_f32_e32 v10, v10, v11
	s_mov_b64 exec, s[16:17]
	global_store_dword v2, v10, s[12:13]
	s_mov_b64 exec, s[18:19]
	global_store_dword v0, v47, s[14:15] offset:1464
	s_mov_b64 exec, s[20:21]
	s_add_u32 s12, s12, 0x200
	s_addc_u32 s13, s13, 0
	global_load_dwordx2 v[122:123], v1, s[6:7]
	global_load_dword v143, v2, s[10:11]
	s_add_u32 s6, s6, 0x8000
	s_addc_u32 s7, s7, 0
	s_add_u32 s10, s10, 0x200
	s_addc_u32 s11, s11, 0
	v_readlane_b32 s0, v6, 28
	v_readlane_b32 s1, v7, 28
	s_waitcnt vmcnt(45)
	v_lshlrev_b32_e32 v50, 16, v124
	v_and_b32_e32 v51, 0xffff0000, v124
	v_lshlrev_b32_e32 v42, 16, v125
	v_and_b32_e32 v43, 0xffff0000, v125
	v_mov_b32_e32 v11, v144
	v_add_f32_e32 v36, s0, v46
	v_max_f32_e64 v37, s1, s1
	v_max_f32_e32 v47, v36, v37
	v_sub_f32_e32 v37, s1, v47
	v_sub_f32_e32 v36, v36, v47
	v_mul_f32_e32 v37, 0x3fb8aa3b, v37
	v_mul_f32_e32 v36, 0x3fb8aa3b, v36
	v_exp_f32_e32 v38, v37
	v_exp_f32_e32 v36, v36
	v_mov_b32_e32 v46, v47
	v_pk_mul_f32 v[50:51], v[38:39], v[50:51] op_sel_hi:[0,1]
	v_pk_mul_f32 v[42:43], v[38:39], v[42:43] op_sel_hi:[0,1]
	v_pk_fma_f32 v[32:33], v[32:33], v[36:37], v[50:51] op_sel_hi:[1,0,1]
	v_pk_fma_f32 v[40:41], v[40:41], v[36:37], v[42:43] op_sel_hi:[1,0,1]
	v_cvt_pk_bf16_f32 v30, v32, v33
	v_cvt_pk_bf16_f32 v31, v40, v41
	global_store_dwordx2 v1, v[30:31], s[8:9]
	v_mov_b32_e32 v37, v38
	v_pk_mul_f32 v[10:11], v[10:11], v[36:37]
	s_add_u32 s8, s8, 0x8000
	s_addc_u32 s9, s9, 0
	v_add_f32_e32 v10, v10, v11
	s_mov_b64 exec, s[16:17]
	global_store_dword v2, v10, s[12:13]
	s_mov_b64 exec, s[18:19]
	global_store_dword v0, v47, s[14:15] offset:1480
	s_mov_b64 exec, s[20:21]
	s_add_u32 s12, s12, 0x200
	s_addc_u32 s13, s13, 0
	global_load_dwordx2 v[124:125], v1, s[6:7]
	global_load_dword v144, v2, s[10:11]
	s_add_u32 s6, s6, 0x8000
	s_addc_u32 s7, s7, 0
	s_add_u32 s10, s10, 0x200
	s_addc_u32 s11, s11, 0
	v_readlane_b32 s0, v6, 29
	v_readlane_b32 s1, v7, 29
	s_waitcnt vmcnt(45)
; DI unsigned pack2(float a, float b) { const f32x2 v = {a, b}; return __builtin_bit_cast(unsigned, __builtin_convertvector(v, bf16v2)); }
; DI float bflo(unsigned w) { return __uint_as_float(w << 16); }
; DI float bfhi(unsigned w) { return __uint_as_float(w & 0xffff0000u); }
; DI void phase_mlstm_scan(const Params& p) {
;     ...
;     for (int cb = 0; cb < 128; cb += 8) {
;       uint2 raw[8]; float kr[8];
; #pragma unroll
;       for (int j = 0; j < 8; ++j) { raw[j] = *(const uint2*)(kv + (size_t)(cb + j) * 16384); kr[j] = don ? ks[(cb + j) * 128] : 0.f; }
; #pragma unroll
;       for (int j = 0; j < 8; ++j) {
;         const float B = csc[(cb + j) * 4], A = csc[(cb + j) * 4 + 1];
;         const float mnew = fmaxf(B + m, A);
;         const float wp = __expf(B + m - mnew), wl = __expf(A - mnew);
;         m = mnew;
;         c0 = wp * c0 + wl * bflo(raw[j].x); c1 = wp * c1 + wl * bfhi(raw[j].x); c2 = wp * c2 + wl * bflo(raw[j].y); c3 = wp * c3 + wl * bfhi(raw[j].y);
;         uint2 o; o.x = pack2(c0, c1); o.y = pack2(c2, c3);
;         *(uint2*)(kv + (size_t)(cb + j) * 16384) = o;
;         if (don) { n = wp * n + wl * kr[j]; ks[(cb + j) * 128] = n; }
;         if (part == 0 && tid == 0) csc[(cb + j) * 4 + 2] = mnew;
;       }
;     }
	v_lshlrev_b32_e32 v50, 16, v126
	v_and_b32_e32 v51, 0xffff0000, v126
	v_lshlrev_b32_e32 v42, 16, v127
	v_and_b32_e32 v43, 0xffff0000, v127
	v_mov_b32_e32 v11, v145
	v_add_f32_e32 v36, s0, v46
	v_max_f32_e64 v37, s1, s1
	v_max_f32_e32 v47, v36, v37
	v_sub_f32_e32 v37, s1, v47
	v_sub_f32_e32 v36, v36, v47
	v_mul_f32_e32 v37, 0x3fb8aa3b, v37
	v_mul_f32_e32 v36, 0x3fb8aa3b, v36
	v_exp_f32_e32 v38, v37
	v_exp_f32_e32 v36, v36
	v_mov_b32_e32 v46, v47
	v_pk_mul_f32 v[50:51], v[38:39], v[50:51] op_sel_hi:[0,1]
	v_pk_mul_f32 v[42:43], v[38:39], v[42:43] op_sel_hi:[0,1]
	v_pk_fma_f32 v[32:33], v[32:33], v[36:37], v[50:51] op_sel_hi:[1,0,1]
	v_pk_fma_f32 v[40:41], v[40:41], v[36:37], v[42:43] op_sel_hi:[1,0,1]
	v_cvt_pk_bf16_f32 v30, v32, v33
	v_cvt_pk_bf16_f32 v31, v40, v41
	global_store_dwordx2 v1, v[30:31], s[8:9]
	v_mov_b32_e32 v37, v38
	v_pk_mul_f32 v[10:11], v[10:11], v[36:37]
	s_add_u32 s8, s8, 0x8000
	s_addc_u32 s9, s9, 0
	v_add_f32_e32 v10, v10, v11
	s_mov_b64 exec, s[16:17]
	global_store_dword v2, v10, s[12:13]
	s_mov_b64 exec, s[18:19]
	global_store_dword v0, v47, s[14:15] offset:1496
	s_mov_b64 exec, s[20:21]
	s_add_u32 s12, s12, 0x200
	s_addc_u32 s13, s13, 0
	global_load_dwordx2 v[126:127], v1, s[6:7]
	global_load_dword v145, v2, s[10:11]
	s_add_u32 s6, s6, 0x8000
	s_addc_u32 s7, s7, 0
	s_add_u32 s10, s10, 0x200
	s_addc_u32 s11, s11, 0
	v_readlane_b32 s0, v6, 30
	v_readlane_b32 s1, v7, 30
	s_waitcnt vmcnt(45)
	v_lshlrev_b32_e32 v50, 16, v128
	v_and_b32_e32 v51, 0xffff0000, v128
	v_lshlrev_b32_e32 v42, 16, v129
	v_and_b32_e32 v43, 0xffff0000, v129
	v_mov_b32_e32 v11, v146
	v_add_f32_e32 v36, s0, v46
	v_max_f32_e64 v37, s1, s1
	v_max_f32_e32 v47, v36, v37
	v_sub_f32_e32 v37, s1, v47
	v_sub_f32_e32 v36, v36, v47
	v_mul_f32_e32 v37, 0x3fb8aa3b, v37
	v_mul_f32_e32 v36, 0x3fb8aa3b, v36
	v_exp_f32_e32 v38, v37
	v_exp_f32_e32 v36, v36
	v_mov_b32_e32 v46, v47
	v_pk_mul_f32 v[50:51], v[38:39], v[50:51] op_sel_hi:[0,1]
	v_pk_mul_f32 v[42:43], v[38:39], v[42:43] op_sel_hi:[0,1]
	v_pk_fma_f32 v[32:33], v[32:33], v[36:37], v[50:51] op_sel_hi:[1,0,1]
	v_pk_fma_f32 v[40:41], v[40:41], v[36:37], v[42:43] op_sel_hi:[1,0,1]
	v_cvt_pk_bf16_f32 v30, v32, v33
	v_cvt_pk_bf16_f32 v31, v40, v41
	global_store_dwordx2 v1, v[30:31], s[8:9]
	v_mov_b32_e32 v37, v38
	v_pk_mul_f32 v[10:11], v[10:11], v[36:37]
	s_add_u32 s8, s8, 0x8000
	s_addc_u32 s9, s9, 0
	v_add_f32_e32 v10, v10, v11
	s_mov_b64 exec, s[16:17]
	global_store_dword v2, v10, s[12:13]
	s_mov_b64 exec, s[18:19]
	global_store_dword v0, v47, s[14:15] offset:1512
	s_mov_b64 exec, s[20:21]
	s_add_u32 s12, s12, 0x200
	s_addc_u32 s13, s13, 0
	global_load_dwordx2 v[128:129], v1, s[6:7]
	global_load_dword v146, v2, s[10:11]
	s_add_u32 s6, s6, 0x8000
	s_addc_u32 s7, s7, 0
	s_add_u32 s10, s10, 0x200
	s_addc_u32 s11, s11, 0
	v_readlane_b32 s0, v6, 31
	v_readlane_b32 s1, v7, 31
	s_waitcnt vmcnt(45)
	v_lshlrev_b32_e32 v50, 16, v130
	v_and_b32_e32 v51, 0xffff0000, v130
	v_lshlrev_b32_e32 v42, 16, v131
	v_and_b32_e32 v43, 0xffff0000, v131
	v_mov_b32_e32 v11, v147
	v_add_f32_e32 v36, s0, v46
	v_max_f32_e64 v37, s1, s1
	v_max_f32_e32 v47, v36, v37
	v_sub_f32_e32 v37, s1, v47
	v_sub_f32_e32 v36, v36, v47
	v_mul_f32_e32 v37, 0x3fb8aa3b, v37
	v_mul_f32_e32 v36, 0x3fb8aa3b, v36
	v_exp_f32_e32 v38, v37
	v_exp_f32_e32 v36, v36
	v_mov_b32_e32 v46, v47
	v_pk_mul_f32 v[50:51], v[38:39], v[50:51] op_sel_hi:[0,1]
	v_pk_mul_f32 v[42:43], v[38:39], v[42:43] op_sel_hi:[0,1]
	v_pk_fma_f32 v[32:33], v[32:33], v[36:37], v[50:51] op_sel_hi:[1,0,1]
	v_pk_fma_f32 v[40:41], v[40:41], v[36:37], v[42:43] op_sel_hi:[1,0,1]
	v_cvt_pk_bf16_f32 v30, v32, v33
	v_cvt_pk_bf16_f32 v31, v40, v41
	global_store_dwordx2 v1, v[30:31], s[8:9]
	v_mov_b32_e32 v37, v38
	v_pk_mul_f32 v[10:11], v[10:11], v[36:37]
	s_add_u32 s8, s8, 0x8000
	s_addc_u32 s9, s9, 0
	v_add_f32_e32 v10, v10, v11
	s_mov_b64 exec, s[16:17]
	global_store_dword v2, v10, s[12:13]
	s_mov_b64 exec, s[18:19]
	global_store_dword v0, v47, s[14:15] offset:1528
	s_mov_b64 exec, s[20:21]
	s_add_u32 s12, s12, 0x200
	s_addc_u32 s13, s13, 0
	global_load_dwordx2 v[130:131], v1, s[6:7]
	global_load_dword v147, v2, s[10:11]
	s_add_u32 s6, s6, 0x8000
	s_addc_u32 s7, s7, 0
	s_add_u32 s10, s10, 0x200
	s_addc_u32 s11, s11, 0
	v_readlane_b32 s0, v6, 32
	v_readlane_b32 s1, v7, 32
	s_waitcnt vmcnt(45)
	v_lshlrev_b32_e32 v50, 16, v100
	v_and_b32_e32 v51, 0xffff0000, v100
	v_lshlrev_b32_e32 v42, 16, v101
	v_and_b32_e32 v43, 0xffff0000, v101
	v_mov_b32_e32 v11, v132
	v_add_f32_e32 v36, s0, v46
	v_max_f32_e64 v37, s1, s1
	v_max_f32_e32 v47, v36, v37
	v_sub_f32_e32 v37, s1, v47
	v_sub_f32_e32 v36, v36, v47
	v_mul_f32_e32 v37, 0x3fb8aa3b, v37
	v_mul_f32_e32 v36, 0x3fb8aa3b, v36
	v_exp_f32_e32 v38, v37
	v_exp_f32_e32 v36, v36
	v_mov_b32_e32 v46, v47
	v_pk_mul_f32 v[50:51], v[38:39], v[50:51] op_sel_hi:[0,1]
	v_pk_mul_f32 v[42:43], v[38:39], v[42:43] op_sel_hi:[0,1]
	v_pk_fma_f32 v[32:33], v[32:33], v[36:37], v[50:51] op_sel_hi:[1,0,1]
	v_pk_fma_f32 v[40:41], v[40:41], v[36:37], v[42:43] op_sel_hi:[1,0,1]
	v_cvt_pk_bf16_f32 v30, v32, v33
	v_cvt_pk_bf16_f32 v31, v40, v41
	global_store_dwordx2 v1, v[30:31], s[8:9]
	v_mov_b32_e32 v37, v38
	v_pk_mul_f32 v[10:11], v[10:11], v[36:37]
	s_add_u32 s8, s8, 0x8000
	s_addc_u32 s9, s9, 0
	v_add_f32_e32 v10, v10, v11
	s_mov_b64 exec, s[16:17]
	global_store_dword v2, v10, s[12:13]
	s_mov_b64 exec, s[18:19]
	global_store_dword v0, v47, s[14:15] offset:1544
	s_mov_b64 exec, s[20:21]
	s_add_u32 s12, s12, 0x200
	s_addc_u32 s13, s13, 0
	global_load_dwordx2 v[100:101], v1, s[6:7]
	global_load_dword v132, v2, s[10:11]
	s_add_u32 s6, s6, 0x8000
	s_addc_u32 s7, s7, 0
	s_add_u32 s10, s10, 0x200
	s_addc_u32 s11, s11, 0
	v_readlane_b32 s0, v6, 33
	v_readlane_b32 s1, v7, 33
	s_waitcnt vmcnt(45)
; DI unsigned pack2(float a, float b) { const f32x2 v = {a, b}; return __builtin_bit_cast(unsigned, __builtin_convertvector(v, bf16v2)); }
; DI float bflo(unsigned w) { return __uint_as_float(w << 16); }
; DI float bfhi(unsigned w) { return __uint_as_float(w & 0xffff0000u); }
; DI void phase_mlstm_scan(const Params& p) {
;     ...
;     for (int cb = 0; cb < 128; cb += 8) {
;       uint2 raw[8]; float kr[8];
; #pragma unroll
;       for (int j = 0; j < 8; ++j) { raw[j] = *(const uint2*)(kv + (size_t)(cb + j) * 16384); kr[j] = don ? ks[(cb + j) * 128] : 0.f; }
; #pragma unroll
;       for (int j = 0; j < 8; ++j) {
;         const float B = csc[(cb + j) * 4], A = csc[(cb + j) * 4 + 1];
;         const float mnew = fmaxf(B + m, A);
;         const float wp = __expf(B + m - mnew), wl = __expf(A - mnew);
;         m = mnew;
;         c0 = wp * c0 + wl * bflo(raw[j].x); c1 = wp * c1 + wl * bfhi(raw[j].x); c2 = wp * c2 + wl * bflo(raw[j].y); c3 = wp * c3 + wl * bfhi(raw[j].y);
;         uint2 o; o.x = pack2(c0, c1); o.y = pack2(c2, c3);
;         *(uint2*)(kv + (size_t)(cb + j) * 16384) = o;
;         if (don) { n = wp * n + wl * kr[j]; ks[(cb + j) * 128] = n; }
;         if (part == 0 && tid == 0) csc[(cb + j) * 4 + 2] = mnew;
;       }
;     }
	v_lshlrev_b32_e32 v50, 16, v102
	v_and_b32_e32 v51, 0xffff0000, v102
	v_lshlrev_b32_e32 v42, 16, v103
	v_and_b32_e32 v43, 0xffff0000, v103
	v_mov_b32_e32 v11, v133
	v_add_f32_e32 v36, s0, v46
	v_max_f32_e64 v37, s1, s1
	v_max_f32_e32 v47, v36, v37
	v_sub_f32_e32 v37, s1, v47
	v_sub_f32_e32 v36, v36, v47
	v_mul_f32_e32 v37, 0x3fb8aa3b, v37
	v_mul_f32_e32 v36, 0x3fb8aa3b, v36
	v_exp_f32_e32 v38, v37
	v_exp_f32_e32 v36, v36
	v_mov_b32_e32 v46, v47
	v_pk_mul_f32 v[50:51], v[38:39], v[50:51] op_sel_hi:[0,1]
	v_pk_mul_f32 v[42:43], v[38:39], v[42:43] op_sel_hi:[0,1]
	v_pk_fma_f32 v[32:33], v[32:33], v[36:37], v[50:51] op_sel_hi:[1,0,1]
	v_pk_fma_f32 v[40:41], v[40:41], v[36:37], v[42:43] op_sel_hi:[1,0,1]
	v_cvt_pk_bf16_f32 v30, v32, v33
	v_cvt_pk_bf16_f32 v31, v40, v41
	global_store_dwordx2 v1, v[30:31], s[8:9]
	v_mov_b32_e32 v37, v38
	v_pk_mul_f32 v[10:11], v[10:11], v[36:37]
	s_add_u32 s8, s8, 0x8000
	s_addc_u32 s9, s9, 0
	v_add_f32_e32 v10, v10, v11
	s_mov_b64 exec, s[16:17]
	global_store_dword v2, v10, s[12:13]
	s_mov_b64 exec, s[18:19]
	global_store_dword v0, v47, s[14:15] offset:1560
	s_mov_b64 exec, s[20:21]
	s_add_u32 s12, s12, 0x200
	s_addc_u32 s13, s13, 0
	global_load_dwordx2 v[102:103], v1, s[6:7]
	global_load_dword v133, v2, s[10:11]
	s_add_u32 s6, s6, 0x8000
	s_addc_u32 s7, s7, 0
	s_add_u32 s10, s10, 0x200
	s_addc_u32 s11, s11, 0
	v_readlane_b32 s0, v6, 34
	v_readlane_b32 s1, v7, 34
	s_waitcnt vmcnt(45)
	v_lshlrev_b32_e32 v50, 16, v104
	v_and_b32_e32 v51, 0xffff0000, v104
	v_lshlrev_b32_e32 v42, 16, v105
	v_and_b32_e32 v43, 0xffff0000, v105
	v_mov_b32_e32 v11, v134
	v_add_f32_e32 v36, s0, v46
	v_max_f32_e64 v37, s1, s1
	v_max_f32_e32 v47, v36, v37
	v_sub_f32_e32 v37, s1, v47
	v_sub_f32_e32 v36, v36, v47
	v_mul_f32_e32 v37, 0x3fb8aa3b, v37
	v_mul_f32_e32 v36, 0x3fb8aa3b, v36
	v_exp_f32_e32 v38, v37
	v_exp_f32_e32 v36, v36
	v_mov_b32_e32 v46, v47
	v_pk_mul_f32 v[50:51], v[38:39], v[50:51] op_sel_hi:[0,1]
	v_pk_mul_f32 v[42:43], v[38:39], v[42:43] op_sel_hi:[0,1]
	v_pk_fma_f32 v[32:33], v[32:33], v[36:37], v[50:51] op_sel_hi:[1,0,1]
	v_pk_fma_f32 v[40:41], v[40:41], v[36:37], v[42:43] op_sel_hi:[1,0,1]
	v_cvt_pk_bf16_f32 v30, v32, v33
	v_cvt_pk_bf16_f32 v31, v40, v41
	global_store_dwordx2 v1, v[30:31], s[8:9]
	v_mov_b32_e32 v37, v38
	v_pk_mul_f32 v[10:11], v[10:11], v[36:37]
	s_add_u32 s8, s8, 0x8000
	s_addc_u32 s9, s9, 0
	v_add_f32_e32 v10, v10, v11
	s_mov_b64 exec, s[16:17]
	global_store_dword v2, v10, s[12:13]
	s_mov_b64 exec, s[18:19]
	global_store_dword v0, v47, s[14:15] offset:1576
	s_mov_b64 exec, s[20:21]
	s_add_u32 s12, s12, 0x200
	s_addc_u32 s13, s13, 0
	global_load_dwordx2 v[104:105], v1, s[6:7]
	global_load_dword v134, v2, s[10:11]
	s_add_u32 s6, s6, 0x8000
	s_addc_u32 s7, s7, 0
	s_add_u32 s10, s10, 0x200
	s_addc_u32 s11, s11, 0
	v_readlane_b32 s0, v6, 35
	v_readlane_b32 s1, v7, 35
	s_waitcnt vmcnt(45)
	v_lshlrev_b32_e32 v50, 16, v106
	v_and_b32_e32 v51, 0xffff0000, v106
	v_lshlrev_b32_e32 v42, 16, v107
	v_and_b32_e32 v43, 0xffff0000, v107
	v_mov_b32_e32 v11, v135
	v_add_f32_e32 v36, s0, v46
	v_max_f32_e64 v37, s1, s1
	v_max_f32_e32 v47, v36, v37
	v_sub_f32_e32 v37, s1, v47
	v_sub_f32_e32 v36, v36, v47
	v_mul_f32_e32 v37, 0x3fb8aa3b, v37
	v_mul_f32_e32 v36, 0x3fb8aa3b, v36
	v_exp_f32_e32 v38, v37
	v_exp_f32_e32 v36, v36
	v_mov_b32_e32 v46, v47
	v_pk_mul_f32 v[50:51], v[38:39], v[50:51] op_sel_hi:[0,1]
	v_pk_mul_f32 v[42:43], v[38:39], v[42:43] op_sel_hi:[0,1]
	v_pk_fma_f32 v[32:33], v[32:33], v[36:37], v[50:51] op_sel_hi:[1,0,1]
	v_pk_fma_f32 v[40:41], v[40:41], v[36:37], v[42:43] op_sel_hi:[1,0,1]
	v_cvt_pk_bf16_f32 v30, v32, v33
	v_cvt_pk_bf16_f32 v31, v40, v41
	global_store_dwordx2 v1, v[30:31], s[8:9]
	v_mov_b32_e32 v37, v38
	v_pk_mul_f32 v[10:11], v[10:11], v[36:37]
	s_add_u32 s8, s8, 0x8000
	s_addc_u32 s9, s9, 0
	v_add_f32_e32 v10, v10, v11
	s_mov_b64 exec, s[16:17]
	global_store_dword v2, v10, s[12:13]
	s_mov_b64 exec, s[18:19]
	global_store_dword v0, v47, s[14:15] offset:1592
	s_mov_b64 exec, s[20:21]
	s_add_u32 s12, s12, 0x200
	s_addc_u32 s13, s13, 0
	global_load_dwordx2 v[106:107], v1, s[6:7]
	global_load_dword v135, v2, s[10:11]
	s_add_u32 s6, s6, 0x8000
	s_addc_u32 s7, s7, 0
	s_add_u32 s10, s10, 0x200
	s_addc_u32 s11, s11, 0
	v_readlane_b32 s0, v6, 36
	v_readlane_b32 s1, v7, 36
	s_waitcnt vmcnt(45)
	v_lshlrev_b32_e32 v50, 16, v108
	v_and_b32_e32 v51, 0xffff0000, v108
	v_lshlrev_b32_e32 v42, 16, v109
	v_and_b32_e32 v43, 0xffff0000, v109
	v_mov_b32_e32 v11, v136
	v_add_f32_e32 v36, s0, v46
	v_max_f32_e64 v37, s1, s1
	v_max_f32_e32 v47, v36, v37
	v_sub_f32_e32 v37, s1, v47
	v_sub_f32_e32 v36, v36, v47
	v_mul_f32_e32 v37, 0x3fb8aa3b, v37
	v_mul_f32_e32 v36, 0x3fb8aa3b, v36
	v_exp_f32_e32 v38, v37
	v_exp_f32_e32 v36, v36
	v_mov_b32_e32 v46, v47
	v_pk_mul_f32 v[50:51], v[38:39], v[50:51] op_sel_hi:[0,1]
	v_pk_mul_f32 v[42:43], v[38:39], v[42:43] op_sel_hi:[0,1]
	v_pk_fma_f32 v[32:33], v[32:33], v[36:37], v[50:51] op_sel_hi:[1,0,1]
	v_pk_fma_f32 v[40:41], v[40:41], v[36:37], v[42:43] op_sel_hi:[1,0,1]
	v_cvt_pk_bf16_f32 v30, v32, v33
	v_cvt_pk_bf16_f32 v31, v40, v41
	global_store_dwordx2 v1, v[30:31], s[8:9]
	v_mov_b32_e32 v37, v38
	v_pk_mul_f32 v[10:11], v[10:11], v[36:37]
	s_add_u32 s8, s8, 0x8000
	s_addc_u32 s9, s9, 0
	v_add_f32_e32 v10, v10, v11
	s_mov_b64 exec, s[16:17]
	global_store_dword v2, v10, s[12:13]
	s_mov_b64 exec, s[18:19]
	global_store_dword v0, v47, s[14:15] offset:1608
	s_mov_b64 exec, s[20:21]
	s_add_u32 s12, s12, 0x200
	s_addc_u32 s13, s13, 0
	global_load_dwordx2 v[108:109], v1, s[6:7]
	global_load_dword v136, v2, s[10:11]
	s_add_u32 s6, s6, 0x8000
	s_addc_u32 s7, s7, 0
	s_add_u32 s10, s10, 0x200
	s_addc_u32 s11, s11, 0
	v_readlane_b32 s0, v6, 37
	v_readlane_b32 s1, v7, 37
	s_waitcnt vmcnt(45)
; DI unsigned pack2(float a, float b) { const f32x2 v = {a, b}; return __builtin_bit_cast(unsigned, __builtin_convertvector(v, bf16v2)); }
; DI float bflo(unsigned w) { return __uint_as_float(w << 16); }
; DI float bfhi(unsigned w) { return __uint_as_float(w & 0xffff0000u); }
; DI void phase_mlstm_scan(const Params& p) {
;     ...
;     for (int cb = 0; cb < 128; cb += 8) {
;       uint2 raw[8]; float kr[8];
; #pragma unroll
;       for (int j = 0; j < 8; ++j) { raw[j] = *(const uint2*)(kv + (size_t)(cb + j) * 16384); kr[j] = don ? ks[(cb + j) * 128] : 0.f; }
; #pragma unroll
;       for (int j = 0; j < 8; ++j) {
;         const float B = csc[(cb + j) * 4], A = csc[(cb + j) * 4 + 1];
;         const float mnew = fmaxf(B + m, A);
;         const float wp = __expf(B + m - mnew), wl = __expf(A - mnew);
;         m = mnew;
;         c0 = wp * c0 + wl * bflo(raw[j].x); c1 = wp * c1 + wl * bfhi(raw[j].x); c2 = wp * c2 + wl * bflo(raw[j].y); c3 = wp * c3 + wl * bfhi(raw[j].y);
;         uint2 o; o.x = pack2(c0, c1); o.y = pack2(c2, c3);
;         *(uint2*)(kv + (size_t)(cb + j) * 16384) = o;
;         if (don) { n = wp * n + wl * kr[j]; ks[(cb + j) * 128] = n; }
;         if (part == 0 && tid == 0) csc[(cb + j) * 4 + 2] = mnew;
;       }
;     }
	v_lshlrev_b32_e32 v50, 16, v110
	v_and_b32_e32 v51, 0xffff0000, v110
	v_lshlrev_b32_e32 v42, 16, v111
	v_and_b32_e32 v43, 0xffff0000, v111
	v_mov_b32_e32 v11, v137
	v_add_f32_e32 v36, s0, v46
	v_max_f32_e64 v37, s1, s1
	v_max_f32_e32 v47, v36, v37
	v_sub_f32_e32 v37, s1, v47
	v_sub_f32_e32 v36, v36, v47
	v_mul_f32_e32 v37, 0x3fb8aa3b, v37
	v_mul_f32_e32 v36, 0x3fb8aa3b, v36
	v_exp_f32_e32 v38, v37
	v_exp_f32_e32 v36, v36
	v_mov_b32_e32 v46, v47
	v_pk_mul_f32 v[50:51], v[38:39], v[50:51] op_sel_hi:[0,1]
	v_pk_mul_f32 v[42:43], v[38:39], v[42:43] op_sel_hi:[0,1]
	v_pk_fma_f32 v[32:33], v[32:33], v[36:37], v[50:51] op_sel_hi:[1,0,1]
	v_pk_fma_f32 v[40:41], v[40:41], v[36:37], v[42:43] op_sel_hi:[1,0,1]
	v_cvt_pk_bf16_f32 v30, v32, v33
	v_cvt_pk_bf16_f32 v31, v40, v41
	global_store_dwordx2 v1, v[30:31], s[8:9]
	v_mov_b32_e32 v37, v38
	v_pk_mul_f32 v[10:11], v[10:11], v[36:37]
	s_add_u32 s8, s8, 0x8000
	s_addc_u32 s9, s9, 0
	v_add_f32_e32 v10, v10, v11
	s_mov_b64 exec, s[16:17]
	global_store_dword v2, v10, s[12:13]
	s_mov_b64 exec, s[18:19]
	global_store_dword v0, v47, s[14:15] offset:1624
	s_mov_b64 exec, s[20:21]
	s_add_u32 s12, s12, 0x200
	s_addc_u32 s13, s13, 0
	global_load_dwordx2 v[110:111], v1, s[6:7]
	global_load_dword v137, v2, s[10:11]
	s_add_u32 s6, s6, 0x8000
	s_addc_u32 s7, s7, 0
	s_add_u32 s10, s10, 0x200
	s_addc_u32 s11, s11, 0
	v_readlane_b32 s0, v6, 38
	v_readlane_b32 s1, v7, 38
	s_waitcnt vmcnt(45)
	v_lshlrev_b32_e32 v50, 16, v112
	v_and_b32_e32 v51, 0xffff0000, v112
	v_lshlrev_b32_e32 v42, 16, v113
	v_and_b32_e32 v43, 0xffff0000, v113
	v_mov_b32_e32 v11, v138
	v_add_f32_e32 v36, s0, v46
	v_max_f32_e64 v37, s1, s1
	v_max_f32_e32 v47, v36, v37
	v_sub_f32_e32 v37, s1, v47
	v_sub_f32_e32 v36, v36, v47
	v_mul_f32_e32 v37, 0x3fb8aa3b, v37
	v_mul_f32_e32 v36, 0x3fb8aa3b, v36
	v_exp_f32_e32 v38, v37
	v_exp_f32_e32 v36, v36
	v_mov_b32_e32 v46, v47
	v_pk_mul_f32 v[50:51], v[38:39], v[50:51] op_sel_hi:[0,1]
	v_pk_mul_f32 v[42:43], v[38:39], v[42:43] op_sel_hi:[0,1]
	v_pk_fma_f32 v[32:33], v[32:33], v[36:37], v[50:51] op_sel_hi:[1,0,1]
	v_pk_fma_f32 v[40:41], v[40:41], v[36:37], v[42:43] op_sel_hi:[1,0,1]
	v_cvt_pk_bf16_f32 v30, v32, v33
	v_cvt_pk_bf16_f32 v31, v40, v41
	global_store_dwordx2 v1, v[30:31], s[8:9]
	v_mov_b32_e32 v37, v38
	v_pk_mul_f32 v[10:11], v[10:11], v[36:37]
	s_add_u32 s8, s8, 0x8000
	s_addc_u32 s9, s9, 0
	v_add_f32_e32 v10, v10, v11
	s_mov_b64 exec, s[16:17]
	global_store_dword v2, v10, s[12:13]
	s_mov_b64 exec, s[18:19]
	global_store_dword v0, v47, s[14:15] offset:1640
	s_mov_b64 exec, s[20:21]
	s_add_u32 s12, s12, 0x200
	s_addc_u32 s13, s13, 0
	global_load_dwordx2 v[112:113], v1, s[6:7]
	global_load_dword v138, v2, s[10:11]
	s_add_u32 s6, s6, 0x8000
	s_addc_u32 s7, s7, 0
	s_add_u32 s10, s10, 0x200
	s_addc_u32 s11, s11, 0
	v_readlane_b32 s0, v6, 39
	v_readlane_b32 s1, v7, 39
	s_waitcnt vmcnt(45)
	v_lshlrev_b32_e32 v50, 16, v114
	v_and_b32_e32 v51, 0xffff0000, v114
	v_lshlrev_b32_e32 v42, 16, v115
	v_and_b32_e32 v43, 0xffff0000, v115
	v_mov_b32_e32 v11, v139
	v_add_f32_e32 v36, s0, v46
	v_max_f32_e64 v37, s1, s1
	v_max_f32_e32 v47, v36, v37
	v_sub_f32_e32 v37, s1, v47
	v_sub_f32_e32 v36, v36, v47
	v_mul_f32_e32 v37, 0x3fb8aa3b, v37
	v_mul_f32_e32 v36, 0x3fb8aa3b, v36
	v_exp_f32_e32 v38, v37
	v_exp_f32_e32 v36, v36
	v_mov_b32_e32 v46, v47
	v_pk_mul_f32 v[50:51], v[38:39], v[50:51] op_sel_hi:[0,1]
	v_pk_mul_f32 v[42:43], v[38:39], v[42:43] op_sel_hi:[0,1]
	v_pk_fma_f32 v[32:33], v[32:33], v[36:37], v[50:51] op_sel_hi:[1,0,1]
	v_pk_fma_f32 v[40:41], v[40:41], v[36:37], v[42:43] op_sel_hi:[1,0,1]
	v_cvt_pk_bf16_f32 v30, v32, v33
	v_cvt_pk_bf16_f32 v31, v40, v41
	global_store_dwordx2 v1, v[30:31], s[8:9]
	v_mov_b32_e32 v37, v38
	v_pk_mul_f32 v[10:11], v[10:11], v[36:37]
	s_add_u32 s8, s8, 0x8000
	s_addc_u32 s9, s9, 0
	v_add_f32_e32 v10, v10, v11
	s_mov_b64 exec, s[16:17]
	global_store_dword v2, v10, s[12:13]
	s_mov_b64 exec, s[18:19]
	global_store_dword v0, v47, s[14:15] offset:1656
	s_mov_b64 exec, s[20:21]
	s_add_u32 s12, s12, 0x200
	s_addc_u32 s13, s13, 0
	global_load_dwordx2 v[114:115], v1, s[6:7]
	global_load_dword v139, v2, s[10:11]
	s_add_u32 s6, s6, 0x8000
	s_addc_u32 s7, s7, 0
	s_add_u32 s10, s10, 0x200
	s_addc_u32 s11, s11, 0
	v_readlane_b32 s0, v6, 40
	v_readlane_b32 s1, v7, 40
	s_waitcnt vmcnt(45)
	v_lshlrev_b32_e32 v50, 16, v116
	v_and_b32_e32 v51, 0xffff0000, v116
	v_lshlrev_b32_e32 v42, 16, v117
	v_and_b32_e32 v43, 0xffff0000, v117
	v_mov_b32_e32 v11, v140
	v_add_f32_e32 v36, s0, v46
	v_max_f32_e64 v37, s1, s1
	v_max_f32_e32 v47, v36, v37
	v_sub_f32_e32 v37, s1, v47
	v_sub_f32_e32 v36, v36, v47
	v_mul_f32_e32 v37, 0x3fb8aa3b, v37
	v_mul_f32_e32 v36, 0x3fb8aa3b, v36
	v_exp_f32_e32 v38, v37
	v_exp_f32_e32 v36, v36
	v_mov_b32_e32 v46, v47
	v_pk_mul_f32 v[50:51], v[38:39], v[50:51] op_sel_hi:[0,1]
	v_pk_mul_f32 v[42:43], v[38:39], v[42:43] op_sel_hi:[0,1]
	v_pk_fma_f32 v[32:33], v[32:33], v[36:37], v[50:51] op_sel_hi:[1,0,1]
	v_pk_fma_f32 v[40:41], v[40:41], v[36:37], v[42:43] op_sel_hi:[1,0,1]
	v_cvt_pk_bf16_f32 v30, v32, v33
	v_cvt_pk_bf16_f32 v31, v40, v41
	global_store_dwordx2 v1, v[30:31], s[8:9]
	v_mov_b32_e32 v37, v38
	v_pk_mul_f32 v[10:11], v[10:11], v[36:37]
	s_add_u32 s8, s8, 0x8000
	s_addc_u32 s9, s9, 0
	v_add_f32_e32 v10, v10, v11
	s_mov_b64 exec, s[16:17]
	global_store_dword v2, v10, s[12:13]
	s_mov_b64 exec, s[18:19]
	global_store_dword v0, v47, s[14:15] offset:1672
	s_mov_b64 exec, s[20:21]
	s_add_u32 s12, s12, 0x200
	s_addc_u32 s13, s13, 0
	global_load_dwordx2 v[116:117], v1, s[6:7]
	global_load_dword v140, v2, s[10:11]
	s_add_u32 s6, s6, 0x8000
	s_addc_u32 s7, s7, 0
	s_add_u32 s10, s10, 0x200
	s_addc_u32 s11, s11, 0
	v_readlane_b32 s0, v6, 41
	v_readlane_b32 s1, v7, 41
	s_waitcnt vmcnt(45)
; DI unsigned pack2(float a, float b) { const f32x2 v = {a, b}; return __builtin_bit_cast(unsigned, __builtin_convertvector(v, bf16v2)); }
; DI float bflo(unsigned w) { return __uint_as_float(w << 16); }
; DI float bfhi(unsigned w) { return __uint_as_float(w & 0xffff0000u); }
; DI void phase_mlstm_scan(const Params& p) {
;     ...
;     for (int cb = 0; cb < 128; cb += 8) {
;       uint2 raw[8]; float kr[8];
; #pragma unroll
;       for (int j = 0; j < 8; ++j) { raw[j] = *(const uint2*)(kv + (size_t)(cb + j) * 16384); kr[j] = don ? ks[(cb + j) * 128] : 0.f; }
; #pragma unroll
;       for (int j = 0; j < 8; ++j) {
;         const float B = csc[(cb + j) * 4], A = csc[(cb + j) * 4 + 1];
;         const float mnew = fmaxf(B + m, A);
;         const float wp = __expf(B + m - mnew), wl = __expf(A - mnew);
;         m = mnew;
;         c0 = wp * c0 + wl * bflo(raw[j].x); c1 = wp * c1 + wl * bfhi(raw[j].x); c2 = wp * c2 + wl * bflo(raw[j].y); c3 = wp * c3 + wl * bfhi(raw[j].y);
;         uint2 o; o.x = pack2(c0, c1); o.y = pack2(c2, c3);
;         *(uint2*)(kv + (size_t)(cb + j) * 16384) = o;
;         if (don) { n = wp * n + wl * kr[j]; ks[(cb + j) * 128] = n; }
;         if (part == 0 && tid == 0) csc[(cb + j) * 4 + 2] = mnew;
;       }
;     }
	v_lshlrev_b32_e32 v50, 16, v118
	v_and_b32_e32 v51, 0xffff0000, v118
	v_lshlrev_b32_e32 v42, 16, v119
	v_and_b32_e32 v43, 0xffff0000, v119
	v_mov_b32_e32 v11, v141
	v_add_f32_e32 v36, s0, v46
	v_max_f32_e64 v37, s1, s1
	v_max_f32_e32 v47, v36, v37
	v_sub_f32_e32 v37, s1, v47
	v_sub_f32_e32 v36, v36, v47
	v_mul_f32_e32 v37, 0x3fb8aa3b, v37
	v_mul_f32_e32 v36, 0x3fb8aa3b, v36
	v_exp_f32_e32 v38, v37
	v_exp_f32_e32 v36, v36
	v_mov_b32_e32 v46, v47
	v_pk_mul_f32 v[50:51], v[38:39], v[50:51] op_sel_hi:[0,1]
	v_pk_mul_f32 v[42:43], v[38:39], v[42:43] op_sel_hi:[0,1]
	v_pk_fma_f32 v[32:33], v[32:33], v[36:37], v[50:51] op_sel_hi:[1,0,1]
	v_pk_fma_f32 v[40:41], v[40:41], v[36:37], v[42:43] op_sel_hi:[1,0,1]
	v_cvt_pk_bf16_f32 v30, v32, v33
	v_cvt_pk_bf16_f32 v31, v40, v41
	global_store_dwordx2 v1, v[30:31], s[8:9]
	v_mov_b32_e32 v37, v38
	v_pk_mul_f32 v[10:11], v[10:11], v[36:37]
	s_add_u32 s8, s8, 0x8000
	s_addc_u32 s9, s9, 0
	v_add_f32_e32 v10, v10, v11
	s_mov_b64 exec, s[16:17]
	global_store_dword v2, v10, s[12:13]
	s_mov_b64 exec, s[18:19]
	global_store_dword v0, v47, s[14:15] offset:1688
	s_mov_b64 exec, s[20:21]
	s_add_u32 s12, s12, 0x200
	s_addc_u32 s13, s13, 0
	global_load_dwordx2 v[118:119], v1, s[6:7]
	global_load_dword v141, v2, s[10:11]
	s_add_u32 s6, s6, 0x8000
	s_addc_u32 s7, s7, 0
	s_add_u32 s10, s10, 0x200
	s_addc_u32 s11, s11, 0
	v_readlane_b32 s0, v6, 42
	v_readlane_b32 s1, v7, 42
	s_waitcnt vmcnt(45)
	v_lshlrev_b32_e32 v50, 16, v120
	v_and_b32_e32 v51, 0xffff0000, v120
	v_lshlrev_b32_e32 v42, 16, v121
	v_and_b32_e32 v43, 0xffff0000, v121
	v_mov_b32_e32 v11, v142
	v_add_f32_e32 v36, s0, v46
	v_max_f32_e64 v37, s1, s1
	v_max_f32_e32 v47, v36, v37
	v_sub_f32_e32 v37, s1, v47
	v_sub_f32_e32 v36, v36, v47
	v_mul_f32_e32 v37, 0x3fb8aa3b, v37
	v_mul_f32_e32 v36, 0x3fb8aa3b, v36
	v_exp_f32_e32 v38, v37
	v_exp_f32_e32 v36, v36
	v_mov_b32_e32 v46, v47
	v_pk_mul_f32 v[50:51], v[38:39], v[50:51] op_sel_hi:[0,1]
	v_pk_mul_f32 v[42:43], v[38:39], v[42:43] op_sel_hi:[0,1]
	v_pk_fma_f32 v[32:33], v[32:33], v[36:37], v[50:51] op_sel_hi:[1,0,1]
	v_pk_fma_f32 v[40:41], v[40:41], v[36:37], v[42:43] op_sel_hi:[1,0,1]
	v_cvt_pk_bf16_f32 v30, v32, v33
	v_cvt_pk_bf16_f32 v31, v40, v41
	global_store_dwordx2 v1, v[30:31], s[8:9]
	v_mov_b32_e32 v37, v38
	v_pk_mul_f32 v[10:11], v[10:11], v[36:37]
	s_add_u32 s8, s8, 0x8000
	s_addc_u32 s9, s9, 0
	v_add_f32_e32 v10, v10, v11
	s_mov_b64 exec, s[16:17]
	global_store_dword v2, v10, s[12:13]
	s_mov_b64 exec, s[18:19]
	global_store_dword v0, v47, s[14:15] offset:1704
	s_mov_b64 exec, s[20:21]
	s_add_u32 s12, s12, 0x200
	s_addc_u32 s13, s13, 0
	global_load_dwordx2 v[120:121], v1, s[6:7]
	global_load_dword v142, v2, s[10:11]
	s_add_u32 s6, s6, 0x8000
	s_addc_u32 s7, s7, 0
	s_add_u32 s10, s10, 0x200
	s_addc_u32 s11, s11, 0
	v_readlane_b32 s0, v6, 43
	v_readlane_b32 s1, v7, 43
	s_waitcnt vmcnt(45)
	v_lshlrev_b32_e32 v50, 16, v122
	v_and_b32_e32 v51, 0xffff0000, v122
	v_lshlrev_b32_e32 v42, 16, v123
	v_and_b32_e32 v43, 0xffff0000, v123
	v_mov_b32_e32 v11, v143
	v_add_f32_e32 v36, s0, v46
	v_max_f32_e64 v37, s1, s1
	v_max_f32_e32 v47, v36, v37
	v_sub_f32_e32 v37, s1, v47
	v_sub_f32_e32 v36, v36, v47
	v_mul_f32_e32 v37, 0x3fb8aa3b, v37
	v_mul_f32_e32 v36, 0x3fb8aa3b, v36
	v_exp_f32_e32 v38, v37
	v_exp_f32_e32 v36, v36
	v_mov_b32_e32 v46, v47
	v_pk_mul_f32 v[50:51], v[38:39], v[50:51] op_sel_hi:[0,1]
	v_pk_mul_f32 v[42:43], v[38:39], v[42:43] op_sel_hi:[0,1]
	v_pk_fma_f32 v[32:33], v[32:33], v[36:37], v[50:51] op_sel_hi:[1,0,1]
	v_pk_fma_f32 v[40:41], v[40:41], v[36:37], v[42:43] op_sel_hi:[1,0,1]
	v_cvt_pk_bf16_f32 v30, v32, v33
	v_cvt_pk_bf16_f32 v31, v40, v41
	global_store_dwordx2 v1, v[30:31], s[8:9]
	v_mov_b32_e32 v37, v38
	v_pk_mul_f32 v[10:11], v[10:11], v[36:37]
	s_add_u32 s8, s8, 0x8000
	s_addc_u32 s9, s9, 0
	v_add_f32_e32 v10, v10, v11
	s_mov_b64 exec, s[16:17]
	global_store_dword v2, v10, s[12:13]
	s_mov_b64 exec, s[18:19]
	global_store_dword v0, v47, s[14:15] offset:1720
	s_mov_b64 exec, s[20:21]
	s_add_u32 s12, s12, 0x200
	s_addc_u32 s13, s13, 0
	global_load_dwordx2 v[122:123], v1, s[6:7]
	global_load_dword v143, v2, s[10:11]
	s_add_u32 s6, s6, 0x8000
	s_addc_u32 s7, s7, 0
	s_add_u32 s10, s10, 0x200
	s_addc_u32 s11, s11, 0
	v_readlane_b32 s0, v6, 44
	v_readlane_b32 s1, v7, 44
	s_waitcnt vmcnt(45)
	v_lshlrev_b32_e32 v50, 16, v124
	v_and_b32_e32 v51, 0xffff0000, v124
	v_lshlrev_b32_e32 v42, 16, v125
	v_and_b32_e32 v43, 0xffff0000, v125
	v_mov_b32_e32 v11, v144
	v_add_f32_e32 v36, s0, v46
	v_max_f32_e64 v37, s1, s1
	v_max_f32_e32 v47, v36, v37
	v_sub_f32_e32 v37, s1, v47
	v_sub_f32_e32 v36, v36, v47
	v_mul_f32_e32 v37, 0x3fb8aa3b, v37
	v_mul_f32_e32 v36, 0x3fb8aa3b, v36
	v_exp_f32_e32 v38, v37
	v_exp_f32_e32 v36, v36
	v_mov_b32_e32 v46, v47
	v_pk_mul_f32 v[50:51], v[38:39], v[50:51] op_sel_hi:[0,1]
	v_pk_mul_f32 v[42:43], v[38:39], v[42:43] op_sel_hi:[0,1]
	v_pk_fma_f32 v[32:33], v[32:33], v[36:37], v[50:51] op_sel_hi:[1,0,1]
	v_pk_fma_f32 v[40:41], v[40:41], v[36:37], v[42:43] op_sel_hi:[1,0,1]
	v_cvt_pk_bf16_f32 v30, v32, v33
	v_cvt_pk_bf16_f32 v31, v40, v41
	global_store_dwordx2 v1, v[30:31], s[8:9]
	v_mov_b32_e32 v37, v38
	v_pk_mul_f32 v[10:11], v[10:11], v[36:37]
	s_add_u32 s8, s8, 0x8000
	s_addc_u32 s9, s9, 0
	v_add_f32_e32 v10, v10, v11
	s_mov_b64 exec, s[16:17]
	global_store_dword v2, v10, s[12:13]
	s_mov_b64 exec, s[18:19]
	global_store_dword v0, v47, s[14:15] offset:1736
	s_mov_b64 exec, s[20:21]
	s_add_u32 s12, s12, 0x200
	s_addc_u32 s13, s13, 0
	global_load_dwordx2 v[124:125], v1, s[6:7]
	global_load_dword v144, v2, s[10:11]
	s_add_u32 s6, s6, 0x8000
	s_addc_u32 s7, s7, 0
	s_add_u32 s10, s10, 0x200
	s_addc_u32 s11, s11, 0
	v_readlane_b32 s0, v6, 45
	v_readlane_b32 s1, v7, 45
	s_waitcnt vmcnt(45)
; DI unsigned pack2(float a, float b) { const f32x2 v = {a, b}; return __builtin_bit_cast(unsigned, __builtin_convertvector(v, bf16v2)); }
; DI float bflo(unsigned w) { return __uint_as_float(w << 16); }
; DI float bfhi(unsigned w) { return __uint_as_float(w & 0xffff0000u); }
; DI void phase_mlstm_scan(const Params& p) {
;     ...
;     for (int cb = 0; cb < 128; cb += 8) {
;       uint2 raw[8]; float kr[8];
; #pragma unroll
;       for (int j = 0; j < 8; ++j) { raw[j] = *(const uint2*)(kv + (size_t)(cb + j) * 16384); kr[j] = don ? ks[(cb + j) * 128] : 0.f; }
; #pragma unroll
;       for (int j = 0; j < 8; ++j) {
;         const float B = csc[(cb + j) * 4], A = csc[(cb + j) * 4 + 1];
;         const float mnew = fmaxf(B + m, A);
;         const float wp = __expf(B + m - mnew), wl = __expf(A - mnew);
;         m = mnew;
;         c0 = wp * c0 + wl * bflo(raw[j].x); c1 = wp * c1 + wl * bfhi(raw[j].x); c2 = wp * c2 + wl * bflo(raw[j].y); c3 = wp * c3 + wl * bfhi(raw[j].y);
;         uint2 o; o.x = pack2(c0, c1); o.y = pack2(c2, c3);
;         *(uint2*)(kv + (size_t)(cb + j) * 16384) = o;
;         if (don) { n = wp * n + wl * kr[j]; ks[(cb + j) * 128] = n; }
;         if (part == 0 && tid == 0) csc[(cb + j) * 4 + 2] = mnew;
;       }
;     }
	v_lshlrev_b32_e32 v50, 16, v126
	v_and_b32_e32 v51, 0xffff0000, v126
	v_lshlrev_b32_e32 v42, 16, v127
	v_and_b32_e32 v43, 0xffff0000, v127
	v_mov_b32_e32 v11, v145
	v_add_f32_e32 v36, s0, v46
	v_max_f32_e64 v37, s1, s1
	v_max_f32_e32 v47, v36, v37
	v_sub_f32_e32 v37, s1, v47
	v_sub_f32_e32 v36, v36, v47
	v_mul_f32_e32 v37, 0x3fb8aa3b, v37
	v_mul_f32_e32 v36, 0x3fb8aa3b, v36
	v_exp_f32_e32 v38, v37
	v_exp_f32_e32 v36, v36
	v_mov_b32_e32 v46, v47
	v_pk_mul_f32 v[50:51], v[38:39], v[50:51] op_sel_hi:[0,1]
	v_pk_mul_f32 v[42:43], v[38:39], v[42:43] op_sel_hi:[0,1]
	v_pk_fma_f32 v[32:33], v[32:33], v[36:37], v[50:51] op_sel_hi:[1,0,1]
	v_pk_fma_f32 v[40:41], v[40:41], v[36:37], v[42:43] op_sel_hi:[1,0,1]
	v_cvt_pk_bf16_f32 v30, v32, v33
	v_cvt_pk_bf16_f32 v31, v40, v41
	global_store_dwordx2 v1, v[30:31], s[8:9]
	v_mov_b32_e32 v37, v38
	v_pk_mul_f32 v[10:11], v[10:11], v[36:37]
	s_add_u32 s8, s8, 0x8000
	s_addc_u32 s9, s9, 0
	v_add_f32_e32 v10, v10, v11
	s_mov_b64 exec, s[16:17]
	global_store_dword v2, v10, s[12:13]
	s_mov_b64 exec, s[18:19]
	global_store_dword v0, v47, s[14:15] offset:1752
	s_mov_b64 exec, s[20:21]
	s_add_u32 s12, s12, 0x200
	s_addc_u32 s13, s13, 0
	global_load_dwordx2 v[126:127], v1, s[6:7]
	global_load_dword v145, v2, s[10:11]
	s_add_u32 s6, s6, 0x8000
	s_addc_u32 s7, s7, 0
	s_add_u32 s10, s10, 0x200
	s_addc_u32 s11, s11, 0
	v_readlane_b32 s0, v6, 46
	v_readlane_b32 s1, v7, 46
	s_waitcnt vmcnt(45)
	v_lshlrev_b32_e32 v50, 16, v128
	v_and_b32_e32 v51, 0xffff0000, v128
	v_lshlrev_b32_e32 v42, 16, v129
	v_and_b32_e32 v43, 0xffff0000, v129
	v_mov_b32_e32 v11, v146
	v_add_f32_e32 v36, s0, v46
	v_max_f32_e64 v37, s1, s1
	v_max_f32_e32 v47, v36, v37
	v_sub_f32_e32 v37, s1, v47
	v_sub_f32_e32 v36, v36, v47
	v_mul_f32_e32 v37, 0x3fb8aa3b, v37
	v_mul_f32_e32 v36, 0x3fb8aa3b, v36
	v_exp_f32_e32 v38, v37
	v_exp_f32_e32 v36, v36
	v_mov_b32_e32 v46, v47
	v_pk_mul_f32 v[50:51], v[38:39], v[50:51] op_sel_hi:[0,1]
	v_pk_mul_f32 v[42:43], v[38:39], v[42:43] op_sel_hi:[0,1]
	v_pk_fma_f32 v[32:33], v[32:33], v[36:37], v[50:51] op_sel_hi:[1,0,1]
	v_pk_fma_f32 v[40:41], v[40:41], v[36:37], v[42:43] op_sel_hi:[1,0,1]
	v_cvt_pk_bf16_f32 v30, v32, v33
	v_cvt_pk_bf16_f32 v31, v40, v41
	global_store_dwordx2 v1, v[30:31], s[8:9]
	v_mov_b32_e32 v37, v38
	v_pk_mul_f32 v[10:11], v[10:11], v[36:37]
	s_add_u32 s8, s8, 0x8000
	s_addc_u32 s9, s9, 0
	v_add_f32_e32 v10, v10, v11
	s_mov_b64 exec, s[16:17]
	global_store_dword v2, v10, s[12:13]
	s_mov_b64 exec, s[18:19]
	global_store_dword v0, v47, s[14:15] offset:1768
	s_mov_b64 exec, s[20:21]
	s_add_u32 s12, s12, 0x200
	s_addc_u32 s13, s13, 0
	global_load_dwordx2 v[128:129], v1, s[6:7]
	global_load_dword v146, v2, s[10:11]
	s_add_u32 s6, s6, 0x8000
	s_addc_u32 s7, s7, 0
	s_add_u32 s10, s10, 0x200
	s_addc_u32 s11, s11, 0
	v_readlane_b32 s0, v6, 47
	v_readlane_b32 s1, v7, 47
	s_waitcnt vmcnt(45)
	v_lshlrev_b32_e32 v50, 16, v130
	v_and_b32_e32 v51, 0xffff0000, v130
	v_lshlrev_b32_e32 v42, 16, v131
	v_and_b32_e32 v43, 0xffff0000, v131
	v_mov_b32_e32 v11, v147
	v_add_f32_e32 v36, s0, v46
	v_max_f32_e64 v37, s1, s1
	v_max_f32_e32 v47, v36, v37
	v_sub_f32_e32 v37, s1, v47
	v_sub_f32_e32 v36, v36, v47
	v_mul_f32_e32 v37, 0x3fb8aa3b, v37
	v_mul_f32_e32 v36, 0x3fb8aa3b, v36
	v_exp_f32_e32 v38, v37
	v_exp_f32_e32 v36, v36
	v_mov_b32_e32 v46, v47
	v_pk_mul_f32 v[50:51], v[38:39], v[50:51] op_sel_hi:[0,1]
	v_pk_mul_f32 v[42:43], v[38:39], v[42:43] op_sel_hi:[0,1]
	v_pk_fma_f32 v[32:33], v[32:33], v[36:37], v[50:51] op_sel_hi:[1,0,1]
	v_pk_fma_f32 v[40:41], v[40:41], v[36:37], v[42:43] op_sel_hi:[1,0,1]
	v_cvt_pk_bf16_f32 v30, v32, v33
	v_cvt_pk_bf16_f32 v31, v40, v41
	global_store_dwordx2 v1, v[30:31], s[8:9]
	v_mov_b32_e32 v37, v38
	v_pk_mul_f32 v[10:11], v[10:11], v[36:37]
	s_add_u32 s8, s8, 0x8000
	s_addc_u32 s9, s9, 0
	v_add_f32_e32 v10, v10, v11
	s_mov_b64 exec, s[16:17]
	global_store_dword v2, v10, s[12:13]
	s_mov_b64 exec, s[18:19]
	global_store_dword v0, v47, s[14:15] offset:1784
	s_mov_b64 exec, s[20:21]
	s_add_u32 s12, s12, 0x200
	s_addc_u32 s13, s13, 0
	global_load_dwordx2 v[130:131], v1, s[6:7]
	global_load_dword v147, v2, s[10:11]
	s_add_u32 s6, s6, 0x8000
	s_addc_u32 s7, s7, 0
	s_add_u32 s10, s10, 0x200
	s_addc_u32 s11, s11, 0
	v_readlane_b32 s0, v6, 48
	v_readlane_b32 s1, v7, 48
	s_waitcnt vmcnt(45)
	v_lshlrev_b32_e32 v50, 16, v100
	v_and_b32_e32 v51, 0xffff0000, v100
	v_lshlrev_b32_e32 v42, 16, v101
	v_and_b32_e32 v43, 0xffff0000, v101
	v_mov_b32_e32 v11, v132
	v_add_f32_e32 v36, s0, v46
	v_max_f32_e64 v37, s1, s1
	v_max_f32_e32 v47, v36, v37
	v_sub_f32_e32 v37, s1, v47
	v_sub_f32_e32 v36, v36, v47
	v_mul_f32_e32 v37, 0x3fb8aa3b, v37
	v_mul_f32_e32 v36, 0x3fb8aa3b, v36
	v_exp_f32_e32 v38, v37
	v_exp_f32_e32 v36, v36
	v_mov_b32_e32 v46, v47
	v_pk_mul_f32 v[50:51], v[38:39], v[50:51] op_sel_hi:[0,1]
	v_pk_mul_f32 v[42:43], v[38:39], v[42:43] op_sel_hi:[0,1]
	v_pk_fma_f32 v[32:33], v[32:33], v[36:37], v[50:51] op_sel_hi:[1,0,1]
	v_pk_fma_f32 v[40:41], v[40:41], v[36:37], v[42:43] op_sel_hi:[1,0,1]
	v_cvt_pk_bf16_f32 v30, v32, v33
	v_cvt_pk_bf16_f32 v31, v40, v41
	global_store_dwordx2 v1, v[30:31], s[8:9]
	v_mov_b32_e32 v37, v38
	v_pk_mul_f32 v[10:11], v[10:11], v[36:37]
	s_add_u32 s8, s8, 0x8000
	s_addc_u32 s9, s9, 0
	v_add_f32_e32 v10, v10, v11
	s_mov_b64 exec, s[16:17]
	global_store_dword v2, v10, s[12:13]
	s_mov_b64 exec, s[18:19]
	global_store_dword v0, v47, s[14:15] offset:1800
	s_mov_b64 exec, s[20:21]
	s_add_u32 s12, s12, 0x200
	s_addc_u32 s13, s13, 0
	v_readlane_b32 s0, v6, 49
	v_readlane_b32 s1, v7, 49
	s_waitcnt vmcnt(43)
; DI unsigned pack2(float a, float b) { const f32x2 v = {a, b}; return __builtin_bit_cast(unsigned, __builtin_convertvector(v, bf16v2)); }
; DI float bflo(unsigned w) { return __uint_as_float(w << 16); }
; DI float bfhi(unsigned w) { return __uint_as_float(w & 0xffff0000u); }
; DI void phase_mlstm_scan(const Params& p) {
;     ...
;     for (int cb = 0; cb < 128; cb += 8) {
;       uint2 raw[8]; float kr[8];
; #pragma unroll
;       for (int j = 0; j < 8; ++j) { raw[j] = *(const uint2*)(kv + (size_t)(cb + j) * 16384); kr[j] = don ? ks[(cb + j) * 128] : 0.f; }
; #pragma unroll
;       for (int j = 0; j < 8; ++j) {
;         const float B = csc[(cb + j) * 4], A = csc[(cb + j) * 4 + 1];
;         const float mnew = fmaxf(B + m, A);
;         const float wp = __expf(B + m - mnew), wl = __expf(A - mnew);
;         m = mnew;
;         c0 = wp * c0 + wl * bflo(raw[j].x); c1 = wp * c1 + wl * bfhi(raw[j].x); c2 = wp * c2 + wl * bflo(raw[j].y); c3 = wp * c3 + wl * bfhi(raw[j].y);
;         uint2 o; o.x = pack2(c0, c1); o.y = pack2(c2, c3);
;         *(uint2*)(kv + (size_t)(cb + j) * 16384) = o;
;         if (don) { n = wp * n + wl * kr[j]; ks[(cb + j) * 128] = n; }
;         if (part == 0 && tid == 0) csc[(cb + j) * 4 + 2] = mnew;
;       }
;     }
	v_lshlrev_b32_e32 v50, 16, v102
	v_and_b32_e32 v51, 0xffff0000, v102
	v_lshlrev_b32_e32 v42, 16, v103
	v_and_b32_e32 v43, 0xffff0000, v103
	v_mov_b32_e32 v11, v133
	v_add_f32_e32 v36, s0, v46
	v_max_f32_e64 v37, s1, s1
	v_max_f32_e32 v47, v36, v37
	v_sub_f32_e32 v37, s1, v47
	v_sub_f32_e32 v36, v36, v47
	v_mul_f32_e32 v37, 0x3fb8aa3b, v37
	v_mul_f32_e32 v36, 0x3fb8aa3b, v36
	v_exp_f32_e32 v38, v37
	v_exp_f32_e32 v36, v36
	v_mov_b32_e32 v46, v47
	v_pk_mul_f32 v[50:51], v[38:39], v[50:51] op_sel_hi:[0,1]
	v_pk_mul_f32 v[42:43], v[38:39], v[42:43] op_sel_hi:[0,1]
	v_pk_fma_f32 v[32:33], v[32:33], v[36:37], v[50:51] op_sel_hi:[1,0,1]
	v_pk_fma_f32 v[40:41], v[40:41], v[36:37], v[42:43] op_sel_hi:[1,0,1]
	v_cvt_pk_bf16_f32 v30, v32, v33
	v_cvt_pk_bf16_f32 v31, v40, v41
	global_store_dwordx2 v1, v[30:31], s[8:9]
	v_mov_b32_e32 v37, v38
	v_pk_mul_f32 v[10:11], v[10:11], v[36:37]
	s_add_u32 s8, s8, 0x8000
	s_addc_u32 s9, s9, 0
	v_add_f32_e32 v10, v10, v11
	s_mov_b64 exec, s[16:17]
	global_store_dword v2, v10, s[12:13]
	s_mov_b64 exec, s[18:19]
	global_store_dword v0, v47, s[14:15] offset:1816
	s_mov_b64 exec, s[20:21]
	s_add_u32 s12, s12, 0x200
	s_addc_u32 s13, s13, 0
	v_readlane_b32 s0, v6, 50
	v_readlane_b32 s1, v7, 50
	s_waitcnt vmcnt(41)
	v_lshlrev_b32_e32 v50, 16, v104
	v_and_b32_e32 v51, 0xffff0000, v104
	v_lshlrev_b32_e32 v42, 16, v105
	v_and_b32_e32 v43, 0xffff0000, v105
	v_mov_b32_e32 v11, v134
	v_add_f32_e32 v36, s0, v46
	v_max_f32_e64 v37, s1, s1
	v_max_f32_e32 v47, v36, v37
	v_sub_f32_e32 v37, s1, v47
	v_sub_f32_e32 v36, v36, v47
	v_mul_f32_e32 v37, 0x3fb8aa3b, v37
	v_mul_f32_e32 v36, 0x3fb8aa3b, v36
	v_exp_f32_e32 v38, v37
	v_exp_f32_e32 v36, v36
	v_mov_b32_e32 v46, v47
	v_pk_mul_f32 v[50:51], v[38:39], v[50:51] op_sel_hi:[0,1]
	v_pk_mul_f32 v[42:43], v[38:39], v[42:43] op_sel_hi:[0,1]
	v_pk_fma_f32 v[32:33], v[32:33], v[36:37], v[50:51] op_sel_hi:[1,0,1]
	v_pk_fma_f32 v[40:41], v[40:41], v[36:37], v[42:43] op_sel_hi:[1,0,1]
	v_cvt_pk_bf16_f32 v30, v32, v33
	v_cvt_pk_bf16_f32 v31, v40, v41
	global_store_dwordx2 v1, v[30:31], s[8:9]
	v_mov_b32_e32 v37, v38
	v_pk_mul_f32 v[10:11], v[10:11], v[36:37]
	s_add_u32 s8, s8, 0x8000
	s_addc_u32 s9, s9, 0
	v_add_f32_e32 v10, v10, v11
	s_mov_b64 exec, s[16:17]
	global_store_dword v2, v10, s[12:13]
	s_mov_b64 exec, s[18:19]
	global_store_dword v0, v47, s[14:15] offset:1832
	s_mov_b64 exec, s[20:21]
	s_add_u32 s12, s12, 0x200
	s_addc_u32 s13, s13, 0
	v_readlane_b32 s0, v6, 51
	v_readlane_b32 s1, v7, 51
	s_waitcnt vmcnt(39)
	v_lshlrev_b32_e32 v50, 16, v106
	v_and_b32_e32 v51, 0xffff0000, v106
	v_lshlrev_b32_e32 v42, 16, v107
	v_and_b32_e32 v43, 0xffff0000, v107
	v_mov_b32_e32 v11, v135
	v_add_f32_e32 v36, s0, v46
	v_max_f32_e64 v37, s1, s1
	v_max_f32_e32 v47, v36, v37
	v_sub_f32_e32 v37, s1, v47
	v_sub_f32_e32 v36, v36, v47
	v_mul_f32_e32 v37, 0x3fb8aa3b, v37
	v_mul_f32_e32 v36, 0x3fb8aa3b, v36
	v_exp_f32_e32 v38, v37
	v_exp_f32_e32 v36, v36
	v_mov_b32_e32 v46, v47
	v_pk_mul_f32 v[50:51], v[38:39], v[50:51] op_sel_hi:[0,1]
	v_pk_mul_f32 v[42:43], v[38:39], v[42:43] op_sel_hi:[0,1]
	v_pk_fma_f32 v[32:33], v[32:33], v[36:37], v[50:51] op_sel_hi:[1,0,1]
	v_pk_fma_f32 v[40:41], v[40:41], v[36:37], v[42:43] op_sel_hi:[1,0,1]
	v_cvt_pk_bf16_f32 v30, v32, v33
	v_cvt_pk_bf16_f32 v31, v40, v41
	global_store_dwordx2 v1, v[30:31], s[8:9]
	v_mov_b32_e32 v37, v38
	v_pk_mul_f32 v[10:11], v[10:11], v[36:37]
	s_add_u32 s8, s8, 0x8000
	s_addc_u32 s9, s9, 0
	v_add_f32_e32 v10, v10, v11
	s_mov_b64 exec, s[16:17]
	global_store_dword v2, v10, s[12:13]
	s_mov_b64 exec, s[18:19]
	global_store_dword v0, v47, s[14:15] offset:1848
	s_mov_b64 exec, s[20:21]
	s_add_u32 s12, s12, 0x200
	s_addc_u32 s13, s13, 0
	v_readlane_b32 s0, v6, 52
	v_readlane_b32 s1, v7, 52
	s_waitcnt vmcnt(37)
	v_lshlrev_b32_e32 v50, 16, v108
	v_and_b32_e32 v51, 0xffff0000, v108
	v_lshlrev_b32_e32 v42, 16, v109
	v_and_b32_e32 v43, 0xffff0000, v109
	v_mov_b32_e32 v11, v136
	v_add_f32_e32 v36, s0, v46
	v_max_f32_e64 v37, s1, s1
	v_max_f32_e32 v47, v36, v37
	v_sub_f32_e32 v37, s1, v47
	v_sub_f32_e32 v36, v36, v47
	v_mul_f32_e32 v37, 0x3fb8aa3b, v37
	v_mul_f32_e32 v36, 0x3fb8aa3b, v36
	v_exp_f32_e32 v38, v37
	v_exp_f32_e32 v36, v36
	v_mov_b32_e32 v46, v47
	v_pk_mul_f32 v[50:51], v[38:39], v[50:51] op_sel_hi:[0,1]
	v_pk_mul_f32 v[42:43], v[38:39], v[42:43] op_sel_hi:[0,1]
	v_pk_fma_f32 v[32:33], v[32:33], v[36:37], v[50:51] op_sel_hi:[1,0,1]
	v_pk_fma_f32 v[40:41], v[40:41], v[36:37], v[42:43] op_sel_hi:[1,0,1]
	v_cvt_pk_bf16_f32 v30, v32, v33
	v_cvt_pk_bf16_f32 v31, v40, v41
	global_store_dwordx2 v1, v[30:31], s[8:9]
	v_mov_b32_e32 v37, v38
	v_pk_mul_f32 v[10:11], v[10:11], v[36:37]
	s_add_u32 s8, s8, 0x8000
	s_addc_u32 s9, s9, 0
	v_add_f32_e32 v10, v10, v11
	s_mov_b64 exec, s[16:17]
	global_store_dword v2, v10, s[12:13]
	s_mov_b64 exec, s[18:19]
	global_store_dword v0, v47, s[14:15] offset:1864
	s_mov_b64 exec, s[20:21]
	s_add_u32 s12, s12, 0x200
	s_addc_u32 s13, s13, 0
	v_readlane_b32 s0, v6, 53
	v_readlane_b32 s1, v7, 53
	s_waitcnt vmcnt(35)
; DI unsigned pack2(float a, float b) { const f32x2 v = {a, b}; return __builtin_bit_cast(unsigned, __builtin_convertvector(v, bf16v2)); }
; DI float bflo(unsigned w) { return __uint_as_float(w << 16); }
; DI float bfhi(unsigned w) { return __uint_as_float(w & 0xffff0000u); }
; DI void phase_mlstm_scan(const Params& p) {
;     ...
;     for (int cb = 0; cb < 128; cb += 8) {
;       uint2 raw[8]; float kr[8];
; #pragma unroll
;       for (int j = 0; j < 8; ++j) { raw[j] = *(const uint2*)(kv + (size_t)(cb + j) * 16384); kr[j] = don ? ks[(cb + j) * 128] : 0.f; }
; #pragma unroll
;       for (int j = 0; j < 8; ++j) {
;         const float B = csc[(cb + j) * 4], A = csc[(cb + j) * 4 + 1];
;         const float mnew = fmaxf(B + m, A);
;         const float wp = __expf(B + m - mnew), wl = __expf(A - mnew);
;         m = mnew;
;         c0 = wp * c0 + wl * bflo(raw[j].x); c1 = wp * c1 + wl * bfhi(raw[j].x); c2 = wp * c2 + wl * bflo(raw[j].y); c3 = wp * c3 + wl * bfhi(raw[j].y);
;         uint2 o; o.x = pack2(c0, c1); o.y = pack2(c2, c3);
;         *(uint2*)(kv + (size_t)(cb + j) * 16384) = o;
;         if (don) { n = wp * n + wl * kr[j]; ks[(cb + j) * 128] = n; }
;         if (part == 0 && tid == 0) csc[(cb + j) * 4 + 2] = mnew;
;       }
;     }
	v_lshlrev_b32_e32 v50, 16, v110
	v_and_b32_e32 v51, 0xffff0000, v110
	v_lshlrev_b32_e32 v42, 16, v111
	v_and_b32_e32 v43, 0xffff0000, v111
	v_mov_b32_e32 v11, v137
	v_add_f32_e32 v36, s0, v46
	v_max_f32_e64 v37, s1, s1
	v_max_f32_e32 v47, v36, v37
	v_sub_f32_e32 v37, s1, v47
	v_sub_f32_e32 v36, v36, v47
	v_mul_f32_e32 v37, 0x3fb8aa3b, v37
	v_mul_f32_e32 v36, 0x3fb8aa3b, v36
	v_exp_f32_e32 v38, v37
	v_exp_f32_e32 v36, v36
	v_mov_b32_e32 v46, v47
	v_pk_mul_f32 v[50:51], v[38:39], v[50:51] op_sel_hi:[0,1]
	v_pk_mul_f32 v[42:43], v[38:39], v[42:43] op_sel_hi:[0,1]
	v_pk_fma_f32 v[32:33], v[32:33], v[36:37], v[50:51] op_sel_hi:[1,0,1]
	v_pk_fma_f32 v[40:41], v[40:41], v[36:37], v[42:43] op_sel_hi:[1,0,1]
	v_cvt_pk_bf16_f32 v30, v32, v33
	v_cvt_pk_bf16_f32 v31, v40, v41
	global_store_dwordx2 v1, v[30:31], s[8:9]
	v_mov_b32_e32 v37, v38
	v_pk_mul_f32 v[10:11], v[10:11], v[36:37]
	s_add_u32 s8, s8, 0x8000
	s_addc_u32 s9, s9, 0
	v_add_f32_e32 v10, v10, v11
	s_mov_b64 exec, s[16:17]
	global_store_dword v2, v10, s[12:13]
	s_mov_b64 exec, s[18:19]
	global_store_dword v0, v47, s[14:15] offset:1880
	s_mov_b64 exec, s[20:21]
	s_add_u32 s12, s12, 0x200
	s_addc_u32 s13, s13, 0
	v_readlane_b32 s0, v6, 54
	v_readlane_b32 s1, v7, 54
	s_waitcnt vmcnt(33)
	v_lshlrev_b32_e32 v50, 16, v112
	v_and_b32_e32 v51, 0xffff0000, v112
	v_lshlrev_b32_e32 v42, 16, v113
	v_and_b32_e32 v43, 0xffff0000, v113
	v_mov_b32_e32 v11, v138
	v_add_f32_e32 v36, s0, v46
	v_max_f32_e64 v37, s1, s1
	v_max_f32_e32 v47, v36, v37
	v_sub_f32_e32 v37, s1, v47
	v_sub_f32_e32 v36, v36, v47
	v_mul_f32_e32 v37, 0x3fb8aa3b, v37
	v_mul_f32_e32 v36, 0x3fb8aa3b, v36
	v_exp_f32_e32 v38, v37
	v_exp_f32_e32 v36, v36
	v_mov_b32_e32 v46, v47
	v_pk_mul_f32 v[50:51], v[38:39], v[50:51] op_sel_hi:[0,1]
	v_pk_mul_f32 v[42:43], v[38:39], v[42:43] op_sel_hi:[0,1]
	v_pk_fma_f32 v[32:33], v[32:33], v[36:37], v[50:51] op_sel_hi:[1,0,1]
	v_pk_fma_f32 v[40:41], v[40:41], v[36:37], v[42:43] op_sel_hi:[1,0,1]
	v_cvt_pk_bf16_f32 v30, v32, v33
	v_cvt_pk_bf16_f32 v31, v40, v41
	global_store_dwordx2 v1, v[30:31], s[8:9]
	v_mov_b32_e32 v37, v38
	v_pk_mul_f32 v[10:11], v[10:11], v[36:37]
	s_add_u32 s8, s8, 0x8000
	s_addc_u32 s9, s9, 0
	v_add_f32_e32 v10, v10, v11
	s_mov_b64 exec, s[16:17]
	global_store_dword v2, v10, s[12:13]
	s_mov_b64 exec, s[18:19]
	global_store_dword v0, v47, s[14:15] offset:1896
	s_mov_b64 exec, s[20:21]
	s_add_u32 s12, s12, 0x200
	s_addc_u32 s13, s13, 0
	v_readlane_b32 s0, v6, 55
	v_readlane_b32 s1, v7, 55
	s_waitcnt vmcnt(31)
	v_lshlrev_b32_e32 v50, 16, v114
	v_and_b32_e32 v51, 0xffff0000, v114
	v_lshlrev_b32_e32 v42, 16, v115
	v_and_b32_e32 v43, 0xffff0000, v115
	v_mov_b32_e32 v11, v139
	v_add_f32_e32 v36, s0, v46
	v_max_f32_e64 v37, s1, s1
	v_max_f32_e32 v47, v36, v37
	v_sub_f32_e32 v37, s1, v47
	v_sub_f32_e32 v36, v36, v47
	v_mul_f32_e32 v37, 0x3fb8aa3b, v37
	v_mul_f32_e32 v36, 0x3fb8aa3b, v36
	v_exp_f32_e32 v38, v37
	v_exp_f32_e32 v36, v36
	v_mov_b32_e32 v46, v47
	v_pk_mul_f32 v[50:51], v[38:39], v[50:51] op_sel_hi:[0,1]
	v_pk_mul_f32 v[42:43], v[38:39], v[42:43] op_sel_hi:[0,1]
	v_pk_fma_f32 v[32:33], v[32:33], v[36:37], v[50:51] op_sel_hi:[1,0,1]
	v_pk_fma_f32 v[40:41], v[40:41], v[36:37], v[42:43] op_sel_hi:[1,0,1]
	v_cvt_pk_bf16_f32 v30, v32, v33
	v_cvt_pk_bf16_f32 v31, v40, v41
	global_store_dwordx2 v1, v[30:31], s[8:9]
	v_mov_b32_e32 v37, v38
	v_pk_mul_f32 v[10:11], v[10:11], v[36:37]
	s_add_u32 s8, s8, 0x8000
	s_addc_u32 s9, s9, 0
	v_add_f32_e32 v10, v10, v11
	s_mov_b64 exec, s[16:17]
	global_store_dword v2, v10, s[12:13]
	s_mov_b64 exec, s[18:19]
	global_store_dword v0, v47, s[14:15] offset:1912
	s_mov_b64 exec, s[20:21]
	s_add_u32 s12, s12, 0x200
	s_addc_u32 s13, s13, 0
	v_readlane_b32 s0, v6, 56
	v_readlane_b32 s1, v7, 56
	s_waitcnt vmcnt(29)
	v_lshlrev_b32_e32 v50, 16, v116
	v_and_b32_e32 v51, 0xffff0000, v116
	v_lshlrev_b32_e32 v42, 16, v117
	v_and_b32_e32 v43, 0xffff0000, v117
	v_mov_b32_e32 v11, v140
	v_add_f32_e32 v36, s0, v46
	v_max_f32_e64 v37, s1, s1
	v_max_f32_e32 v47, v36, v37
	v_sub_f32_e32 v37, s1, v47
	v_sub_f32_e32 v36, v36, v47
	v_mul_f32_e32 v37, 0x3fb8aa3b, v37
	v_mul_f32_e32 v36, 0x3fb8aa3b, v36
	v_exp_f32_e32 v38, v37
	v_exp_f32_e32 v36, v36
	v_mov_b32_e32 v46, v47
	v_pk_mul_f32 v[50:51], v[38:39], v[50:51] op_sel_hi:[0,1]
	v_pk_mul_f32 v[42:43], v[38:39], v[42:43] op_sel_hi:[0,1]
	v_pk_fma_f32 v[32:33], v[32:33], v[36:37], v[50:51] op_sel_hi:[1,0,1]
	v_pk_fma_f32 v[40:41], v[40:41], v[36:37], v[42:43] op_sel_hi:[1,0,1]
	v_cvt_pk_bf16_f32 v30, v32, v33
	v_cvt_pk_bf16_f32 v31, v40, v41
	global_store_dwordx2 v1, v[30:31], s[8:9]
	v_mov_b32_e32 v37, v38
	v_pk_mul_f32 v[10:11], v[10:11], v[36:37]
	s_add_u32 s8, s8, 0x8000
	s_addc_u32 s9, s9, 0
	v_add_f32_e32 v10, v10, v11
	s_mov_b64 exec, s[16:17]
	global_store_dword v2, v10, s[12:13]
	s_mov_b64 exec, s[18:19]
	global_store_dword v0, v47, s[14:15] offset:1928
	s_mov_b64 exec, s[20:21]
	s_add_u32 s12, s12, 0x200
	s_addc_u32 s13, s13, 0
	v_readlane_b32 s0, v6, 57
	v_readlane_b32 s1, v7, 57
	s_waitcnt vmcnt(27)
; DI unsigned pack2(float a, float b) { const f32x2 v = {a, b}; return __builtin_bit_cast(unsigned, __builtin_convertvector(v, bf16v2)); }
; DI float bflo(unsigned w) { return __uint_as_float(w << 16); }
; DI float bfhi(unsigned w) { return __uint_as_float(w & 0xffff0000u); }
; DI void phase_mlstm_scan(const Params& p) {
;     ...
;     for (int cb = 0; cb < 128; cb += 8) {
;       uint2 raw[8]; float kr[8];
; #pragma unroll
;       for (int j = 0; j < 8; ++j) { raw[j] = *(const uint2*)(kv + (size_t)(cb + j) * 16384); kr[j] = don ? ks[(cb + j) * 128] : 0.f; }
; #pragma unroll
;       for (int j = 0; j < 8; ++j) {
;         const float B = csc[(cb + j) * 4], A = csc[(cb + j) * 4 + 1];
;         const float mnew = fmaxf(B + m, A);
;         const float wp = __expf(B + m - mnew), wl = __expf(A - mnew);
;         m = mnew;
;         c0 = wp * c0 + wl * bflo(raw[j].x); c1 = wp * c1 + wl * bfhi(raw[j].x); c2 = wp * c2 + wl * bflo(raw[j].y); c3 = wp * c3 + wl * bfhi(raw[j].y);
;         uint2 o; o.x = pack2(c0, c1); o.y = pack2(c2, c3);
;         *(uint2*)(kv + (size_t)(cb + j) * 16384) = o;
;         if (don) { n = wp * n + wl * kr[j]; ks[(cb + j) * 128] = n; }
;         if (part == 0 && tid == 0) csc[(cb + j) * 4 + 2] = mnew;
;       }
;     }
	v_lshlrev_b32_e32 v50, 16, v118
	v_and_b32_e32 v51, 0xffff0000, v118
	v_lshlrev_b32_e32 v42, 16, v119
	v_and_b32_e32 v43, 0xffff0000, v119
	v_mov_b32_e32 v11, v141
	v_add_f32_e32 v36, s0, v46
	v_max_f32_e64 v37, s1, s1
	v_max_f32_e32 v47, v36, v37
	v_sub_f32_e32 v37, s1, v47
	v_sub_f32_e32 v36, v36, v47
	v_mul_f32_e32 v37, 0x3fb8aa3b, v37
	v_mul_f32_e32 v36, 0x3fb8aa3b, v36
	v_exp_f32_e32 v38, v37
	v_exp_f32_e32 v36, v36
	v_mov_b32_e32 v46, v47
	v_pk_mul_f32 v[50:51], v[38:39], v[50:51] op_sel_hi:[0,1]
	v_pk_mul_f32 v[42:43], v[38:39], v[42:43] op_sel_hi:[0,1]
	v_pk_fma_f32 v[32:33], v[32:33], v[36:37], v[50:51] op_sel_hi:[1,0,1]
	v_pk_fma_f32 v[40:41], v[40:41], v[36:37], v[42:43] op_sel_hi:[1,0,1]
	v_cvt_pk_bf16_f32 v30, v32, v33
	v_cvt_pk_bf16_f32 v31, v40, v41
	global_store_dwordx2 v1, v[30:31], s[8:9]
	v_mov_b32_e32 v37, v38
	v_pk_mul_f32 v[10:11], v[10:11], v[36:37]
	s_add_u32 s8, s8, 0x8000
	s_addc_u32 s9, s9, 0
	v_add_f32_e32 v10, v10, v11
	s_mov_b64 exec, s[16:17]
	global_store_dword v2, v10, s[12:13]
	s_mov_b64 exec, s[18:19]
	global_store_dword v0, v47, s[14:15] offset:1944
	s_mov_b64 exec, s[20:21]
	s_add_u32 s12, s12, 0x200
	s_addc_u32 s13, s13, 0
	v_readlane_b32 s0, v6, 58
	v_readlane_b32 s1, v7, 58
	s_waitcnt vmcnt(25)
	v_lshlrev_b32_e32 v50, 16, v120
	v_and_b32_e32 v51, 0xffff0000, v120
	v_lshlrev_b32_e32 v42, 16, v121
	v_and_b32_e32 v43, 0xffff0000, v121
	v_mov_b32_e32 v11, v142
	v_add_f32_e32 v36, s0, v46
	v_max_f32_e64 v37, s1, s1
	v_max_f32_e32 v47, v36, v37
	v_sub_f32_e32 v37, s1, v47
	v_sub_f32_e32 v36, v36, v47
	v_mul_f32_e32 v37, 0x3fb8aa3b, v37
	v_mul_f32_e32 v36, 0x3fb8aa3b, v36
	v_exp_f32_e32 v38, v37
	v_exp_f32_e32 v36, v36
	v_mov_b32_e32 v46, v47
	v_pk_mul_f32 v[50:51], v[38:39], v[50:51] op_sel_hi:[0,1]
	v_pk_mul_f32 v[42:43], v[38:39], v[42:43] op_sel_hi:[0,1]
	v_pk_fma_f32 v[32:33], v[32:33], v[36:37], v[50:51] op_sel_hi:[1,0,1]
	v_pk_fma_f32 v[40:41], v[40:41], v[36:37], v[42:43] op_sel_hi:[1,0,1]
	v_cvt_pk_bf16_f32 v30, v32, v33
	v_cvt_pk_bf16_f32 v31, v40, v41
	global_store_dwordx2 v1, v[30:31], s[8:9]
	v_mov_b32_e32 v37, v38
	v_pk_mul_f32 v[10:11], v[10:11], v[36:37]
	s_add_u32 s8, s8, 0x8000
	s_addc_u32 s9, s9, 0
	v_add_f32_e32 v10, v10, v11
	s_mov_b64 exec, s[16:17]
	global_store_dword v2, v10, s[12:13]
	s_mov_b64 exec, s[18:19]
	global_store_dword v0, v47, s[14:15] offset:1960
	s_mov_b64 exec, s[20:21]
	s_add_u32 s12, s12, 0x200
	s_addc_u32 s13, s13, 0
	v_readlane_b32 s0, v6, 59
	v_readlane_b32 s1, v7, 59
	s_waitcnt vmcnt(23)
	v_lshlrev_b32_e32 v50, 16, v122
	v_and_b32_e32 v51, 0xffff0000, v122
	v_lshlrev_b32_e32 v42, 16, v123
	v_and_b32_e32 v43, 0xffff0000, v123
	v_mov_b32_e32 v11, v143
	v_add_f32_e32 v36, s0, v46
	v_max_f32_e64 v37, s1, s1
	v_max_f32_e32 v47, v36, v37
	v_sub_f32_e32 v37, s1, v47
	v_sub_f32_e32 v36, v36, v47
	v_mul_f32_e32 v37, 0x3fb8aa3b, v37
	v_mul_f32_e32 v36, 0x3fb8aa3b, v36
	v_exp_f32_e32 v38, v37
	v_exp_f32_e32 v36, v36
	v_mov_b32_e32 v46, v47
	v_pk_mul_f32 v[50:51], v[38:39], v[50:51] op_sel_hi:[0,1]
	v_pk_mul_f32 v[42:43], v[38:39], v[42:43] op_sel_hi:[0,1]
	v_pk_fma_f32 v[32:33], v[32:33], v[36:37], v[50:51] op_sel_hi:[1,0,1]
	v_pk_fma_f32 v[40:41], v[40:41], v[36:37], v[42:43] op_sel_hi:[1,0,1]
	v_cvt_pk_bf16_f32 v30, v32, v33
	v_cvt_pk_bf16_f32 v31, v40, v41
	global_store_dwordx2 v1, v[30:31], s[8:9]
	v_mov_b32_e32 v37, v38
	v_pk_mul_f32 v[10:11], v[10:11], v[36:37]
	s_add_u32 s8, s8, 0x8000
	s_addc_u32 s9, s9, 0
	v_add_f32_e32 v10, v10, v11
	s_mov_b64 exec, s[16:17]
	global_store_dword v2, v10, s[12:13]
	s_mov_b64 exec, s[18:19]
	global_store_dword v0, v47, s[14:15] offset:1976
	s_mov_b64 exec, s[20:21]
	s_add_u32 s12, s12, 0x200
	s_addc_u32 s13, s13, 0
	v_readlane_b32 s0, v6, 60
	v_readlane_b32 s1, v7, 60
	s_waitcnt vmcnt(21)
	v_lshlrev_b32_e32 v50, 16, v124
	v_and_b32_e32 v51, 0xffff0000, v124
	v_lshlrev_b32_e32 v42, 16, v125
	v_and_b32_e32 v43, 0xffff0000, v125
	v_mov_b32_e32 v11, v144
	v_add_f32_e32 v36, s0, v46
	v_max_f32_e64 v37, s1, s1
	v_max_f32_e32 v47, v36, v37
	v_sub_f32_e32 v37, s1, v47
	v_sub_f32_e32 v36, v36, v47
	v_mul_f32_e32 v37, 0x3fb8aa3b, v37
	v_mul_f32_e32 v36, 0x3fb8aa3b, v36
	v_exp_f32_e32 v38, v37
	v_exp_f32_e32 v36, v36
	v_mov_b32_e32 v46, v47
	v_pk_mul_f32 v[50:51], v[38:39], v[50:51] op_sel_hi:[0,1]
	v_pk_mul_f32 v[42:43], v[38:39], v[42:43] op_sel_hi:[0,1]
	v_pk_fma_f32 v[32:33], v[32:33], v[36:37], v[50:51] op_sel_hi:[1,0,1]
	v_pk_fma_f32 v[40:41], v[40:41], v[36:37], v[42:43] op_sel_hi:[1,0,1]
	v_cvt_pk_bf16_f32 v30, v32, v33
	v_cvt_pk_bf16_f32 v31, v40, v41
	global_store_dwordx2 v1, v[30:31], s[8:9]
	v_mov_b32_e32 v37, v38
	v_pk_mul_f32 v[10:11], v[10:11], v[36:37]
	s_add_u32 s8, s8, 0x8000
	s_addc_u32 s9, s9, 0
	v_add_f32_e32 v10, v10, v11
	s_mov_b64 exec, s[16:17]
	global_store_dword v2, v10, s[12:13]
	s_mov_b64 exec, s[18:19]
	global_store_dword v0, v47, s[14:15] offset:1992
	s_mov_b64 exec, s[20:21]
	s_add_u32 s12, s12, 0x200
	s_addc_u32 s13, s13, 0
	v_readlane_b32 s0, v6, 61
	v_readlane_b32 s1, v7, 61
	s_waitcnt vmcnt(19)
; DI unsigned pack2(float a, float b) { const f32x2 v = {a, b}; return __builtin_bit_cast(unsigned, __builtin_convertvector(v, bf16v2)); }
; DI float bflo(unsigned w) { return __uint_as_float(w << 16); }
; DI float bfhi(unsigned w) { return __uint_as_float(w & 0xffff0000u); }
; DI unsigned xb_add(unsigned* p, unsigned v) { return __hip_atomic_fetch_add(p, v, __ATOMIC_RELAXED, __HIP_MEMORY_SCOPE_AGENT); }
; DI void phase_mlstm_scan(const Params& p) {
;     ...
;     for (int cb = 0; cb < 128; cb += 8) {
;       uint2 raw[8]; float kr[8];
; #pragma unroll
;       for (int j = 0; j < 8; ++j) { raw[j] = *(const uint2*)(kv + (size_t)(cb + j) * 16384); kr[j] = don ? ks[(cb + j) * 128] : 0.f; }
; #pragma unroll
;       for (int j = 0; j < 8; ++j) {
;         const float B = csc[(cb + j) * 4], A = csc[(cb + j) * 4 + 1];
;         const float mnew = fmaxf(B + m, A);
;         const float wp = __expf(B + m - mnew), wl = __expf(A - mnew);
;         m = mnew;
;         c0 = wp * c0 + wl * bflo(raw[j].x); c1 = wp * c1 + wl * bfhi(raw[j].x); c2 = wp * c2 + wl * bflo(raw[j].y); c3 = wp * c3 + wl * bfhi(raw[j].y);
;         uint2 o; o.x = pack2(c0, c1); o.y = pack2(c2, c3);
;         *(uint2*)(kv + (size_t)(cb + j) * 16384) = o;
;         if (don) { n = wp * n + wl * kr[j]; ks[(cb + j) * 128] = n; }
;         if (part == 0 && tid == 0) csc[(cb + j) * 4 + 2] = mnew;
;       }
;     }
; DI void xcd_barrier(const XcdBarrier& b) {
;   asm volatile("s_waitcnt vmcnt(0)" ::: "memory");
;   __syncthreads();
;   if (threadIdx.x == 0) {
;     unsigned* bar = b.bar;
;     __builtin_amdgcn_s_waitcnt(0);
;     unsigned nloc = b.st[0], nx = b.st[1];
;     if (nloc == 0u) { xcd_barrier_complete(bar, b.x, nloc, nx); b.st[0] = nloc; b.st[1] = nx; }
;     const unsigned old = xb_add(&bar[XB_XSUB(b.x)], 1u);
	v_lshlrev_b32_e32 v50, 16, v126
	v_and_b32_e32 v51, 0xffff0000, v126
	v_lshlrev_b32_e32 v42, 16, v127
	v_and_b32_e32 v43, 0xffff0000, v127
	v_mov_b32_e32 v11, v145
	v_add_f32_e32 v36, s0, v46
	v_max_f32_e64 v37, s1, s1
	v_max_f32_e32 v47, v36, v37
	v_sub_f32_e32 v37, s1, v47
	v_sub_f32_e32 v36, v36, v47
	v_mul_f32_e32 v37, 0x3fb8aa3b, v37
	v_mul_f32_e32 v36, 0x3fb8aa3b, v36
	v_exp_f32_e32 v38, v37
	v_exp_f32_e32 v36, v36
	v_mov_b32_e32 v46, v47
	v_pk_mul_f32 v[50:51], v[38:39], v[50:51] op_sel_hi:[0,1]
	v_pk_mul_f32 v[42:43], v[38:39], v[42:43] op_sel_hi:[0,1]
	v_pk_fma_f32 v[32:33], v[32:33], v[36:37], v[50:51] op_sel_hi:[1,0,1]
	v_pk_fma_f32 v[40:41], v[40:41], v[36:37], v[42:43] op_sel_hi:[1,0,1]
	v_cvt_pk_bf16_f32 v30, v32, v33
	v_cvt_pk_bf16_f32 v31, v40, v41
	global_store_dwordx2 v1, v[30:31], s[8:9]
	v_mov_b32_e32 v37, v38
	v_pk_mul_f32 v[10:11], v[10:11], v[36:37]
	s_add_u32 s8, s8, 0x8000
	s_addc_u32 s9, s9, 0
	v_add_f32_e32 v10, v10, v11
	s_mov_b64 exec, s[16:17]
	global_store_dword v2, v10, s[12:13]
	s_mov_b64 exec, s[18:19]
	global_store_dword v0, v47, s[14:15] offset:2008
	s_mov_b64 exec, s[20:21]
	s_add_u32 s12, s12, 0x200
	s_addc_u32 s13, s13, 0
	v_readlane_b32 s0, v6, 62
	v_readlane_b32 s1, v7, 62
	s_waitcnt vmcnt(17)
	v_lshlrev_b32_e32 v50, 16, v128
	v_and_b32_e32 v51, 0xffff0000, v128
	v_lshlrev_b32_e32 v42, 16, v129
	v_and_b32_e32 v43, 0xffff0000, v129
	v_mov_b32_e32 v11, v146
	v_add_f32_e32 v36, s0, v46
	v_max_f32_e64 v37, s1, s1
	v_max_f32_e32 v47, v36, v37
	v_sub_f32_e32 v37, s1, v47
	v_sub_f32_e32 v36, v36, v47
	v_mul_f32_e32 v37, 0x3fb8aa3b, v37
	v_mul_f32_e32 v36, 0x3fb8aa3b, v36
	v_exp_f32_e32 v38, v37
	v_exp_f32_e32 v36, v36
	v_mov_b32_e32 v46, v47
	v_pk_mul_f32 v[50:51], v[38:39], v[50:51] op_sel_hi:[0,1]
	v_pk_mul_f32 v[42:43], v[38:39], v[42:43] op_sel_hi:[0,1]
	v_pk_fma_f32 v[32:33], v[32:33], v[36:37], v[50:51] op_sel_hi:[1,0,1]
	v_pk_fma_f32 v[40:41], v[40:41], v[36:37], v[42:43] op_sel_hi:[1,0,1]
	v_cvt_pk_bf16_f32 v30, v32, v33
	v_cvt_pk_bf16_f32 v31, v40, v41
	global_store_dwordx2 v1, v[30:31], s[8:9]
	v_mov_b32_e32 v37, v38
	v_pk_mul_f32 v[10:11], v[10:11], v[36:37]
	s_add_u32 s8, s8, 0x8000
	s_addc_u32 s9, s9, 0
	v_add_f32_e32 v10, v10, v11
	s_mov_b64 exec, s[16:17]
	global_store_dword v2, v10, s[12:13]
	s_mov_b64 exec, s[18:19]
	global_store_dword v0, v47, s[14:15] offset:2024
	s_mov_b64 exec, s[20:21]
	s_add_u32 s12, s12, 0x200
	s_addc_u32 s13, s13, 0
	v_readlane_b32 s0, v6, 63
	v_readlane_b32 s1, v7, 63
	s_waitcnt vmcnt(15)
	v_lshlrev_b32_e32 v50, 16, v130
	v_and_b32_e32 v51, 0xffff0000, v130
	v_lshlrev_b32_e32 v42, 16, v131
	v_and_b32_e32 v43, 0xffff0000, v131
	v_mov_b32_e32 v11, v147
	v_add_f32_e32 v36, s0, v46
	v_max_f32_e64 v37, s1, s1
	v_max_f32_e32 v47, v36, v37
	v_sub_f32_e32 v37, s1, v47
	v_sub_f32_e32 v36, v36, v47
	v_mul_f32_e32 v37, 0x3fb8aa3b, v37
	v_mul_f32_e32 v36, 0x3fb8aa3b, v36
	v_exp_f32_e32 v38, v37
	v_exp_f32_e32 v36, v36
	v_mov_b32_e32 v46, v47
	v_pk_mul_f32 v[50:51], v[38:39], v[50:51] op_sel_hi:[0,1]
	v_pk_mul_f32 v[42:43], v[38:39], v[42:43] op_sel_hi:[0,1]
	v_pk_fma_f32 v[32:33], v[32:33], v[36:37], v[50:51] op_sel_hi:[1,0,1]
	v_pk_fma_f32 v[40:41], v[40:41], v[36:37], v[42:43] op_sel_hi:[1,0,1]
	v_cvt_pk_bf16_f32 v30, v32, v33
	v_cvt_pk_bf16_f32 v31, v40, v41
	global_store_dwordx2 v1, v[30:31], s[8:9]
	v_mov_b32_e32 v37, v38
	v_pk_mul_f32 v[10:11], v[10:11], v[36:37]
	s_add_u32 s8, s8, 0x8000
	s_addc_u32 s9, s9, 0
	v_add_f32_e32 v10, v10, v11
	s_mov_b64 exec, s[16:17]
	global_store_dword v2, v10, s[12:13]
	s_mov_b64 exec, s[18:19]
	global_store_dword v0, v47, s[14:15] offset:2040
	s_mov_b64 exec, s[20:21]
	s_add_u32 s12, s12, 0x200
	s_addc_u32 s13, s13, 0
	s_add_i32 s2, s2, s70
	s_branch .Lsc_unit
.Lsc_done:
.LBB0_515:
	s_waitcnt vmcnt(0)
	s_barrier
	s_mov_b64 s[0:1], exec
	v_readlane_b32 s4, v250, 5
	v_readlane_b32 s5, v250, 6
	s_and_b64 s[4:5], s[0:1], s[4:5]
	s_mov_b64 exec, s[4:5]
	s_cbranch_execz .LBB0_567
	s_add_i32 s2, 0, 0x22ff0
	v_mov_b32_e32 v0, s2
	s_waitcnt vmcnt(0) expcnt(0) lgkmcnt(0)
	ds_read_b32 v2, v0
	s_add_i32 s2, 0, 0x22ff4
	v_mov_b32_e32 v0, s2
	ds_read_b32 v0, v0
	s_waitcnt lgkmcnt(1)
	v_cmp_ne_u32_e32 vcc, 0, v2
	s_cbranch_vccnz .LBB0_531
	s_add_u32 s4, s68, 0x3ab00200
	s_addc_u32 s5, s69, 0
	s_add_u32 s6, s68, 0x3ab00400
	s_addc_u32 s7, s69, 0
	s_add_u32 s8, s68, 0x3ab00500
	s_addc_u32 s9, s69, 0
	s_add_u32 s10, s68, 0x3ab00600
	s_addc_u32 s11, s69, 0
	s_add_u32 s12, s68, 0x3ab00700
	s_addc_u32 s13, s69, 0
	s_add_u32 s14, s68, 0x3ab00800
	s_addc_u32 s15, s69, 0
	s_add_u32 s16, s68, 0x3ab00900
	s_addc_u32 s17, s69, 0
	s_add_u32 s18, s68, 0x3ab00a00
	s_addc_u32 s19, s69, 0
	s_add_u32 s20, s68, 0x3ab00b00
	s_addc_u32 s21, s69, 0
	s_add_u32 s22, s68, 0x3ab00c00
	s_addc_u32 s23, s69, 0
	s_add_u32 s26, s68, 0x3ab00d00
	s_addc_u32 s27, s69, 0
	s_add_u32 s30, s68, 0x3ab00e00
	s_addc_u32 s31, s69, 0
	s_add_u32 s34, s68, 0x3ab00f00
	s_addc_u32 s35, s69, 0
	s_add_u32 s40, s68, 0x3ab01000
	s_addc_u32 s41, s69, 0
	s_add_u32 s42, s68, 0x3ab01100
	s_addc_u32 s43, s69, 0
	s_add_u32 s48, s68, 0x3ab01200
	v_readlane_b32 s2, v250, 2
	s_addc_u32 s49, s69, 0
	s_mul_i32 s2, s71, s2
	s_add_u32 s50, s68, 0x3ab01300
	s_mul_i32 s2, s2, s70
	s_addc_u32 s51, s69, 0
	s_mov_b32 s54, 1
	v_mov_b32_e32 v16, 0
	s_branch .LBB0_519
